# E2 spurious-wait removal + vmcnt(8) K-loop waits + batched GEMM3 epilogue + q|f lb preload
# speedup vs baseline: 1.5840x; 1.5840x over previous
; #define PG8_STAGE(bufoff, gbase, voff) do { _Pragma("unroll") for (int _i = 0; _i < 2; ++_i) \
;         __builtin_amdgcn_global_load_lds((const unsigned*)((const char*)(gbase) + (voff)[_i]), (LAS unsigned*)(lds + (bufoff) + ldsw + _i * 8192), 16, 0, 0); } while (0)
; #define PG8_LDA(dst, b, h) do { _Pragma("unroll") for (int m = 0; m < 4; ++m) _Pragma("unroll") for (int k = 0; k < 2; ++k) dst[m][k] = *(const LAS bf16x8*)(lds + PG8_SA(b, h) + aoff + m * 2048 + k * 1024); } while (0)
; #define PG8_LDB(dst, b, h) do { _Pragma("unroll") for (int n = 0; n < 2; ++n) _Pragma("unroll") for (int k = 0; k < 2; ++k) dst[n][k] = *(const LAS bf16x8*)(lds + PG8_SB(b, h) + boff + n * 2048 + k * 1024); } while (0)
; #define PG8_MMA(ai, bj, At, Bt) do { __builtin_amdgcn_s_setprio(1); _Pragma("unroll") for (int m = 0; m < 4; ++m) _Pragma("unroll") for (int n = 0; n < 2; ++n) _Pragma("unroll") for (int k = 0; k < 2; ++k) \
;         acc[ai][bj][m][n] = __builtin_amdgcn_mfma_f32_16x16x32_bf16(Bt[n][k], At[m][k], acc[ai][bj][m][n], 0, 0, 0); __builtin_amdgcn_s_setprio(0); } while (0)
; #define PG8_WAIT_V(n) asm volatile("s_waitcnt vmcnt(" #n ")" ::: "memory")
; #define PG8_BAR __builtin_amdgcn_s_barrier()
; template <class Epi>
; __device__ __forceinline__ void gemm_phase(LAS unsigned char* lds, const Gemm g, const StaticOrder& S, const Epi& E) {
;     ...
;         for (int t = 0; t < nt; t += 2) {
;             const bool last = (t == nt - 2);
;             if constexpr (Epi::MIDHOOK) { if (t == nt / 2) { if (wr == 0) PG8_BAR; E.mid(acc, cur, wr, wc, fr, fq); if (wr == 1) PG8_BAR; } }
;             const char* a1 = cA + (size_t)(t + 1) * kstep;
;             const char* a2 = last ? nA : cA + (size_t)(t + 2) * kstep; const char* b2 = last ? nB : cB + (size_t)(t + 2) * kstep;
;             const char* a3 = a2 + kstep; const char* b3 = b2 + kstep;
;             PG8_LDB(B0, 0, 0); PG8_LDA(At, 0, 0); PG8_LDB(B1, 0, 1); PG8_STAGE(PG8_SA(1, 1), a1 + hstep, voffA);
;             PG8_WAIT_L(0); PG8_BAR; PG8_SCHED; PG8_MMA(0, 0, At, B0); PG8_MMA(0, 1, At, B1); PG8_SCHED; PG8_BAR; PG8_SCHED;
;             PG8_LDA(At, 0, 1); PG8_STAGE(PG8_SB(0, 0), b2, voffB); PG8_STAGE(PG8_SA(0, 0), a2, voffA); PG8_STAGE(PG8_SB(0, 1), b2 + hstep, voffB);
;             PG8_WAIT_V(6); PG8_WAIT_L(0); PG8_BAR; PG8_SCHED; PG8_MMA(1, 0, At, B0); PG8_MMA(1, 1, At, B1); PG8_SCHED; PG8_BAR; PG8_SCHED;
.LBB0_129:
	s_add_u32 s47, s66, 0xfff04000
	s_addc_u32 s51, s67, -1
	s_cmp_eq_u32 s35, 60
	s_cselect_b32 s53, s3, s51
	s_cselect_b32 s52, s5, s47
	s_cselect_b32 s59, s14, s34
	s_cselect_b32 s58, s26, s27
	v_lshl_add_u64 v[206:207], s[66:67], 0, v[128:129]
	s_add_i32 m0, s65, 0xc000
	ds_read_b128 v[134:137], v177
	ds_read_b128 v[138:141], v177 offset:1024
	ds_read_b128 v[142:145], v177 offset:2048
	ds_read_b128 v[146:149], v177 offset:3072
	ds_read_b128 v[150:153], v178
	ds_read_b128 v[154:157], v178 offset:1024
	ds_read_b128 v[158:161], v178 offset:2048
	ds_read_b128 v[162:165], v178 offset:3072
	ds_read_b128 v[166:169], v178 offset:4096
	ds_read_b128 v[170:173], v178 offset:5120
	ds_read_b128 v[182:185], v178 offset:6144
	ds_read_b128 v[186:189], v178 offset:7168
	ds_read_b128 v[190:193], v179
	ds_read_b128 v[194:197], v179 offset:1024
	ds_read_b128 v[198:201], v179 offset:2048
	ds_read_b128 v[202:205], v179 offset:3072
	global_load_lds_dwordx4 v[206:207], off
	v_lshl_add_u64 v[206:207], v[206:207], 0, s[8:9]
	s_add_i32 m0, s65, 0xe000
	s_nop 0
	global_load_lds_dwordx4 v[206:207], off
	s_waitcnt vmcnt(8)
	s_waitcnt lgkmcnt(0)
	s_barrier
	s_setprio 1
	s_waitcnt lgkmcnt(0)
	v_mfma_f32_16x16x32_bf16 v[124:127], v[134:137], v[150:153], v[124:127]
	v_mfma_f32_16x16x32_bf16 v[116:119], v[142:145], v[150:153], v[116:119]
	v_mfma_f32_16x16x32_bf16 v[108:111], v[134:137], v[158:161], v[108:111]
	v_mfma_f32_16x16x32_bf16 v[100:103], v[142:145], v[158:161], v[100:103]
	v_mfma_f32_16x16x32_bf16 v[92:95], v[134:137], v[166:169], v[92:95]
	v_mfma_f32_16x16x32_bf16 v[84:87], v[142:145], v[166:169], v[84:87]
	v_mfma_f32_16x16x32_bf16 v[76:79], v[134:137], v[182:185], v[76:79]
	v_mfma_f32_16x16x32_bf16 v[68:71], v[142:145], v[182:185], v[68:71]
	v_mfma_f32_16x16x32_bf16 v[124:127], v[138:141], v[154:157], v[124:127]
	v_mfma_f32_16x16x32_bf16 v[116:119], v[146:149], v[154:157], v[116:119]
	v_mfma_f32_16x16x32_bf16 v[108:111], v[138:141], v[162:165], v[108:111]
	v_mfma_f32_16x16x32_bf16 v[100:103], v[146:149], v[162:165], v[100:103]
	v_mfma_f32_16x16x32_bf16 v[92:95], v[138:141], v[170:173], v[92:95]
	v_mfma_f32_16x16x32_bf16 v[84:87], v[146:149], v[170:173], v[84:87]
	v_mfma_f32_16x16x32_bf16 v[76:79], v[138:141], v[186:189], v[76:79]
	v_mfma_f32_16x16x32_bf16 v[68:71], v[146:149], v[186:189], v[68:71]
	s_setprio 0
	s_setprio 1
	v_mfma_f32_16x16x32_bf16 v[120:123], v[190:193], v[150:153], v[120:123]
	v_mfma_f32_16x16x32_bf16 v[112:115], v[198:201], v[150:153], v[112:115]
	v_mfma_f32_16x16x32_bf16 v[104:107], v[190:193], v[158:161], v[104:107]
	v_mfma_f32_16x16x32_bf16 v[96:99], v[198:201], v[158:161], v[96:99]
	v_mfma_f32_16x16x32_bf16 v[88:91], v[190:193], v[166:169], v[88:91]
	v_mfma_f32_16x16x32_bf16 v[80:83], v[198:201], v[166:169], v[80:83]
	v_mfma_f32_16x16x32_bf16 v[72:75], v[190:193], v[182:185], v[72:75]
	v_mfma_f32_16x16x32_bf16 v[64:67], v[198:201], v[182:185], v[64:67]
	v_mfma_f32_16x16x32_bf16 v[120:123], v[194:197], v[154:157], v[120:123]
	v_mfma_f32_16x16x32_bf16 v[112:115], v[202:205], v[154:157], v[112:115]
	v_mfma_f32_16x16x32_bf16 v[104:107], v[194:197], v[162:165], v[104:107]
	v_mfma_f32_16x16x32_bf16 v[96:99], v[202:205], v[162:165], v[96:99]
	v_mfma_f32_16x16x32_bf16 v[88:91], v[194:197], v[170:173], v[88:91]
	v_mfma_f32_16x16x32_bf16 v[80:83], v[202:205], v[170:173], v[80:83]
	v_mfma_f32_16x16x32_bf16 v[72:75], v[194:197], v[186:189], v[72:75]
	v_mfma_f32_16x16x32_bf16 v[64:67], v[202:205], v[186:189], v[64:67]
	s_setprio 0
	s_barrier
	s_add_i32 s47, s92, s75
	v_lshl_add_u64 v[206:207], s[58:59], 0, v[128:129]
	s_mov_b32 m0, s47
	ds_read_b128 v[150:153], v178 offset:16384
	ds_read_b128 v[154:157], v178 offset:17408
	ds_read_b128 v[158:161], v178 offset:18432
	ds_read_b128 v[162:165], v178 offset:19456
	ds_read_b128 v[166:169], v178 offset:20480
	ds_read_b128 v[170:173], v178 offset:21504
	ds_read_b128 v[182:185], v178 offset:22528
	ds_read_b128 v[186:189], v178 offset:23552
	global_load_lds_dwordx4 v[206:207], off
	v_lshl_add_u64 v[208:209], v[206:207], 0, s[8:9]
	s_add_i32 m0, s47, 0x2000
	s_add_i32 s47, s93, s75
	global_load_lds_dwordx4 v[208:209], off
	v_lshl_add_u64 v[208:209], s[52:53], 0, v[128:129]
	s_mov_b32 m0, s65
	v_lshl_add_u64 v[212:213], v[208:209], 0, s[8:9]
	global_load_lds_dwordx4 v[208:209], off
	s_mov_b32 m0, s76
	s_nop 0
	global_load_lds_dwordx4 v[212:213], off
	v_lshl_add_u64 v[212:213], v[206:207], 0, s[10:11]
	s_mov_b32 m0, s47
	s_nop 0
	global_load_lds_dwordx4 v[212:213], off
	v_lshl_add_u64 v[212:213], v[206:207], 0, s[12:13]
	s_add_i32 m0, s47, 0x2000
	s_nop 0
	global_load_lds_dwordx4 v[212:213], off
	s_waitcnt vmcnt(8)
	s_waitcnt lgkmcnt(0)
	s_barrier
; #define PG8_STAGE(bufoff, gbase, voff) do { _Pragma("unroll") for (int _i = 0; _i < 2; ++_i) \
;         __builtin_amdgcn_global_load_lds((const unsigned*)((const char*)(gbase) + (voff)[_i]), (LAS unsigned*)(lds + (bufoff) + ldsw + _i * 8192), 16, 0, 0); } while (0)
; #define PG8_LDA(dst, b, h) do { _Pragma("unroll") for (int m = 0; m < 4; ++m) _Pragma("unroll") for (int k = 0; k < 2; ++k) dst[m][k] = *(const LAS bf16x8*)(lds + PG8_SA(b, h) + aoff + m * 2048 + k * 1024); } while (0)
; #define PG8_LDB(dst, b, h) do { _Pragma("unroll") for (int n = 0; n < 2; ++n) _Pragma("unroll") for (int k = 0; k < 2; ++k) dst[n][k] = *(const LAS bf16x8*)(lds + PG8_SB(b, h) + boff + n * 2048 + k * 1024); } while (0)
; #define PG8_MMA(ai, bj, At, Bt) do { __builtin_amdgcn_s_setprio(1); _Pragma("unroll") for (int m = 0; m < 4; ++m) _Pragma("unroll") for (int n = 0; n < 2; ++n) _Pragma("unroll") for (int k = 0; k < 2; ++k) \
;         acc[ai][bj][m][n] = __builtin_amdgcn_mfma_f32_16x16x32_bf16(Bt[n][k], At[m][k], acc[ai][bj][m][n], 0, 0, 0); __builtin_amdgcn_s_setprio(0); } while (0)
; #define PG8_WAIT_V(n) asm volatile("s_waitcnt vmcnt(" #n ")" ::: "memory")
; #define PG8_WAIT_L(n) asm volatile("s_waitcnt lgkmcnt(" #n ")" ::: "memory")
; #define PG8_BAR __builtin_amdgcn_s_barrier()
; #define PG8_SCHED __builtin_amdgcn_sched_barrier(0)
; template <class Epi>
; __device__ __forceinline__ void gemm_phase(LAS unsigned char* lds, const Gemm g, const StaticOrder& S, const Epi& E) {
;     ...
;             PG8_WAIT_V(6); PG8_WAIT_L(0); PG8_BAR; PG8_SCHED; PG8_MMA(1, 0, At, B0); PG8_MMA(1, 1, At, B1); PG8_SCHED; PG8_BAR; PG8_SCHED;
;             PG8_LDB(B0, 1, 0); PG8_LDA(At, 1, 0); PG8_LDB(B1, 1, 1); PG8_STAGE(PG8_SA(0, 1), a2 + hstep, voffA);
;             PG8_WAIT_L(0); PG8_BAR; PG8_SCHED; PG8_MMA(0, 0, At, B0); PG8_MMA(0, 1, At, B1); PG8_SCHED; PG8_BAR; PG8_SCHED;
;             PG8_LDA(At, 1, 1); PG8_STAGE(PG8_SB(1, 0), b3, voffB); PG8_STAGE(PG8_SA(1, 0), a3, voffA); PG8_STAGE(PG8_SB(1, 1), b3 + hstep, voffB);
	s_setprio 1
	s_waitcnt lgkmcnt(0)
	v_mfma_f32_16x16x32_bf16 v[60:63], v[134:137], v[150:153], v[60:63]
	v_mfma_f32_16x16x32_bf16 v[52:55], v[142:145], v[150:153], v[52:55]
	v_mfma_f32_16x16x32_bf16 v[44:47], v[134:137], v[158:161], v[44:47]
	v_mfma_f32_16x16x32_bf16 v[36:39], v[142:145], v[158:161], v[36:39]
	v_mfma_f32_16x16x32_bf16 v[28:31], v[134:137], v[166:169], v[28:31]
	v_mfma_f32_16x16x32_bf16 v[20:23], v[142:145], v[166:169], v[20:23]
	v_mfma_f32_16x16x32_bf16 v[12:15], v[134:137], v[182:185], v[12:15]
	v_mfma_f32_16x16x32_bf16 v[4:7], v[142:145], v[182:185], v[4:7]
	v_mfma_f32_16x16x32_bf16 v[60:63], v[138:141], v[154:157], v[60:63]
	v_mfma_f32_16x16x32_bf16 v[52:55], v[146:149], v[154:157], v[52:55]
	v_mfma_f32_16x16x32_bf16 v[44:47], v[138:141], v[162:165], v[44:47]
	v_mfma_f32_16x16x32_bf16 v[36:39], v[146:149], v[162:165], v[36:39]
	v_mfma_f32_16x16x32_bf16 v[28:31], v[138:141], v[170:173], v[28:31]
	v_mfma_f32_16x16x32_bf16 v[20:23], v[146:149], v[170:173], v[20:23]
	v_mfma_f32_16x16x32_bf16 v[12:15], v[138:141], v[186:189], v[12:15]
	v_mfma_f32_16x16x32_bf16 v[4:7], v[146:149], v[186:189], v[4:7]
	s_setprio 0
	s_setprio 1
	v_mfma_f32_16x16x32_bf16 v[56:59], v[190:193], v[150:153], v[56:59]
	v_mfma_f32_16x16x32_bf16 v[48:51], v[198:201], v[150:153], v[48:51]
	v_mfma_f32_16x16x32_bf16 v[40:43], v[190:193], v[158:161], v[40:43]
	v_mfma_f32_16x16x32_bf16 v[32:35], v[198:201], v[158:161], v[32:35]
	v_mfma_f32_16x16x32_bf16 v[24:27], v[190:193], v[166:169], v[24:27]
	v_mfma_f32_16x16x32_bf16 v[16:19], v[198:201], v[166:169], v[16:19]
	v_mfma_f32_16x16x32_bf16 v[8:11], v[190:193], v[182:185], v[8:11]
	v_mfma_f32_16x16x32_bf16 v[0:3], v[198:201], v[182:185], v[0:3]
	v_mfma_f32_16x16x32_bf16 v[56:59], v[194:197], v[154:157], v[56:59]
	v_mfma_f32_16x16x32_bf16 v[48:51], v[202:205], v[154:157], v[48:51]
	v_mfma_f32_16x16x32_bf16 v[40:43], v[194:197], v[162:165], v[40:43]
	v_mfma_f32_16x16x32_bf16 v[32:35], v[202:205], v[162:165], v[32:35]
	v_mfma_f32_16x16x32_bf16 v[24:27], v[194:197], v[170:173], v[24:27]
	v_mfma_f32_16x16x32_bf16 v[16:19], v[202:205], v[170:173], v[16:19]
	v_mfma_f32_16x16x32_bf16 v[8:11], v[194:197], v[186:189], v[8:11]
	v_mfma_f32_16x16x32_bf16 v[0:3], v[202:205], v[186:189], v[0:3]
	s_setprio 0
	s_barrier
	s_add_i32 s47, 0, 0x18000
	s_add_i32 s51, 0, 0x1c000
	s_mov_b32 m0, s77
	v_add_u32_e32 v146, s47, v176
	v_add_u32_e32 v181, s51, v176
	v_lshl_add_u64 v[212:213], v[208:209], 0, s[10:11]
	ds_read_b128 v[134:137], v146
	ds_read_b128 v[138:141], v146 offset:1024
	ds_read_b128 v[142:145], v146 offset:2048
	ds_read_b128 v[146:149], v146 offset:3072
	ds_read_b128 v[150:153], v178 offset:32768
	ds_read_b128 v[154:157], v178 offset:33792
	ds_read_b128 v[158:161], v178 offset:34816
	ds_read_b128 v[162:165], v178 offset:35840
	ds_read_b128 v[166:169], v178 offset:36864
	ds_read_b128 v[170:173], v178 offset:37888
	ds_read_b128 v[182:185], v178 offset:38912
	ds_read_b128 v[186:189], v178 offset:39936
	ds_read_b128 v[190:193], v181
	ds_read_b128 v[194:197], v181 offset:1024
	ds_read_b128 v[198:201], v181 offset:2048
	ds_read_b128 v[202:205], v181 offset:3072
	global_load_lds_dwordx4 v[212:213], off
	v_lshl_add_u64 v[212:213], v[208:209], 0, s[12:13]
	s_mov_b32 m0, s78
	s_nop 0
	global_load_lds_dwordx4 v[212:213], off
	s_waitcnt vmcnt(8)
	s_waitcnt lgkmcnt(0)
	s_barrier
	s_setprio 1
	s_waitcnt lgkmcnt(0)
	v_mfma_f32_16x16x32_bf16 v[124:127], v[134:137], v[150:153], v[124:127]
	v_mfma_f32_16x16x32_bf16 v[116:119], v[142:145], v[150:153], v[116:119]
	v_mfma_f32_16x16x32_bf16 v[108:111], v[134:137], v[158:161], v[108:111]
	v_mfma_f32_16x16x32_bf16 v[100:103], v[142:145], v[158:161], v[100:103]
	v_mfma_f32_16x16x32_bf16 v[92:95], v[134:137], v[166:169], v[92:95]
	v_mfma_f32_16x16x32_bf16 v[84:87], v[142:145], v[166:169], v[84:87]
	v_mfma_f32_16x16x32_bf16 v[76:79], v[134:137], v[182:185], v[76:79]
	v_mfma_f32_16x16x32_bf16 v[68:71], v[142:145], v[182:185], v[68:71]
	v_mfma_f32_16x16x32_bf16 v[124:127], v[138:141], v[154:157], v[124:127]
	v_mfma_f32_16x16x32_bf16 v[116:119], v[146:149], v[154:157], v[116:119]
	v_mfma_f32_16x16x32_bf16 v[108:111], v[138:141], v[162:165], v[108:111]
	v_mfma_f32_16x16x32_bf16 v[100:103], v[146:149], v[162:165], v[100:103]
	v_mfma_f32_16x16x32_bf16 v[92:95], v[138:141], v[170:173], v[92:95]
	v_mfma_f32_16x16x32_bf16 v[84:87], v[146:149], v[170:173], v[84:87]
	v_mfma_f32_16x16x32_bf16 v[76:79], v[138:141], v[186:189], v[76:79]
	v_mfma_f32_16x16x32_bf16 v[68:71], v[146:149], v[186:189], v[68:71]
	s_setprio 0
	s_setprio 1
	v_mfma_f32_16x16x32_bf16 v[120:123], v[190:193], v[150:153], v[120:123]
	v_mfma_f32_16x16x32_bf16 v[112:115], v[198:201], v[150:153], v[112:115]
	v_mfma_f32_16x16x32_bf16 v[104:107], v[190:193], v[158:161], v[104:107]
	v_mfma_f32_16x16x32_bf16 v[96:99], v[198:201], v[158:161], v[96:99]
	v_mfma_f32_16x16x32_bf16 v[88:91], v[190:193], v[166:169], v[88:91]
	v_mfma_f32_16x16x32_bf16 v[80:83], v[198:201], v[166:169], v[80:83]
	v_mfma_f32_16x16x32_bf16 v[72:75], v[190:193], v[182:185], v[72:75]
	v_mfma_f32_16x16x32_bf16 v[64:67], v[198:201], v[182:185], v[64:67]
	v_mfma_f32_16x16x32_bf16 v[120:123], v[194:197], v[154:157], v[120:123]
	v_mfma_f32_16x16x32_bf16 v[112:115], v[202:205], v[154:157], v[112:115]
	v_mfma_f32_16x16x32_bf16 v[104:107], v[194:197], v[162:165], v[104:107]
	v_mfma_f32_16x16x32_bf16 v[96:99], v[202:205], v[162:165], v[96:99]
	v_mfma_f32_16x16x32_bf16 v[88:91], v[194:197], v[170:173], v[88:91]
	v_mfma_f32_16x16x32_bf16 v[80:83], v[202:205], v[170:173], v[80:83]
	v_mfma_f32_16x16x32_bf16 v[72:75], v[194:197], v[186:189], v[72:75]
	v_mfma_f32_16x16x32_bf16 v[64:67], v[202:205], v[186:189], v[64:67]
	s_setprio 0
	s_barrier
; #define PG8_STAGE(bufoff, gbase, voff) do { _Pragma("unroll") for (int _i = 0; _i < 2; ++_i) \
;         __builtin_amdgcn_global_load_lds((const unsigned*)((const char*)(gbase) + (voff)[_i]), (LAS unsigned*)(lds + (bufoff) + ldsw + _i * 8192), 16, 0, 0); } while (0)
; #define PG8_LDA(dst, b, h) do { _Pragma("unroll") for (int m = 0; m < 4; ++m) _Pragma("unroll") for (int k = 0; k < 2; ++k) dst[m][k] = *(const LAS bf16x8*)(lds + PG8_SA(b, h) + aoff + m * 2048 + k * 1024); } while (0)
; #define PG8_LDB(dst, b, h) do { _Pragma("unroll") for (int n = 0; n < 2; ++n) _Pragma("unroll") for (int k = 0; k < 2; ++k) dst[n][k] = *(const LAS bf16x8*)(lds + PG8_SB(b, h) + boff + n * 2048 + k * 1024); } while (0)
; #define PG8_MMA(ai, bj, At, Bt) do { __builtin_amdgcn_s_setprio(1); _Pragma("unroll") for (int m = 0; m < 4; ++m) _Pragma("unroll") for (int n = 0; n < 2; ++n) _Pragma("unroll") for (int k = 0; k < 2; ++k) \
;         acc[ai][bj][m][n] = __builtin_amdgcn_mfma_f32_16x16x32_bf16(Bt[n][k], At[m][k], acc[ai][bj][m][n], 0, 0, 0); __builtin_amdgcn_s_setprio(0); } while (0)
; #define PG8_WAIT_V(n) asm volatile("s_waitcnt vmcnt(" #n ")" ::: "memory")
; #define PG8_WAIT_L(n) asm volatile("s_waitcnt lgkmcnt(" #n ")" ::: "memory")
; #define PG8_BAR __builtin_amdgcn_s_barrier()
; #define PG8_SCHED __builtin_amdgcn_sched_barrier(0)
; template <class Epi>
; __device__ __forceinline__ void gemm_phase(LAS unsigned char* lds, const Gemm g, const StaticOrder& S, const Epi& E) {
;     ...
;             PG8_LDB(B0, 1, 0); PG8_LDA(At, 1, 0); PG8_LDB(B1, 1, 1); PG8_STAGE(PG8_SA(0, 1), a2 + hstep, voffA);
;             PG8_WAIT_L(0); PG8_BAR; PG8_SCHED; PG8_MMA(0, 0, At, B0); PG8_MMA(0, 1, At, B1); PG8_SCHED; PG8_BAR; PG8_SCHED;
;             PG8_LDA(At, 1, 1); PG8_STAGE(PG8_SB(1, 0), b3, voffB); PG8_STAGE(PG8_SA(1, 0), a3, voffA); PG8_STAGE(PG8_SB(1, 1), b3 + hstep, voffB);
;             PG8_WAIT_V(6); PG8_WAIT_L(0); PG8_BAR; PG8_SCHED; PG8_MMA(1, 0, At, B0); PG8_MMA(1, 1, At, B1); PG8_SCHED; PG8_BAR; PG8_SCHED;
;         }
	s_add_i32 s47, s47, s75
	v_lshl_add_u64 v[212:213], v[206:207], 0, s[18:19]
	s_mov_b32 m0, s47
	ds_read_b128 v[150:153], v178 offset:49152
	ds_read_b128 v[154:157], v178 offset:50176
	ds_read_b128 v[158:161], v178 offset:51200
	ds_read_b128 v[162:165], v178 offset:52224
	ds_read_b128 v[166:169], v178 offset:53248
	ds_read_b128 v[170:173], v178 offset:54272
	ds_read_b128 v[182:185], v178 offset:55296
	ds_read_b128 v[186:189], v178 offset:56320
	global_load_lds_dwordx4 v[212:213], off
	v_lshl_add_u64 v[212:213], v[206:207], 0, s[20:21]
	s_add_i32 m0, s47, 0x2000
	s_add_i32 s47, s51, s75
	global_load_lds_dwordx4 v[212:213], off
	v_lshl_add_u64 v[212:213], v[208:209], 0, s[18:19]
	s_mov_b32 m0, s80
	v_lshl_add_u64 v[208:209], v[208:209], 0, s[20:21]
	global_load_lds_dwordx4 v[212:213], off
	s_mov_b32 m0, s81
	s_nop 0
	global_load_lds_dwordx4 v[208:209], off
	v_lshl_add_u64 v[208:209], v[206:207], 0, s[22:23]
	s_mov_b32 m0, s47
	v_lshl_add_u64 v[206:207], v[206:207], 0, s[24:25]
	global_load_lds_dwordx4 v[208:209], off
	s_add_i32 m0, s47, 0x2000
	s_nop 0
	global_load_lds_dwordx4 v[206:207], off
	s_waitcnt vmcnt(8)
	s_waitcnt lgkmcnt(0)
	s_barrier
	s_setprio 1
	s_waitcnt lgkmcnt(0)
	v_mfma_f32_16x16x32_bf16 v[60:63], v[134:137], v[150:153], v[60:63]
	v_mfma_f32_16x16x32_bf16 v[52:55], v[142:145], v[150:153], v[52:55]
	v_mfma_f32_16x16x32_bf16 v[44:47], v[134:137], v[158:161], v[44:47]
	v_mfma_f32_16x16x32_bf16 v[36:39], v[142:145], v[158:161], v[36:39]
	v_mfma_f32_16x16x32_bf16 v[28:31], v[134:137], v[166:169], v[28:31]
	v_mfma_f32_16x16x32_bf16 v[20:23], v[142:145], v[166:169], v[20:23]
	v_mfma_f32_16x16x32_bf16 v[12:15], v[134:137], v[182:185], v[12:15]
	v_mfma_f32_16x16x32_bf16 v[4:7], v[142:145], v[182:185], v[4:7]
	v_mfma_f32_16x16x32_bf16 v[60:63], v[138:141], v[154:157], v[60:63]
	v_mfma_f32_16x16x32_bf16 v[52:55], v[146:149], v[154:157], v[52:55]
	v_mfma_f32_16x16x32_bf16 v[44:47], v[138:141], v[162:165], v[44:47]
	v_mfma_f32_16x16x32_bf16 v[36:39], v[146:149], v[162:165], v[36:39]
	v_mfma_f32_16x16x32_bf16 v[28:31], v[138:141], v[170:173], v[28:31]
	v_mfma_f32_16x16x32_bf16 v[20:23], v[146:149], v[170:173], v[20:23]
	v_mfma_f32_16x16x32_bf16 v[12:15], v[138:141], v[186:189], v[12:15]
	v_mfma_f32_16x16x32_bf16 v[4:7], v[146:149], v[186:189], v[4:7]
	s_setprio 0
	s_setprio 1
	v_mfma_f32_16x16x32_bf16 v[56:59], v[190:193], v[150:153], v[56:59]
	v_mfma_f32_16x16x32_bf16 v[48:51], v[198:201], v[150:153], v[48:51]
	v_mfma_f32_16x16x32_bf16 v[40:43], v[190:193], v[158:161], v[40:43]
	v_mfma_f32_16x16x32_bf16 v[32:35], v[198:201], v[158:161], v[32:35]
	v_mfma_f32_16x16x32_bf16 v[24:27], v[190:193], v[166:169], v[24:27]
	v_mfma_f32_16x16x32_bf16 v[16:19], v[198:201], v[166:169], v[16:19]
	v_mfma_f32_16x16x32_bf16 v[8:11], v[190:193], v[182:185], v[8:11]
	v_mfma_f32_16x16x32_bf16 v[0:3], v[198:201], v[182:185], v[0:3]
	v_mfma_f32_16x16x32_bf16 v[56:59], v[194:197], v[154:157], v[56:59]
	v_mfma_f32_16x16x32_bf16 v[48:51], v[202:205], v[154:157], v[48:51]
	v_mfma_f32_16x16x32_bf16 v[40:43], v[194:197], v[162:165], v[40:43]
	v_mfma_f32_16x16x32_bf16 v[32:35], v[202:205], v[162:165], v[32:35]
	v_mfma_f32_16x16x32_bf16 v[24:27], v[194:197], v[170:173], v[24:27]
	v_mfma_f32_16x16x32_bf16 v[16:19], v[202:205], v[170:173], v[16:19]
	v_mfma_f32_16x16x32_bf16 v[8:11], v[194:197], v[186:189], v[8:11]
	v_mfma_f32_16x16x32_bf16 v[0:3], v[202:205], v[186:189], v[0:3]
	s_setprio 0
	s_barrier
	s_add_i32 s35, s35, 2
	s_add_u32 s66, s66, 0x8000
	s_addc_u32 s67, s67, 0
	s_add_u32 s27, s27, 0x8000
	s_addc_u32 s34, s34, 0
	s_cmp_gt_u32 s35, 61
	s_cbranch_scc0 .LBB0_129
	s_and_b64 vcc, exec, s[38:39]
	s_cbranch_vccz .LBB0_132
	s_barrier

; __device__ __forceinline__ float fexp(float x) { return __builtin_amdgcn_exp2f(x * 1.44269504089f); }
; __device__ __forceinline__ float fsigmoid(float x) { return __builtin_amdgcn_rcpf(1.0f + fexp(-x)); }
; __device__ __forceinline__ float row16_scan(float t) { t += dpp0<0x111>(t); t += dpp0<0x112>(t); t += dpp0<0x114>(t); t += dpp0<0x118>(t); return t; }
;     __device__ __forceinline__ void operator()(f32x4 (&acc)[2][2][4][2], const pg8::Unit& u, int wr, int wc, int fr, int fq) const {
;     ...
;             const int h = tile - 24, lane = fq * 16 + fr, src15 = (lane & 48) | 15;
;             const float* lbp = (const float*)(ws + WS_LB) + h * 128 + c8;
; #pragma unroll
;             for (int ai = 0; ai < 2; ++ai) {
;                 const size_t cb = ((size_t)(bb * 64 + nb + 2 * ai) * 16 + h);
; #pragma unroll
;                 for (int n = 0; n < 2; ++n)
; #pragma unroll
;                     for (int j = 0; j < 4; ++j) {
;                         const float lbv = lbp[4 * n + j];
;                         float cc[4];
; #pragma unroll
;                         for (int m = 0; m < 4; ++m) { const float s = fsigmoid(acc[ai][1][m][n][j]); const float f = lbv + (1.0f - lbv) * s;
;                             acc[ai][1][m][n][j] = 1.0f - f; cc[m] = row16_scan(__builtin_amdgcn_logf(f) * 0.69314718056f); }
;                         const float t0 = __shfl(cc[0], src15), t1 = __shfl(cc[1], src15), t2 = __shfl(cc[2], src15), t3 = __shfl(cc[3], src15);
;                         const float cmid = t0 + t1, clast = cmid + t2 + t3;
;                         cc[1] += t0; cc[2] += cmid; cc[3] += cmid + t2;
; #pragma unroll
;                         for (int m = 0; m < 4; ++m) { const float x = cc[m] - cmid; const float qv = acc[ai][0][m][n][j];
;                             acc[ai][0][m][n][j] = qv * fsigmoid(qv) * fexp(x); acc[ai][1][m][n][j] *= fexp(-x); }
;                         if (fr == 0) { float* sp = (float*)(ws + WS_SCL) + cb * 384 + c8 + 4 * n + j; sp[0] = fexp(cmid); sp[128] = fexp(clast); sp[256] = fexp(clast - cmid); }
.LBB0_144:
	s_andn2_b64 vcc, exec, s[4:5]
	s_cbranch_vccnz .LBB0_178
	s_sub_i32 s3, s64, 24
	s_lshl_b32 s14, s3, 7
	s_lshl_b64 s[4:5], s[14:15], 2
	v_readlane_b32 s14, v252, 18
	s_add_u32 s4, s14, s4
	v_readlane_b32 s14, v252, 19
	s_addc_u32 s5, s14, s5
	v_ashrrev_i32_e32 v137, 31, v136
	v_lshl_add_u64 v[138:139], v[136:137], 2, s[4:5]
	global_load_dword v187, v[138:139], off
	global_load_dword v242, v[138:139], off
	global_load_dword v243, v[138:139], off offset:4
	global_load_dword v244, v[138:139], off offset:8
	global_load_dword v245, v[138:139], off offset:12
	global_load_dword v246, v[138:139], off offset:16
	global_load_dword v247, v[138:139], off offset:20
	global_load_dword v248, v[138:139], off offset:24
	global_load_dword v249, v[138:139], off offset:28
	v_mul_f32_e32 v140, 0xbfb8aa3b, v120
	v_mul_f32_e32 v141, 0xbfb8aa3b, v104
	v_exp_f32_e32 v140, v140
	v_exp_f32_e32 v141, v141
	v_mul_f32_e32 v142, 0xbfb8aa3b, v88
	v_mul_f32_e32 v143, 0xbfb8aa3b, v72
	v_add_f32_e32 v140, 1.0, v140
	v_add_f32_e32 v141, 1.0, v141
	v_exp_f32_e32 v142, v142
	v_exp_f32_e32 v143, v143
	v_rcp_f32_e32 v140, v140
	v_rcp_f32_e32 v141, v141
	v_add_f32_e32 v142, 1.0, v142
	v_add_f32_e32 v143, 1.0, v143
	v_rcp_f32_e32 v142, v142
	v_rcp_f32_e32 v143, v143
	v_lshl_add_u32 v135, v181, 4, v172
	v_and_b32_e32 v135, 48, v135
	v_and_or_b32 v135, v180, 64, v135
	v_lshlrev_b32_e32 v135, 2, v135
	s_lshl_b32 s14, s47, 6
	s_add_i32 s66, s51, s14
	s_ashr_i32 s67, s66, 31
	s_lshl_b64 s[26:27], s[66:67], 4
	s_add_u32 s68, s26, s3
	s_addc_u32 s69, s27, 0
	s_mul_i32 s14, s69, 0x600
	s_mul_hi_u32 s26, s68, 0x600
	v_cmp_eq_u32_e64 s[4:5], 0, v172
	s_add_i32 s14, s26, s14
	s_mul_i32 s26, s68, 0x600
	s_waitcnt vmcnt(0)
	v_sub_f32_e32 v144, 1.0, v187
	v_fma_f32 v188, v140, v144, v187
	v_fma_f32 v189, v141, v144, v187
	v_log_f32_e32 v140, v188
	v_log_f32_e32 v141, v189
	v_fma_f32 v190, v142, v144, v187
	v_fmac_f32_e32 v187, v143, v144
	v_mul_f32_e32 v144, 0x3f317218, v140
	v_mul_f32_e32 v145, 0x3f317218, v141
	v_log_f32_e32 v142, v190
	v_log_f32_e32 v143, v187
	v_mov_b32_dpp v144, v144 row_shr:1 row_mask:0xf bank_mask:0xf bound_ctrl:1
	v_mov_b32_dpp v145, v145 row_shr:1 row_mask:0xf bank_mask:0xf bound_ctrl:1
	v_fmac_f32_e32 v144, 0x3f317218, v140
	v_fmac_f32_e32 v145, 0x3f317218, v141
	v_mul_f32_e32 v146, 0x3f317218, v142
	v_add_f32_dpp v140, v144, v144 row_shr:2 row_mask:0xf bank_mask:0xf bound_ctrl:1
	v_add_f32_dpp v141, v145, v145 row_shr:2 row_mask:0xf bank_mask:0xf bound_ctrl:1
	v_mul_f32_e32 v147, 0x3f317218, v143
	v_add_f32_dpp v140, v140, v140 row_shr:4 row_mask:0xf bank_mask:0xf bound_ctrl:1
	v_add_f32_dpp v141, v141, v141 row_shr:4 row_mask:0xf bank_mask:0xf bound_ctrl:1
	v_mov_b32_dpp v146, v146 row_shr:1 row_mask:0xf bank_mask:0xf bound_ctrl:1
	v_add_f32_dpp v191, v140, v140 row_shr:8 row_mask:0xf bank_mask:0xf bound_ctrl:1
	v_add_f32_dpp v192, v141, v141 row_shr:8 row_mask:0xf bank_mask:0xf bound_ctrl:1
	v_mov_b32_dpp v148, v147 row_shr:1 row_mask:0xf bank_mask:0xf bound_ctrl:1
	ds_bpermute_b32 v147, v135, v191 offset:60
	ds_bpermute_b32 v141, v135, v192 offset:60
	v_fmac_f32_e32 v146, 0x3f317218, v142
	v_fmac_f32_e32 v148, 0x3f317218, v143
	s_nop 0
	v_add_f32_dpp v142, v146, v146 row_shr:2 row_mask:0xf bank_mask:0xf bound_ctrl:1
	v_add_f32_dpp v140, v148, v148 row_shr:2 row_mask:0xf bank_mask:0xf bound_ctrl:1
	s_nop 0
	v_add_f32_dpp v142, v142, v142 row_shr:4 row_mask:0xf bank_mask:0xf bound_ctrl:1
	v_add_f32_dpp v146, v140, v140 row_shr:4 row_mask:0xf bank_mask:0xf bound_ctrl:1
	s_nop 0
	v_add_f32_dpp v193, v142, v142 row_shr:8 row_mask:0xf bank_mask:0xf bound_ctrl:1
	v_mov_b32_dpp v140, v146 row_shr:8 row_mask:0xf bank_mask:0xf bound_ctrl:1
	ds_bpermute_b32 v144, v135, v193 offset:60
	s_waitcnt lgkmcnt(1)
	v_pk_add_f32 v[142:143], v[146:147], v[140:141]
	ds_bpermute_b32 v140, v135, v142 offset:60
	s_waitcnt lgkmcnt(1)
	v_add_f32_e32 v194, v143, v144
	s_and_saveexec_b64 s[70:71], s[4:5]
	s_cbranch_execz .LBB0_147
	s_waitcnt lgkmcnt(0)
	v_add_f32_e32 v140, v194, v140
	v_mul_f32_e32 v141, 0x3fb8aa3b, v143
	v_readlane_b32 s27, v252, 20
	v_exp_f32_e32 v144, v141
	v_mul_f32_e32 v141, 0x3fb8aa3b, v140
	v_sub_f32_e32 v140, v140, v143
	s_add_u32 s34, s27, s26
	v_readlane_b32 s27, v252, 21
	v_exp_f32_e32 v145, v141
	v_mul_f32_e32 v140, 0x3fb8aa3b, v140
	s_addc_u32 s35, s27, s14
	v_exp_f32_e32 v146, v140
	v_lshl_add_u64 v[140:141], v[136:137], 2, s[34:35]
	global_store_dword v[140:141], v144, off
	global_store_dword v[140:141], v145, off offset:512
	global_store_dword v[140:141], v146, off offset:1024
; __device__ __forceinline__ float fexp(float x) { return __builtin_amdgcn_exp2f(x * 1.44269504089f); }
; __device__ __forceinline__ float fsigmoid(float x) { return __builtin_amdgcn_rcpf(1.0f + fexp(-x)); }
; __device__ __forceinline__ float row16_scan(float t) { t += dpp0<0x111>(t); t += dpp0<0x112>(t); t += dpp0<0x114>(t); t += dpp0<0x118>(t); return t; }
;     __device__ __forceinline__ void operator()(f32x4 (&acc)[2][2][4][2], const pg8::Unit& u, int wr, int wc, int fr, int fq) const {
;     ...
;                     for (int j = 0; j < 4; ++j) {
;                         const float lbv = lbp[4 * n + j];
;                         float cc[4];
; #pragma unroll
;                         for (int m = 0; m < 4; ++m) { const float s = fsigmoid(acc[ai][1][m][n][j]); const float f = lbv + (1.0f - lbv) * s;
;                             acc[ai][1][m][n][j] = 1.0f - f; cc[m] = row16_scan(__builtin_amdgcn_logf(f) * 0.69314718056f); }
;                         const float t0 = __shfl(cc[0], src15), t1 = __shfl(cc[1], src15), t2 = __shfl(cc[2], src15), t3 = __shfl(cc[3], src15);
;                         const float cmid = t0 + t1, clast = cmid + t2 + t3;
;                         cc[1] += t0; cc[2] += cmid; cc[3] += cmid + t2;
; #pragma unroll
;                         for (int m = 0; m < 4; ++m) { const float x = cc[m] - cmid; const float qv = acc[ai][0][m][n][j];
;                             acc[ai][0][m][n][j] = qv * fsigmoid(qv) * fexp(x); acc[ai][1][m][n][j] *= fexp(-x); }
;                         if (fr == 0) { float* sp = (float*)(ws + WS_SCL) + cb * 384 + c8 + 4 * n + j; sp[0] = fexp(cmid); sp[128] = fexp(clast); sp[256] = fexp(clast - cmid); }
.LBB0_147:
	s_or_b64 exec, exec, s[70:71]
	v_mov_b32_e32 v146, v243
	s_waitcnt lgkmcnt(0)
	v_mul_f32_e32 v140, 0xbfb8aa3b, v121
	v_mul_f32_e32 v141, 0xbfb8aa3b, v105
	v_exp_f32_e32 v140, v140
	v_exp_f32_e32 v141, v141
	v_mul_f32_e32 v144, 0xbfb8aa3b, v89
	v_mul_f32_e32 v145, 0xbfb8aa3b, v73
	v_exp_f32_e32 v144, v144
	v_exp_f32_e32 v145, v145
	v_add_f32_e32 v140, 1.0, v140
	v_add_f32_e32 v141, 1.0, v141
	v_rcp_f32_e32 v140, v140
	v_rcp_f32_e32 v141, v141
	v_add_f32_e32 v144, 1.0, v144
	v_add_f32_e32 v145, 1.0, v145
	v_rcp_f32_e32 v144, v144
	v_rcp_f32_e32 v145, v145
	v_or_b32_e32 v135, 60, v135
	v_sub_f32_e32 v148, 1.0, v146
	v_fma_f32 v173, v140, v148, v146
	v_fma_f32 v182, v141, v148, v146
	v_log_f32_e32 v140, v173
	v_log_f32_e32 v141, v182
	v_fma_f32 v183, v144, v148, v146
	v_fmac_f32_e32 v146, v145, v148
	v_log_f32_e32 v144, v183
	v_log_f32_e32 v145, v146
	v_mul_f32_e32 v148, 0x3f317218, v140
	v_mul_f32_e32 v149, 0x3f317218, v141
	v_mul_f32_e32 v150, 0x3f317218, v144
	v_mov_b32_dpp v148, v148 row_shr:1 row_mask:0xf bank_mask:0xf bound_ctrl:1
	v_mov_b32_dpp v149, v149 row_shr:1 row_mask:0xf bank_mask:0xf bound_ctrl:1
	v_fmac_f32_e32 v148, 0x3f317218, v140
	v_fmac_f32_e32 v149, 0x3f317218, v141
	v_mul_f32_e32 v151, 0x3f317218, v145
	v_add_f32_dpp v140, v148, v148 row_shr:2 row_mask:0xf bank_mask:0xf bound_ctrl:1
	v_add_f32_dpp v141, v149, v149 row_shr:2 row_mask:0xf bank_mask:0xf bound_ctrl:1
	v_mov_b32_dpp v150, v150 row_shr:1 row_mask:0xf bank_mask:0xf bound_ctrl:1
	v_add_f32_dpp v140, v140, v140 row_shr:4 row_mask:0xf bank_mask:0xf bound_ctrl:1
	v_add_f32_dpp v141, v141, v141 row_shr:4 row_mask:0xf bank_mask:0xf bound_ctrl:1
	v_mov_b32_dpp v151, v151 row_shr:1 row_mask:0xf bank_mask:0xf bound_ctrl:1
	v_add_f32_dpp v184, v140, v140 row_shr:8 row_mask:0xf bank_mask:0xf bound_ctrl:1
	v_add_f32_dpp v185, v141, v141 row_shr:8 row_mask:0xf bank_mask:0xf bound_ctrl:1
	v_fmac_f32_e32 v150, 0x3f317218, v144
	v_fmac_f32_e32 v151, 0x3f317218, v145
	ds_bpermute_b32 v145, v135, v184
	ds_bpermute_b32 v141, v135, v185
	v_add_f32_dpp v144, v150, v150 row_shr:2 row_mask:0xf bank_mask:0xf bound_ctrl:1
	v_add_f32_dpp v140, v151, v151 row_shr:2 row_mask:0xf bank_mask:0xf bound_ctrl:1
	s_nop 0
	v_add_f32_dpp v144, v144, v144 row_shr:4 row_mask:0xf bank_mask:0xf bound_ctrl:1
	s_nop 1
	v_add_f32_dpp v186, v144, v144 row_shr:8 row_mask:0xf bank_mask:0xf bound_ctrl:1
	v_add_f32_dpp v144, v140, v140 row_shr:4 row_mask:0xf bank_mask:0xf bound_ctrl:1
	ds_bpermute_b32 v149, v135, v186
	s_nop 0
	v_mov_b32_dpp v140, v144 row_shr:8 row_mask:0xf bank_mask:0xf bound_ctrl:1
	s_waitcnt lgkmcnt(1)
	v_pk_add_f32 v[140:141], v[144:145], v[140:141]
	ds_bpermute_b32 v148, v135, v140
	s_waitcnt lgkmcnt(1)
	v_add_f32_e32 v144, v141, v149
	s_and_saveexec_b64 s[70:71], s[4:5]
	s_cbranch_execz .LBB0_149
	s_add_u32 s34, s30, s26
	v_mul_f32_e32 v151, 0x3fb8aa3b, v141
	s_addc_u32 s35, s31, s14
	v_exp_f32_e32 v151, v151
	s_waitcnt lgkmcnt(0)
	v_add_f32_e32 v150, v144, v148
	v_lshl_add_u64 v[148:149], v[136:137], 2, s[34:35]
	v_add_co_u32_e32 v148, vcc, 0x49300000, v148
	s_nop 1
	v_addc_co_u32_e32 v149, vcc, 0, v149, vcc
	global_store_dword v[148:149], v151, off offset:4
	v_mul_f32_e32 v151, 0x3fb8aa3b, v150
	v_sub_f32_e32 v150, v150, v141
	v_mul_f32_e32 v150, 0x3fb8aa3b, v150
	v_exp_f32_e32 v151, v151
	v_exp_f32_e32 v150, v150
	global_store_dword v[148:149], v151, off offset:516
	global_store_dword v[148:149], v150, off offset:1028
.LBB0_149:
	s_or_b64 exec, exec, s[70:71]
	v_mov_b32_e32 v199, v244
	s_waitcnt lgkmcnt(0)
	v_mul_f32_e32 v148, 0xbfb8aa3b, v122
	v_mul_f32_e32 v149, 0xbfb8aa3b, v106
	v_exp_f32_e32 v148, v148
	v_exp_f32_e32 v149, v149
	v_mul_f32_e32 v150, 0xbfb8aa3b, v90
	v_mul_f32_e32 v151, 0xbfb8aa3b, v74
	v_add_f32_e32 v148, 1.0, v148
	v_add_f32_e32 v149, 1.0, v149
	v_exp_f32_e32 v150, v150
	v_exp_f32_e32 v151, v151
	v_rcp_f32_e32 v148, v148
	v_rcp_f32_e32 v149, v149
	v_add_f32_e32 v150, 1.0, v150
	v_add_f32_e32 v151, 1.0, v151
	v_rcp_f32_e32 v150, v150
	v_rcp_f32_e32 v151, v151
	v_sub_f32_e32 v152, 1.0, v199
	v_fma_f32 v202, v148, v152, v199
	v_fma_f32 v203, v149, v152, v199
	v_log_f32_e32 v148, v202
	v_log_f32_e32 v149, v203
	v_fma_f32 v204, v150, v152, v199
	v_fmac_f32_e32 v199, v151, v152
	v_mul_f32_e32 v152, 0x3f317218, v148
	v_mul_f32_e32 v153, 0x3f317218, v149
	v_log_f32_e32 v150, v204
	v_log_f32_e32 v151, v199
	v_mov_b32_dpp v152, v152 row_shr:1 row_mask:0xf bank_mask:0xf bound_ctrl:1
	v_mov_b32_dpp v153, v153 row_shr:1 row_mask:0xf bank_mask:0xf bound_ctrl:1
	v_fmac_f32_e32 v152, 0x3f317218, v148
	v_fmac_f32_e32 v153, 0x3f317218, v149
	v_mul_f32_e32 v154, 0x3f317218, v150
	v_add_f32_dpp v148, v152, v152 row_shr:2 row_mask:0xf bank_mask:0xf bound_ctrl:1
	v_add_f32_dpp v149, v153, v153 row_shr:2 row_mask:0xf bank_mask:0xf bound_ctrl:1
	v_mul_f32_e32 v155, 0x3f317218, v151
	v_add_f32_dpp v148, v148, v148 row_shr:4 row_mask:0xf bank_mask:0xf bound_ctrl:1
	v_add_f32_dpp v149, v149, v149 row_shr:4 row_mask:0xf bank_mask:0xf bound_ctrl:1
	v_mov_b32_dpp v154, v154 row_shr:1 row_mask:0xf bank_mask:0xf bound_ctrl:1
	v_add_f32_dpp v205, v148, v148 row_shr:8 row_mask:0xf bank_mask:0xf bound_ctrl:1
	v_add_f32_dpp v206, v149, v149 row_shr:8 row_mask:0xf bank_mask:0xf bound_ctrl:1
	v_mov_b32_dpp v156, v155 row_shr:1 row_mask:0xf bank_mask:0xf bound_ctrl:1
	ds_bpermute_b32 v155, v135, v205
	ds_bpermute_b32 v149, v135, v206
	v_fmac_f32_e32 v154, 0x3f317218, v150
	v_fmac_f32_e32 v156, 0x3f317218, v151
	s_nop 0
	v_add_f32_dpp v150, v154, v154 row_shr:2 row_mask:0xf bank_mask:0xf bound_ctrl:1
	v_add_f32_dpp v148, v156, v156 row_shr:2 row_mask:0xf bank_mask:0xf bound_ctrl:1
	s_nop 0
	v_add_f32_dpp v150, v150, v150 row_shr:4 row_mask:0xf bank_mask:0xf bound_ctrl:1
	v_add_f32_dpp v154, v148, v148 row_shr:4 row_mask:0xf bank_mask:0xf bound_ctrl:1
	s_nop 0
	v_add_f32_dpp v207, v150, v150 row_shr:8 row_mask:0xf bank_mask:0xf bound_ctrl:1
	v_mov_b32_dpp v148, v154 row_shr:8 row_mask:0xf bank_mask:0xf bound_ctrl:1
	ds_bpermute_b32 v152, v135, v207
	s_waitcnt lgkmcnt(1)
	v_pk_add_f32 v[150:151], v[154:155], v[148:149]
	ds_bpermute_b32 v148, v135, v150
	s_waitcnt lgkmcnt(1)
	v_add_f32_e32 v208, v151, v152
	s_and_saveexec_b64 s[70:71], s[4:5]
	s_cbranch_execz .LBB0_151
	s_add_u32 s34, s30, s26
	v_mul_f32_e32 v153, 0x3fb8aa3b, v151
	s_addc_u32 s35, s31, s14
	v_exp_f32_e32 v153, v153
	s_waitcnt lgkmcnt(0)
	v_add_f32_e32 v152, v208, v148
	v_lshl_add_u64 v[148:149], v[136:137], 2, s[34:35]
	v_add_co_u32_e32 v148, vcc, 0x49300000, v148
	s_nop 1
	v_addc_co_u32_e32 v149, vcc, 0, v149, vcc
	global_store_dword v[148:149], v153, off offset:8
	v_mul_f32_e32 v153, 0x3fb8aa3b, v152
	v_sub_f32_e32 v152, v152, v151
	v_mul_f32_e32 v152, 0x3fb8aa3b, v152
	v_exp_f32_e32 v153, v153
	v_exp_f32_e32 v152, v152
	global_store_dword v[148:149], v153, off offset:520
	global_store_dword v[148:149], v152, off offset:1032
; __device__ __forceinline__ float fexp(float x) { return __builtin_amdgcn_exp2f(x * 1.44269504089f); }
; __device__ __forceinline__ float fsigmoid(float x) { return __builtin_amdgcn_rcpf(1.0f + fexp(-x)); }
; __device__ __forceinline__ float row16_scan(float t) { t += dpp0<0x111>(t); t += dpp0<0x112>(t); t += dpp0<0x114>(t); t += dpp0<0x118>(t); return t; }
;     __device__ __forceinline__ void operator()(f32x4 (&acc)[2][2][4][2], const pg8::Unit& u, int wr, int wc, int fr, int fq) const {
;     ...
;                     for (int j = 0; j < 4; ++j) {
;                         const float lbv = lbp[4 * n + j];
;                         float cc[4];
; #pragma unroll
;                         for (int m = 0; m < 4; ++m) { const float s = fsigmoid(acc[ai][1][m][n][j]); const float f = lbv + (1.0f - lbv) * s;
;                             acc[ai][1][m][n][j] = 1.0f - f; cc[m] = row16_scan(__builtin_amdgcn_logf(f) * 0.69314718056f); }
;                         const float t0 = __shfl(cc[0], src15), t1 = __shfl(cc[1], src15), t2 = __shfl(cc[2], src15), t3 = __shfl(cc[3], src15);
;                         const float cmid = t0 + t1, clast = cmid + t2 + t3;
;                         cc[1] += t0; cc[2] += cmid; cc[3] += cmid + t2;
; #pragma unroll
;                         for (int m = 0; m < 4; ++m) { const float x = cc[m] - cmid; const float qv = acc[ai][0][m][n][j];
;                             acc[ai][0][m][n][j] = qv * fsigmoid(qv) * fexp(x); acc[ai][1][m][n][j] *= fexp(-x); }
;                         if (fr == 0) { float* sp = (float*)(ws + WS_SCL) + cb * 384 + c8 + 4 * n + j; sp[0] = fexp(cmid); sp[128] = fexp(clast); sp[256] = fexp(clast - cmid); }
.LBB0_151:
	s_or_b64 exec, exec, s[70:71]
	v_mov_b32_e32 v154, v245
	s_waitcnt lgkmcnt(0)
	v_mul_f32_e32 v148, 0xbfb8aa3b, v123
	v_mul_f32_e32 v149, 0xbfb8aa3b, v107
	v_exp_f32_e32 v148, v148
	v_exp_f32_e32 v149, v149
	v_mul_f32_e32 v152, 0xbfb8aa3b, v91
	v_mul_f32_e32 v153, 0xbfb8aa3b, v75
	v_exp_f32_e32 v152, v152
	v_exp_f32_e32 v153, v153
	v_add_f32_e32 v148, 1.0, v148
	v_add_f32_e32 v149, 1.0, v149
	v_rcp_f32_e32 v148, v148
	v_rcp_f32_e32 v149, v149
	v_add_f32_e32 v152, 1.0, v152
	v_add_f32_e32 v153, 1.0, v153
	v_rcp_f32_e32 v152, v152
	v_rcp_f32_e32 v153, v153
	v_sub_f32_e32 v156, 1.0, v154
	v_fma_f32 v195, v148, v156, v154
	v_fma_f32 v196, v149, v156, v154
	v_log_f32_e32 v148, v195
	v_log_f32_e32 v149, v196
	v_fma_f32 v197, v152, v156, v154
	v_fmac_f32_e32 v154, v153, v156
	v_log_f32_e32 v152, v197
	v_log_f32_e32 v153, v154
	v_mul_f32_e32 v156, 0x3f317218, v148
	v_mul_f32_e32 v157, 0x3f317218, v149
	v_mul_f32_e32 v158, 0x3f317218, v152
	v_mov_b32_dpp v156, v156 row_shr:1 row_mask:0xf bank_mask:0xf bound_ctrl:1
	v_mov_b32_dpp v157, v157 row_shr:1 row_mask:0xf bank_mask:0xf bound_ctrl:1
	v_fmac_f32_e32 v156, 0x3f317218, v148
	v_fmac_f32_e32 v157, 0x3f317218, v149
	v_mul_f32_e32 v159, 0x3f317218, v153
	v_add_f32_dpp v148, v156, v156 row_shr:2 row_mask:0xf bank_mask:0xf bound_ctrl:1
	v_add_f32_dpp v149, v157, v157 row_shr:2 row_mask:0xf bank_mask:0xf bound_ctrl:1
	v_mov_b32_dpp v158, v158 row_shr:1 row_mask:0xf bank_mask:0xf bound_ctrl:1
	v_add_f32_dpp v148, v148, v148 row_shr:4 row_mask:0xf bank_mask:0xf bound_ctrl:1
	v_add_f32_dpp v149, v149, v149 row_shr:4 row_mask:0xf bank_mask:0xf bound_ctrl:1
	v_mov_b32_dpp v159, v159 row_shr:1 row_mask:0xf bank_mask:0xf bound_ctrl:1
	v_add_f32_dpp v198, v148, v148 row_shr:8 row_mask:0xf bank_mask:0xf bound_ctrl:1
	v_add_f32_dpp v200, v149, v149 row_shr:8 row_mask:0xf bank_mask:0xf bound_ctrl:1
	v_fmac_f32_e32 v158, 0x3f317218, v152
	v_fmac_f32_e32 v159, 0x3f317218, v153
	ds_bpermute_b32 v153, v135, v198
	ds_bpermute_b32 v149, v135, v200
	v_add_f32_dpp v152, v158, v158 row_shr:2 row_mask:0xf bank_mask:0xf bound_ctrl:1
	v_add_f32_dpp v148, v159, v159 row_shr:2 row_mask:0xf bank_mask:0xf bound_ctrl:1
	s_nop 0
	v_add_f32_dpp v152, v152, v152 row_shr:4 row_mask:0xf bank_mask:0xf bound_ctrl:1
	s_nop 1
	v_add_f32_dpp v201, v152, v152 row_shr:8 row_mask:0xf bank_mask:0xf bound_ctrl:1
	v_add_f32_dpp v152, v148, v148 row_shr:4 row_mask:0xf bank_mask:0xf bound_ctrl:1
	ds_bpermute_b32 v157, v135, v201
	s_nop 0
	v_mov_b32_dpp v148, v152 row_shr:8 row_mask:0xf bank_mask:0xf bound_ctrl:1
	s_waitcnt lgkmcnt(1)
	v_pk_add_f32 v[148:149], v[152:153], v[148:149]
	ds_bpermute_b32 v156, v135, v148
	s_waitcnt lgkmcnt(1)
	v_add_f32_e32 v152, v149, v157
	s_and_saveexec_b64 s[70:71], s[4:5]
	s_cbranch_execz .LBB0_153
	s_add_u32 s34, s30, s26
	v_mul_f32_e32 v159, 0x3fb8aa3b, v149
	s_addc_u32 s35, s31, s14
	v_exp_f32_e32 v159, v159
	s_waitcnt lgkmcnt(0)
	v_add_f32_e32 v158, v152, v156
	v_lshl_add_u64 v[156:157], v[136:137], 2, s[34:35]
	v_add_co_u32_e32 v156, vcc, 0x49300000, v156
	s_nop 1
	v_addc_co_u32_e32 v157, vcc, 0, v157, vcc
	global_store_dword v[156:157], v159, off offset:12
	v_mul_f32_e32 v159, 0x3fb8aa3b, v158
	v_sub_f32_e32 v158, v158, v149
	v_mul_f32_e32 v158, 0x3fb8aa3b, v158
	v_exp_f32_e32 v159, v159
	v_exp_f32_e32 v158, v158
	global_store_dword v[156:157], v159, off offset:524
	global_store_dword v[156:157], v158, off offset:1036
.LBB0_153:
	s_or_b64 exec, exec, s[70:71]
	v_mov_b32_e32 v216, v246
	s_waitcnt lgkmcnt(0)
	v_mul_f32_e32 v156, 0xbfb8aa3b, v112
	v_mul_f32_e32 v157, 0xbfb8aa3b, v96
	v_exp_f32_e32 v156, v156
	v_exp_f32_e32 v157, v157
	v_mul_f32_e32 v158, 0xbfb8aa3b, v80
	v_mul_f32_e32 v159, 0xbfb8aa3b, v64
	v_add_f32_e32 v156, 1.0, v156
	v_add_f32_e32 v157, 1.0, v157
	v_exp_f32_e32 v158, v158
	v_exp_f32_e32 v159, v159
	v_rcp_f32_e32 v156, v156
	v_rcp_f32_e32 v157, v157
	v_add_f32_e32 v158, 1.0, v158
	v_add_f32_e32 v159, 1.0, v159
	v_rcp_f32_e32 v158, v158
	v_rcp_f32_e32 v159, v159
	v_sub_f32_e32 v160, 1.0, v216
	v_fma_f32 v217, v156, v160, v216
	v_fma_f32 v218, v157, v160, v216
	v_log_f32_e32 v156, v217
	v_log_f32_e32 v157, v218
	v_fma_f32 v219, v158, v160, v216
	v_fmac_f32_e32 v216, v159, v160
	v_mul_f32_e32 v160, 0x3f317218, v156
	v_mul_f32_e32 v161, 0x3f317218, v157
	v_log_f32_e32 v158, v219
	v_log_f32_e32 v159, v216
	v_mov_b32_dpp v160, v160 row_shr:1 row_mask:0xf bank_mask:0xf bound_ctrl:1
	v_mov_b32_dpp v161, v161 row_shr:1 row_mask:0xf bank_mask:0xf bound_ctrl:1
	v_fmac_f32_e32 v160, 0x3f317218, v156
	v_fmac_f32_e32 v161, 0x3f317218, v157
	v_mul_f32_e32 v162, 0x3f317218, v158
	v_add_f32_dpp v156, v160, v160 row_shr:2 row_mask:0xf bank_mask:0xf bound_ctrl:1
	v_add_f32_dpp v157, v161, v161 row_shr:2 row_mask:0xf bank_mask:0xf bound_ctrl:1
	v_mul_f32_e32 v163, 0x3f317218, v159
	v_add_f32_dpp v156, v156, v156 row_shr:4 row_mask:0xf bank_mask:0xf bound_ctrl:1
	v_add_f32_dpp v157, v157, v157 row_shr:4 row_mask:0xf bank_mask:0xf bound_ctrl:1
	v_mov_b32_dpp v162, v162 row_shr:1 row_mask:0xf bank_mask:0xf bound_ctrl:1
	v_add_f32_dpp v220, v156, v156 row_shr:8 row_mask:0xf bank_mask:0xf bound_ctrl:1
	v_add_f32_dpp v229, v157, v157 row_shr:8 row_mask:0xf bank_mask:0xf bound_ctrl:1
	v_mov_b32_dpp v164, v163 row_shr:1 row_mask:0xf bank_mask:0xf bound_ctrl:1
	ds_bpermute_b32 v163, v135, v220
	ds_bpermute_b32 v157, v135, v229
	v_fmac_f32_e32 v162, 0x3f317218, v158
	v_fmac_f32_e32 v164, 0x3f317218, v159
	s_nop 0
	v_add_f32_dpp v158, v162, v162 row_shr:2 row_mask:0xf bank_mask:0xf bound_ctrl:1
	v_add_f32_dpp v156, v164, v164 row_shr:2 row_mask:0xf bank_mask:0xf bound_ctrl:1
	s_nop 0
	v_add_f32_dpp v158, v158, v158 row_shr:4 row_mask:0xf bank_mask:0xf bound_ctrl:1
	v_add_f32_dpp v162, v156, v156 row_shr:4 row_mask:0xf bank_mask:0xf bound_ctrl:1
	s_nop 0
	v_add_f32_dpp v230, v158, v158 row_shr:8 row_mask:0xf bank_mask:0xf bound_ctrl:1
	v_mov_b32_dpp v156, v162 row_shr:8 row_mask:0xf bank_mask:0xf bound_ctrl:1
	ds_bpermute_b32 v160, v135, v230
	s_waitcnt lgkmcnt(1)
	v_pk_add_f32 v[158:159], v[162:163], v[156:157]
	ds_bpermute_b32 v156, v135, v158
	s_waitcnt lgkmcnt(1)
	v_add_f32_e32 v231, v159, v160
	s_and_saveexec_b64 s[70:71], s[4:5]
	s_cbranch_execz .LBB0_155
	s_add_u32 s34, s30, s26
	v_mul_f32_e32 v161, 0x3fb8aa3b, v159
	s_addc_u32 s35, s31, s14
	v_exp_f32_e32 v161, v161
	s_waitcnt lgkmcnt(0)
	v_add_f32_e32 v160, v231, v156
	v_lshl_add_u64 v[156:157], v[136:137], 2, s[34:35]
	v_add_co_u32_e32 v156, vcc, 0x49300000, v156
	s_nop 1
	v_addc_co_u32_e32 v157, vcc, 0, v157, vcc
	global_store_dword v[156:157], v161, off offset:16
	v_mul_f32_e32 v161, 0x3fb8aa3b, v160
	v_sub_f32_e32 v160, v160, v159
	v_mul_f32_e32 v160, 0x3fb8aa3b, v160
	v_exp_f32_e32 v161, v161
	v_exp_f32_e32 v160, v160
	global_store_dword v[156:157], v161, off offset:528
	global_store_dword v[156:157], v160, off offset:1040
; __device__ __forceinline__ float fexp(float x) { return __builtin_amdgcn_exp2f(x * 1.44269504089f); }
; __device__ __forceinline__ float fsigmoid(float x) { return __builtin_amdgcn_rcpf(1.0f + fexp(-x)); }
; __device__ __forceinline__ float row16_scan(float t) { t += dpp0<0x111>(t); t += dpp0<0x112>(t); t += dpp0<0x114>(t); t += dpp0<0x118>(t); return t; }
;     __device__ __forceinline__ void operator()(f32x4 (&acc)[2][2][4][2], const pg8::Unit& u, int wr, int wc, int fr, int fq) const {
;     ...
;                     for (int j = 0; j < 4; ++j) {
;                         const float lbv = lbp[4 * n + j];
;                         float cc[4];
; #pragma unroll
;                         for (int m = 0; m < 4; ++m) { const float s = fsigmoid(acc[ai][1][m][n][j]); const float f = lbv + (1.0f - lbv) * s;
;                             acc[ai][1][m][n][j] = 1.0f - f; cc[m] = row16_scan(__builtin_amdgcn_logf(f) * 0.69314718056f); }
;                         const float t0 = __shfl(cc[0], src15), t1 = __shfl(cc[1], src15), t2 = __shfl(cc[2], src15), t3 = __shfl(cc[3], src15);
;                         const float cmid = t0 + t1, clast = cmid + t2 + t3;
;                         cc[1] += t0; cc[2] += cmid; cc[3] += cmid + t2;
; #pragma unroll
;                         for (int m = 0; m < 4; ++m) { const float x = cc[m] - cmid; const float qv = acc[ai][0][m][n][j];
;                             acc[ai][0][m][n][j] = qv * fsigmoid(qv) * fexp(x); acc[ai][1][m][n][j] *= fexp(-x); }
;                         if (fr == 0) { float* sp = (float*)(ws + WS_SCL) + cb * 384 + c8 + 4 * n + j; sp[0] = fexp(cmid); sp[128] = fexp(clast); sp[256] = fexp(clast - cmid); }
.LBB0_155:
	s_or_b64 exec, exec, s[70:71]
	v_mov_b32_e32 v221, v247
	s_waitcnt lgkmcnt(0)
	v_mul_f32_e32 v156, 0xbfb8aa3b, v113
	v_mul_f32_e32 v157, 0xbfb8aa3b, v97
	v_exp_f32_e32 v156, v156
	v_exp_f32_e32 v157, v157
	v_mul_f32_e32 v160, 0xbfb8aa3b, v81
	v_mul_f32_e32 v161, 0xbfb8aa3b, v65
	v_exp_f32_e32 v160, v160
	v_exp_f32_e32 v161, v161
	v_add_f32_e32 v156, 1.0, v156
	v_add_f32_e32 v157, 1.0, v157
	v_rcp_f32_e32 v156, v156
	v_rcp_f32_e32 v157, v157
	v_add_f32_e32 v160, 1.0, v160
	v_add_f32_e32 v161, 1.0, v161
	v_rcp_f32_e32 v160, v160
	v_rcp_f32_e32 v161, v161
	v_sub_f32_e32 v162, 1.0, v221
	v_fma_f32 v222, v156, v162, v221
	v_fma_f32 v223, v157, v162, v221
	v_log_f32_e32 v156, v222
	v_log_f32_e32 v157, v223
	v_fma_f32 v224, v160, v162, v221
	v_fmac_f32_e32 v221, v161, v162
	v_log_f32_e32 v160, v224
	v_log_f32_e32 v161, v221
	v_mul_f32_e32 v162, 0x3f317218, v156
	v_mul_f32_e32 v164, 0x3f317218, v157
	v_mul_f32_e32 v165, 0x3f317218, v160
	v_mov_b32_dpp v162, v162 row_shr:1 row_mask:0xf bank_mask:0xf bound_ctrl:1
	v_mov_b32_dpp v164, v164 row_shr:1 row_mask:0xf bank_mask:0xf bound_ctrl:1
	v_fmac_f32_e32 v162, 0x3f317218, v156
	v_fmac_f32_e32 v164, 0x3f317218, v157
	v_mul_f32_e32 v166, 0x3f317218, v161
	v_add_f32_dpp v156, v162, v162 row_shr:2 row_mask:0xf bank_mask:0xf bound_ctrl:1
	v_add_f32_dpp v157, v164, v164 row_shr:2 row_mask:0xf bank_mask:0xf bound_ctrl:1
	v_mov_b32_dpp v165, v165 row_shr:1 row_mask:0xf bank_mask:0xf bound_ctrl:1
	v_add_f32_dpp v156, v156, v156 row_shr:4 row_mask:0xf bank_mask:0xf bound_ctrl:1
	v_add_f32_dpp v157, v157, v157 row_shr:4 row_mask:0xf bank_mask:0xf bound_ctrl:1
	v_mov_b32_dpp v166, v166 row_shr:1 row_mask:0xf bank_mask:0xf bound_ctrl:1
	v_add_f32_dpp v225, v156, v156 row_shr:8 row_mask:0xf bank_mask:0xf bound_ctrl:1
	v_add_f32_dpp v226, v157, v157 row_shr:8 row_mask:0xf bank_mask:0xf bound_ctrl:1
	v_fmac_f32_e32 v165, 0x3f317218, v160
	v_fmac_f32_e32 v166, 0x3f317218, v161
	ds_bpermute_b32 v161, v135, v225
	ds_bpermute_b32 v157, v135, v226
	v_add_f32_dpp v160, v165, v165 row_shr:2 row_mask:0xf bank_mask:0xf bound_ctrl:1
	v_add_f32_dpp v156, v166, v166 row_shr:2 row_mask:0xf bank_mask:0xf bound_ctrl:1
	s_nop 0
	v_add_f32_dpp v160, v160, v160 row_shr:4 row_mask:0xf bank_mask:0xf bound_ctrl:1
	s_nop 1
	v_add_f32_dpp v227, v160, v160 row_shr:8 row_mask:0xf bank_mask:0xf bound_ctrl:1
	v_add_f32_dpp v160, v156, v156 row_shr:4 row_mask:0xf bank_mask:0xf bound_ctrl:1
	ds_bpermute_b32 v162, v135, v227
	s_nop 0
	v_mov_b32_dpp v156, v160 row_shr:8 row_mask:0xf bank_mask:0xf bound_ctrl:1
	s_waitcnt lgkmcnt(1)
	v_pk_add_f32 v[156:157], v[160:161], v[156:157]
	ds_bpermute_b32 v160, v135, v156
	s_waitcnt lgkmcnt(1)
	v_add_f32_e32 v228, v157, v162
	s_and_saveexec_b64 s[70:71], s[4:5]
	s_cbranch_execz .LBB0_157
	s_add_u32 s34, s30, s26
	v_mul_f32_e32 v162, 0x3fb8aa3b, v157
	s_addc_u32 s35, s31, s14
	v_exp_f32_e32 v162, v162
	v_lshl_add_u64 v[164:165], v[136:137], 2, s[34:35]
	v_add_co_u32_e32 v164, vcc, 0x49300000, v164
	s_waitcnt lgkmcnt(0)
	v_add_f32_e32 v160, v228, v160
	v_addc_co_u32_e32 v165, vcc, 0, v165, vcc
	global_store_dword v[164:165], v162, off offset:20
	v_mul_f32_e32 v162, 0x3fb8aa3b, v160
	v_sub_f32_e32 v160, v160, v157
	v_mul_f32_e32 v160, 0x3fb8aa3b, v160
	v_exp_f32_e32 v162, v162
	v_exp_f32_e32 v160, v160
	global_store_dword v[164:165], v162, off offset:532
	global_store_dword v[164:165], v160, off offset:1044
.LBB0_157:
	s_or_b64 exec, exec, s[70:71]
	s_waitcnt lgkmcnt(0)
	v_mov_b32_e32 v160, v248
	v_mul_f32_e32 v162, 0xbfb8aa3b, v114
	v_mul_f32_e32 v164, 0xbfb8aa3b, v98
	v_mul_f32_e32 v165, 0xbfb8aa3b, v82
	v_exp_f32_e32 v162, v162
	v_exp_f32_e32 v164, v164
	v_exp_f32_e32 v165, v165
	v_mul_f32_e32 v166, 0xbfb8aa3b, v66
	v_add_f32_e32 v162, 1.0, v162
	v_add_f32_e32 v164, 1.0, v164
	v_exp_f32_e32 v166, v166
	v_add_f32_e32 v165, 1.0, v165
	v_rcp_f32_e32 v162, v162
	v_rcp_f32_e32 v164, v164
	v_rcp_f32_e32 v165, v165
	v_add_f32_e32 v166, 1.0, v166
	v_rcp_f32_e32 v166, v166
	v_sub_f32_e32 v167, 1.0, v160
	v_fma_f32 v162, v162, v167, v160
	v_fma_f32 v209, v164, v167, v160
	v_fma_f32 v235, v165, v167, v160
	v_log_f32_e32 v164, v162
	v_log_f32_e32 v165, v209
	v_fmac_f32_e32 v160, v166, v167
	v_log_f32_e32 v166, v235
	v_mul_f32_e32 v168, 0x3f317218, v164
	v_mul_f32_e32 v169, 0x3f317218, v165
	v_log_f32_e32 v167, v160
	v_mov_b32_dpp v168, v168 row_shr:1 row_mask:0xf bank_mask:0xf bound_ctrl:1
	v_mov_b32_dpp v169, v169 row_shr:1 row_mask:0xf bank_mask:0xf bound_ctrl:1
	v_fmac_f32_e32 v168, 0x3f317218, v164
	v_fmac_f32_e32 v169, 0x3f317218, v165
	v_mul_f32_e32 v170, 0x3f317218, v166
	v_add_f32_dpp v164, v168, v168 row_shr:2 row_mask:0xf bank_mask:0xf bound_ctrl:1
	v_add_f32_dpp v165, v169, v169 row_shr:2 row_mask:0xf bank_mask:0xf bound_ctrl:1
	v_mul_f32_e32 v171, 0x3f317218, v167
	v_add_f32_dpp v164, v164, v164 row_shr:4 row_mask:0xf bank_mask:0xf bound_ctrl:1
	v_add_f32_dpp v165, v165, v165 row_shr:4 row_mask:0xf bank_mask:0xf bound_ctrl:1
	v_mov_b32_dpp v170, v170 row_shr:1 row_mask:0xf bank_mask:0xf bound_ctrl:1
	v_add_f32_dpp v236, v164, v164 row_shr:8 row_mask:0xf bank_mask:0xf bound_ctrl:1
	v_add_f32_dpp v237, v165, v165 row_shr:8 row_mask:0xf bank_mask:0xf bound_ctrl:1
	v_mov_b32_dpp v211, v171 row_shr:1 row_mask:0xf bank_mask:0xf bound_ctrl:1
	ds_bpermute_b32 v171, v135, v236
	ds_bpermute_b32 v165, v135, v237
	v_fmac_f32_e32 v170, 0x3f317218, v166
	v_fmac_f32_e32 v211, 0x3f317218, v167
	s_nop 0
	v_add_f32_dpp v166, v170, v170 row_shr:2 row_mask:0xf bank_mask:0xf bound_ctrl:1
	v_add_f32_dpp v164, v211, v211 row_shr:2 row_mask:0xf bank_mask:0xf bound_ctrl:1
	s_nop 0
	v_add_f32_dpp v166, v166, v166 row_shr:4 row_mask:0xf bank_mask:0xf bound_ctrl:1
	v_add_f32_dpp v170, v164, v164 row_shr:4 row_mask:0xf bank_mask:0xf bound_ctrl:1
	s_nop 0
	v_add_f32_dpp v238, v166, v166 row_shr:8 row_mask:0xf bank_mask:0xf bound_ctrl:1
	v_mov_b32_dpp v164, v170 row_shr:8 row_mask:0xf bank_mask:0xf bound_ctrl:1
	ds_bpermute_b32 v168, v135, v238
	s_waitcnt lgkmcnt(1)
	v_pk_add_f32 v[166:167], v[170:171], v[164:165]
	ds_bpermute_b32 v164, v135, v166
	s_waitcnt lgkmcnt(1)
	v_add_f32_e32 v170, v167, v168
	s_and_saveexec_b64 s[70:71], s[4:5]
	s_cbranch_execz .LBB0_159
	s_add_u32 s34, s30, s26
	v_mul_f32_e32 v169, 0x3fb8aa3b, v167
	s_addc_u32 s35, s31, s14
	v_exp_f32_e32 v169, v169
	s_waitcnt lgkmcnt(0)
	v_add_f32_e32 v168, v170, v164
	v_lshl_add_u64 v[164:165], v[136:137], 2, s[34:35]
	v_add_co_u32_e32 v164, vcc, 0x49300000, v164
	s_nop 1
	v_addc_co_u32_e32 v165, vcc, 0, v165, vcc
	global_store_dword v[164:165], v169, off offset:24
	v_mul_f32_e32 v169, 0x3fb8aa3b, v168
	v_sub_f32_e32 v168, v168, v167
	v_mul_f32_e32 v168, 0x3fb8aa3b, v168
	v_exp_f32_e32 v169, v169
	v_exp_f32_e32 v168, v168
	global_store_dword v[164:165], v169, off offset:536
	global_store_dword v[164:165], v168, off offset:1048
; __device__ __forceinline__ float fexp(float x) { return __builtin_amdgcn_exp2f(x * 1.44269504089f); }
; __device__ __forceinline__ float fsigmoid(float x) { return __builtin_amdgcn_rcpf(1.0f + fexp(-x)); }
; __device__ __forceinline__ float row16_scan(float t) { t += dpp0<0x111>(t); t += dpp0<0x112>(t); t += dpp0<0x114>(t); t += dpp0<0x118>(t); return t; }
;     __device__ __forceinline__ void operator()(f32x4 (&acc)[2][2][4][2], const pg8::Unit& u, int wr, int wc, int fr, int fq) const {
;     ...
;                     for (int j = 0; j < 4; ++j) {
;                         const float lbv = lbp[4 * n + j];
;                         float cc[4];
; #pragma unroll
;                         for (int m = 0; m < 4; ++m) { const float s = fsigmoid(acc[ai][1][m][n][j]); const float f = lbv + (1.0f - lbv) * s;
;                             acc[ai][1][m][n][j] = 1.0f - f; cc[m] = row16_scan(__builtin_amdgcn_logf(f) * 0.69314718056f); }
;                         const float t0 = __shfl(cc[0], src15), t1 = __shfl(cc[1], src15), t2 = __shfl(cc[2], src15), t3 = __shfl(cc[3], src15);
;                         const float cmid = t0 + t1, clast = cmid + t2 + t3;
;                         cc[1] += t0; cc[2] += cmid; cc[3] += cmid + t2;
; #pragma unroll
;                         for (int m = 0; m < 4; ++m) { const float x = cc[m] - cmid; const float qv = acc[ai][0][m][n][j];
;                             acc[ai][0][m][n][j] = qv * fsigmoid(qv) * fexp(x); acc[ai][1][m][n][j] *= fexp(-x); }
.LBB0_159:
	s_or_b64 exec, exec, s[70:71]
	v_mov_b32_e32 v211, v249
	s_waitcnt lgkmcnt(0)
	v_mul_f32_e32 v164, 0xbfb8aa3b, v115
	v_mul_f32_e32 v165, 0xbfb8aa3b, v99
	v_exp_f32_e32 v164, v164
	v_exp_f32_e32 v165, v165
	v_mul_f32_e32 v168, 0xbfb8aa3b, v83
	v_mul_f32_e32 v169, 0xbfb8aa3b, v67
	v_exp_f32_e32 v168, v168
	v_exp_f32_e32 v169, v169
	v_add_f32_e32 v164, 1.0, v164
	v_add_f32_e32 v165, 1.0, v165
	v_rcp_f32_e32 v164, v164
	v_rcp_f32_e32 v165, v165
	v_add_f32_e32 v168, 1.0, v168
	v_add_f32_e32 v169, 1.0, v169
	v_rcp_f32_e32 v168, v168
	v_rcp_f32_e32 v169, v169
	v_sub_f32_e32 v215, 1.0, v211
	v_fma_f32 v212, v164, v215, v211
	v_fma_f32 v213, v165, v215, v211
	v_log_f32_e32 v164, v212
	v_log_f32_e32 v165, v213
	v_fma_f32 v214, v168, v215, v211
	v_fmac_f32_e32 v211, v169, v215
	v_log_f32_e32 v168, v214
	v_log_f32_e32 v169, v211
	v_mul_f32_e32 v215, 0x3f317218, v164
	v_mul_f32_e32 v232, 0x3f317218, v165
	v_mul_f32_e32 v233, 0x3f317218, v168
	v_mov_b32_dpp v215, v215 row_shr:1 row_mask:0xf bank_mask:0xf bound_ctrl:1
	v_mov_b32_dpp v232, v232 row_shr:1 row_mask:0xf bank_mask:0xf bound_ctrl:1
	v_fmac_f32_e32 v215, 0x3f317218, v164
	v_fmac_f32_e32 v232, 0x3f317218, v165
	v_mul_f32_e32 v234, 0x3f317218, v169
	v_add_f32_dpp v164, v215, v215 row_shr:2 row_mask:0xf bank_mask:0xf bound_ctrl:1
	v_add_f32_dpp v165, v232, v232 row_shr:2 row_mask:0xf bank_mask:0xf bound_ctrl:1
	v_mov_b32_dpp v233, v233 row_shr:1 row_mask:0xf bank_mask:0xf bound_ctrl:1
	v_add_f32_dpp v164, v164, v164 row_shr:4 row_mask:0xf bank_mask:0xf bound_ctrl:1
	v_add_f32_dpp v165, v165, v165 row_shr:4 row_mask:0xf bank_mask:0xf bound_ctrl:1
	v_mov_b32_dpp v234, v234 row_shr:1 row_mask:0xf bank_mask:0xf bound_ctrl:1
	v_add_f32_dpp v215, v164, v164 row_shr:8 row_mask:0xf bank_mask:0xf bound_ctrl:1
	v_add_f32_dpp v232, v165, v165 row_shr:8 row_mask:0xf bank_mask:0xf bound_ctrl:1
	v_fmac_f32_e32 v233, 0x3f317218, v168
	v_fmac_f32_e32 v234, 0x3f317218, v169
	ds_bpermute_b32 v169, v135, v215
	ds_bpermute_b32 v165, v135, v232
	v_add_f32_dpp v168, v233, v233 row_shr:2 row_mask:0xf bank_mask:0xf bound_ctrl:1
	v_add_f32_dpp v164, v234, v234 row_shr:2 row_mask:0xf bank_mask:0xf bound_ctrl:1
	s_nop 0
	v_add_f32_dpp v168, v168, v168 row_shr:4 row_mask:0xf bank_mask:0xf bound_ctrl:1
	s_nop 1
	v_add_f32_dpp v233, v168, v168 row_shr:8 row_mask:0xf bank_mask:0xf bound_ctrl:1
	v_add_f32_dpp v168, v164, v164 row_shr:4 row_mask:0xf bank_mask:0xf bound_ctrl:1
	ds_bpermute_b32 v234, v135, v233
	s_nop 0
	v_mov_b32_dpp v164, v168 row_shr:8 row_mask:0xf bank_mask:0xf bound_ctrl:1
	s_waitcnt lgkmcnt(1)
	v_pk_add_f32 v[164:165], v[168:169], v[164:165]
	ds_bpermute_b32 v168, v135, v164
	s_waitcnt lgkmcnt(1)
	v_add_f32_e32 v234, v165, v234
	s_and_saveexec_b64 s[70:71], s[4:5]
	s_cbranch_execz .LBB0_161
	s_add_u32 s26, s30, s26
	v_mul_f32_e32 v239, 0x3fb8aa3b, v165
	s_addc_u32 s27, s31, s14
	v_exp_f32_e32 v239, v239
	v_lshl_add_u64 v[240:241], v[136:137], 2, s[26:27]
	v_add_co_u32_e32 v240, vcc, 0x49300000, v240
	s_waitcnt lgkmcnt(0)
	v_add_f32_e32 v168, v234, v168
	v_addc_co_u32_e32 v241, vcc, 0, v241, vcc
	global_store_dword v[240:241], v239, off offset:28
	v_mul_f32_e32 v239, 0x3fb8aa3b, v168
	v_sub_f32_e32 v168, v168, v165
	v_mul_f32_e32 v168, 0x3fb8aa3b, v168
	v_exp_f32_e32 v239, v239
	v_exp_f32_e32 v168, v168
	global_store_dword v[240:241], v239, off offset:540
	global_store_dword v[240:241], v168, off offset:1052
.LBB0_161:
	s_or_b64 exec, exec, s[70:71]
	s_waitcnt lgkmcnt(0)
	v_sub_f32_e32 v168, 1.0, v162
	v_sub_f32_e32 v239, 1.0, v160
	v_sub_f32_e32 v160, v236, v167
	v_mul_f32_e32 v162, 0xbfb8aa3b, v118
	v_add_f32_e32 v171, v237, v171
	v_add_f32_e32 v237, v238, v167
	v_add_f32_e32 v238, v166, v170
	v_exp_f32_e32 v162, v162
	v_mul_f32_e32 v166, 0x3fb8aa3b, v160
	v_mul_f32_e32 v160, 0xbfb8aa3b, v160
	v_exp_f32_e32 v160, v160
	v_add_f32_e32 v162, 1.0, v162
	v_rcp_f32_e32 v162, v162
	v_exp_f32_e32 v166, v166
	v_mul_f32_e32 v160, v168, v160
	v_mul_f32_e32 v168, 0xbfb8aa3b, v102
	v_exp_f32_e32 v168, v168
	v_mul_f32_e32 v162, v118, v162
	v_mul_f32_e32 v162, v162, v166
	v_sub_f32_e32 v166, v171, v167
	v_add_f32_e32 v168, 1.0, v168
	v_rcp_f32_e32 v168, v168
	v_mul_f32_e32 v170, 0x3fb8aa3b, v166
	v_mul_f32_e32 v171, 0xbfb8aa3b, v86
	v_exp_f32_e32 v170, v170
	v_mul_f32_e32 v166, 0xbfb8aa3b, v166
	v_exp_f32_e32 v171, v171
	v_exp_f32_e32 v166, v166
	v_mul_f32_e32 v168, v102, v168
	v_sub_f32_e32 v209, 1.0, v209
	v_mul_f32_e32 v168, v168, v170
	v_sub_f32_e32 v170, v237, v167
	v_add_f32_e32 v171, 1.0, v171
	v_mul_f32_e32 v166, v209, v166
	v_rcp_f32_e32 v171, v171
	v_mul_f32_e32 v209, 0x3fb8aa3b, v170
	v_exp_f32_e32 v209, v209
	v_sub_f32_e32 v236, 1.0, v211
	v_add_f32_e32 v211, v232, v169
	v_mul_f32_e32 v169, 0xbfb8aa3b, v119
	v_exp_f32_e32 v169, v169
	v_mul_f32_e32 v171, v86, v171
	v_mul_f32_e32 v171, v171, v209
	v_sub_f32_e32 v209, v238, v167
	v_mul_f32_e32 v167, 0xbfb8aa3b, v70
	v_mul_f32_e32 v170, 0xbfb8aa3b, v170
	v_exp_f32_e32 v167, v167
	v_add_f32_e32 v232, v164, v234
	v_sub_f32_e32 v164, v215, v165
	v_add_f32_e32 v169, 1.0, v169
	v_exp_f32_e32 v170, v170
	v_rcp_f32_e32 v169, v169
	v_mul_f32_e32 v215, 0x3fb8aa3b, v164
	v_mul_f32_e32 v164, 0xbfb8aa3b, v164
	v_exp_f32_e32 v215, v215
	v_exp_f32_e32 v164, v164
	v_sub_f32_e32 v235, 1.0, v235
	v_add_f32_e32 v167, 1.0, v167
	v_mul_f32_e32 v170, v235, v170
	v_rcp_f32_e32 v167, v167
	v_mul_f32_e32 v235, 0x3fb8aa3b, v209
	v_sub_f32_e32 v212, 1.0, v212
	v_mul_f32_e32 v169, v119, v169
	v_sub_f32_e32 v211, v211, v165
	v_exp_f32_e32 v235, v235
	v_mul_f32_e32 v169, v169, v215
	v_mul_f32_e32 v164, v212, v164
	v_mul_f32_e32 v212, 0xbfb8aa3b, v103
	v_mul_f32_e32 v215, 0x3fb8aa3b, v211
; __device__ __forceinline__ float fexp(float x) { return __builtin_amdgcn_exp2f(x * 1.44269504089f); }
; __device__ __forceinline__ float fsigmoid(float x) { return __builtin_amdgcn_rcpf(1.0f + fexp(-x)); }
;     __device__ __forceinline__ void operator()(f32x4 (&acc)[2][2][4][2], const pg8::Unit& u, int wr, int wc, int fr, int fq) const {
;     ...
;                         const float cmid = t0 + t1, clast = cmid + t2 + t3;
;                         cc[1] += t0; cc[2] += cmid; cc[3] += cmid + t2;
; #pragma unroll
;                         for (int m = 0; m < 4; ++m) { const float x = cc[m] - cmid; const float qv = acc[ai][0][m][n][j];
;                             acc[ai][0][m][n][j] = qv * fsigmoid(qv) * fexp(x); acc[ai][1][m][n][j] *= fexp(-x); }
	v_mul_f32_e32 v211, 0xbfb8aa3b, v211
	v_exp_f32_e32 v212, v212
	v_exp_f32_e32 v211, v211
	v_mul_f32_e32 v167, v70, v167
	v_mul_f32_e32 v167, v167, v235
	v_sub_f32_e32 v213, 1.0, v213
	v_sub_f32_e32 v235, 1.0, v214
	v_add_f32_e32 v214, v233, v165
	v_add_f32_e32 v212, 1.0, v212
	v_mul_f32_e32 v211, v213, v211
	v_sub_f32_e32 v213, v214, v165
	v_mul_f32_e32 v214, 0xbfb8aa3b, v87
	v_rcp_f32_e32 v212, v212
	v_exp_f32_e32 v214, v214
	v_exp_f32_e32 v215, v215
	v_sub_f32_e32 v233, 1.0, v216
	v_mul_f32_e32 v212, v103, v212
	v_add_f32_e32 v214, 1.0, v214
	v_mul_f32_e32 v212, v212, v215
	v_rcp_f32_e32 v214, v214
	v_mul_f32_e32 v215, 0x3fb8aa3b, v213
	v_exp_f32_e32 v215, v215
	v_add_f32_e32 v216, v229, v163
	v_mul_f32_e32 v163, 0xbfb8aa3b, v116
	v_exp_f32_e32 v163, v163
	v_mul_f32_e32 v214, v87, v214
	v_mul_f32_e32 v214, v214, v215
	v_sub_f32_e32 v215, v232, v165
	v_mul_f32_e32 v165, 0xbfb8aa3b, v71
	v_exp_f32_e32 v165, v165
	v_add_f32_e32 v229, v158, v231
	v_sub_f32_e32 v158, v220, v159
	v_add_f32_e32 v163, 1.0, v163
	v_rcp_f32_e32 v163, v163
	v_mul_f32_e32 v220, 0x3fb8aa3b, v158
	v_mul_f32_e32 v158, 0xbfb8aa3b, v158
	v_exp_f32_e32 v220, v220
	v_exp_f32_e32 v158, v158
	v_add_f32_e32 v165, 1.0, v165
	v_rcp_f32_e32 v165, v165
	v_mul_f32_e32 v232, 0x3fb8aa3b, v215
	v_sub_f32_e32 v217, 1.0, v217
	v_mul_f32_e32 v163, v116, v163
	v_sub_f32_e32 v216, v216, v159
	v_exp_f32_e32 v232, v232
	v_mul_f32_e32 v163, v163, v220
	v_mul_f32_e32 v158, v217, v158
	v_mul_f32_e32 v217, 0xbfb8aa3b, v100
	v_mul_f32_e32 v220, 0x3fb8aa3b, v216
	v_mul_f32_e32 v216, 0xbfb8aa3b, v216
	v_exp_f32_e32 v217, v217
	v_exp_f32_e32 v216, v216
	v_mul_f32_e32 v165, v71, v165
	v_mul_f32_e32 v165, v165, v232
	v_sub_f32_e32 v218, 1.0, v218
	v_sub_f32_e32 v232, 1.0, v219
	v_add_f32_e32 v219, v230, v159
	v_add_f32_e32 v217, 1.0, v217
	v_mul_f32_e32 v216, v218, v216
	v_sub_f32_e32 v218, v219, v159
	v_mul_f32_e32 v219, 0xbfb8aa3b, v84
	v_rcp_f32_e32 v217, v217
	v_exp_f32_e32 v219, v219
	v_exp_f32_e32 v220, v220
	v_sub_f32_e32 v230, 1.0, v221
	v_mul_f32_e32 v217, v100, v217
	v_add_f32_e32 v219, 1.0, v219
	v_mul_f32_e32 v217, v217, v220
	v_rcp_f32_e32 v219, v219
	v_mul_f32_e32 v220, 0x3fb8aa3b, v218
	v_exp_f32_e32 v220, v220
	v_add_f32_e32 v221, v226, v161
	v_mul_f32_e32 v161, 0xbfb8aa3b, v117
	v_exp_f32_e32 v161, v161
	v_mul_f32_e32 v219, v84, v219
	v_mul_f32_e32 v219, v219, v220
	v_sub_f32_e32 v220, v229, v159
	v_mul_f32_e32 v159, 0xbfb8aa3b, v68
	v_exp_f32_e32 v159, v159
	v_add_f32_e32 v226, v156, v228
	v_sub_f32_e32 v156, v225, v157
	v_add_f32_e32 v161, 1.0, v161
	v_rcp_f32_e32 v161, v161
	v_mul_f32_e32 v225, 0x3fb8aa3b, v156
	v_mul_f32_e32 v156, 0xbfb8aa3b, v156
	v_exp_f32_e32 v225, v225
	v_exp_f32_e32 v156, v156
	v_add_f32_e32 v159, 1.0, v159
	v_rcp_f32_e32 v159, v159
	v_mul_f32_e32 v229, 0x3fb8aa3b, v220
	v_sub_f32_e32 v222, 1.0, v222
	v_mul_f32_e32 v161, v117, v161
	v_sub_f32_e32 v221, v221, v157
	v_exp_f32_e32 v229, v229
	v_mul_f32_e32 v161, v161, v225
	v_mul_f32_e32 v156, v222, v156
	v_mul_f32_e32 v222, 0xbfb8aa3b, v101
	v_mul_f32_e32 v225, 0x3fb8aa3b, v221
	v_mul_f32_e32 v221, 0xbfb8aa3b, v221
	v_exp_f32_e32 v222, v222
	v_exp_f32_e32 v221, v221
	v_mul_f32_e32 v159, v68, v159
	v_mul_f32_e32 v159, v159, v229
	v_sub_f32_e32 v223, 1.0, v223
	v_sub_f32_e32 v229, 1.0, v224
	v_add_f32_e32 v224, v227, v157
	v_add_f32_e32 v222, 1.0, v222
	v_mul_f32_e32 v221, v223, v221
	v_sub_f32_e32 v223, v224, v157
	v_mul_f32_e32 v224, 0xbfb8aa3b, v85
	v_rcp_f32_e32 v222, v222
	v_exp_f32_e32 v224, v224
	v_exp_f32_e32 v225, v225
	v_sub_f32_e32 v227, 1.0, v199
	v_mul_f32_e32 v222, v101, v222
	v_add_f32_e32 v224, 1.0, v224
	v_mul_f32_e32 v222, v222, v225
	v_rcp_f32_e32 v224, v224
	v_mul_f32_e32 v225, 0x3fb8aa3b, v223
	v_exp_f32_e32 v225, v225
	v_add_f32_e32 v199, v206, v155
	v_mul_f32_e32 v155, 0xbfb8aa3b, v126
	v_exp_f32_e32 v155, v155
	v_mul_f32_e32 v224, v85, v224
	v_mul_f32_e32 v224, v224, v225
	v_sub_f32_e32 v225, v226, v157
	v_mul_f32_e32 v157, 0xbfb8aa3b, v69
	v_exp_f32_e32 v157, v157
	v_add_f32_e32 v206, v150, v208
	v_sub_f32_e32 v150, v205, v151
	v_add_f32_e32 v155, 1.0, v155
	v_rcp_f32_e32 v155, v155
	v_mul_f32_e32 v205, 0x3fb8aa3b, v150
	v_mul_f32_e32 v150, 0xbfb8aa3b, v150
	v_exp_f32_e32 v205, v205
	v_exp_f32_e32 v150, v150
	v_add_f32_e32 v157, 1.0, v157
	v_rcp_f32_e32 v157, v157
	v_mul_f32_e32 v226, 0x3fb8aa3b, v225
	v_sub_f32_e32 v202, 1.0, v202
	v_mul_f32_e32 v155, v126, v155
	v_sub_f32_e32 v199, v199, v151
	v_exp_f32_e32 v226, v226
	v_mul_f32_e32 v155, v155, v205
	v_mul_f32_e32 v150, v202, v150
	v_mul_f32_e32 v202, 0xbfb8aa3b, v110
	v_mul_f32_e32 v205, 0x3fb8aa3b, v199
	v_mul_f32_e32 v199, 0xbfb8aa3b, v199
	v_exp_f32_e32 v202, v202
	v_exp_f32_e32 v199, v199
	v_mul_f32_e32 v157, v69, v157
	v_mul_f32_e32 v157, v157, v226
	v_sub_f32_e32 v203, 1.0, v203
	v_sub_f32_e32 v226, 1.0, v204
	v_add_f32_e32 v204, v207, v151
	v_add_f32_e32 v202, 1.0, v202
	v_mul_f32_e32 v199, v203, v199
	v_sub_f32_e32 v203, v204, v151
	v_mul_f32_e32 v204, 0xbfb8aa3b, v94
	v_rcp_f32_e32 v202, v202
	v_exp_f32_e32 v204, v204
	v_exp_f32_e32 v205, v205
	v_add_f32_e32 v147, v192, v147
	v_mul_f32_e32 v202, v110, v202
	v_add_f32_e32 v204, 1.0, v204
	v_mul_f32_e32 v202, v202, v205
	v_rcp_f32_e32 v204, v204
	v_mul_f32_e32 v205, 0x3fb8aa3b, v203
	v_exp_f32_e32 v205, v205
	v_add_f32_e32 v192, v193, v143
	v_mul_f32_e32 v204, v94, v204
	v_sub_f32_e32 v191, v191, v143
	v_mul_f32_e32 v204, v204, v205
	v_sub_f32_e32 v205, v206, v151
	v_mul_f32_e32 v151, 0xbfb8aa3b, v78
	v_exp_f32_e32 v151, v151
	v_mul_f32_e32 v193, 0xbfb8aa3b, v124
	v_add_f32_e32 v142, v142, v194
	v_exp_f32_e32 v193, v193
	v_mul_f32_e32 v194, 0x3fb8aa3b, v191
; __device__ __forceinline__ float fexp(float x) { return __builtin_amdgcn_exp2f(x * 1.44269504089f); }
; __device__ __forceinline__ float fsigmoid(float x) { return __builtin_amdgcn_rcpf(1.0f + fexp(-x)); }
;     __device__ __forceinline__ void operator()(f32x4 (&acc)[2][2][4][2], const pg8::Unit& u, int wr, int wc, int fr, int fq) const {
;     ...
;                         for (int m = 0; m < 4; ++m) { const float x = cc[m] - cmid; const float qv = acc[ai][0][m][n][j];
;                             acc[ai][0][m][n][j] = qv * fsigmoid(qv) * fexp(x); acc[ai][1][m][n][j] *= fexp(-x); }
;                         if (fr == 0) { float* sp = (float*)(ws + WS_SCL) + cb * 384 + c8 + 4 * n + j; sp[0] = fexp(cmid); sp[128] = fexp(clast); sp[256] = fexp(clast - cmid); }
;                         asm volatile("" ::: "memory");
;                     }
;                 bf16_t* qp = (bf16_t*)(ws + WS_QI) + cb * 8192 + fr * 128 + c8; bf16_t* kp = (bf16_t*)(ws + WS_KI) + cb * 8192 + fr * 128 + c8;
	v_mul_f32_e32 v191, 0xbfb8aa3b, v191
	v_exp_f32_e32 v191, v191
	v_add_f32_e32 v151, 1.0, v151
	v_add_f32_e32 v153, v200, v153
	v_add_f32_e32 v200, v201, v149
	v_add_f32_e32 v201, v148, v152
	v_mul_f32_e32 v152, 0xbfb8aa3b, v127
	v_rcp_f32_e32 v151, v151
	v_mul_f32_e32 v206, 0x3fb8aa3b, v205
	v_exp_f32_e32 v152, v152
	v_exp_f32_e32 v206, v206
	v_sub_f32_e32 v188, 1.0, v188
	v_add_f32_e32 v193, 1.0, v193
	v_rcp_f32_e32 v193, v193
	v_mul_f32_e32 v188, v188, v191
	v_mul_f32_e32 v191, 0xbfb8aa3b, v108
	v_exp_f32_e32 v194, v194
	v_exp_f32_e32 v191, v191
	v_mul_f32_e32 v151, v78, v151
	v_sub_f32_e32 v148, v198, v149
	v_add_f32_e32 v152, 1.0, v152
	v_mul_f32_e32 v151, v151, v206
	v_sub_f32_e32 v206, 1.0, v154
	v_rcp_f32_e32 v152, v152
	v_mul_f32_e32 v154, 0x3fb8aa3b, v148
	v_exp_f32_e32 v154, v154
	v_mul_f32_e32 v193, v124, v193
	v_sub_f32_e32 v147, v147, v143
	v_mul_f32_e32 v193, v193, v194
	v_add_f32_e32 v191, 1.0, v191
	v_mul_f32_e32 v194, 0x3fb8aa3b, v147
	v_mul_f32_e32 v147, 0xbfb8aa3b, v147
	v_rcp_f32_e32 v191, v191
	v_exp_f32_e32 v147, v147
	v_mul_f32_e32 v152, v127, v152
	v_exp_f32_e32 v194, v194
	v_mul_f32_e32 v152, v152, v154
	v_mul_f32_e32 v154, 0xbfb8aa3b, v111
	v_mul_f32_e32 v148, 0xbfb8aa3b, v148
	v_exp_f32_e32 v154, v154
	v_sub_f32_e32 v189, 1.0, v189
	v_exp_f32_e32 v148, v148
	v_mul_f32_e32 v191, v108, v191
	v_mul_f32_e32 v189, v189, v147
	v_sub_f32_e32 v147, v192, v143
	v_mul_f32_e32 v192, 0xbfb8aa3b, v92
	v_sub_f32_e32 v142, v142, v143
	v_mul_f32_e32 v143, 0xbfb8aa3b, v76
	v_mul_f32_e32 v191, v191, v194
	v_exp_f32_e32 v192, v192
	v_mul_f32_e32 v194, 0x3fb8aa3b, v147
	v_mul_f32_e32 v147, 0xbfb8aa3b, v147
	v_exp_f32_e32 v143, v143
	v_exp_f32_e32 v147, v147
	v_sub_f32_e32 v195, 1.0, v195
	v_sub_f32_e32 v153, v153, v149
	v_add_f32_e32 v154, 1.0, v154
	v_mul_f32_e32 v148, v195, v148
	v_rcp_f32_e32 v154, v154
	v_mul_f32_e32 v195, 0x3fb8aa3b, v153
	v_exp_f32_e32 v195, v195
	v_mul_f32_e32 v153, 0xbfb8aa3b, v153
	v_sub_f32_e32 v190, 1.0, v190
	v_add_f32_e32 v192, 1.0, v192
	v_add_f32_e32 v143, 1.0, v143
	v_exp_f32_e32 v153, v153
	v_rcp_f32_e32 v192, v192
	v_mul_f32_e32 v190, v190, v147
	v_rcp_f32_e32 v143, v143
	v_mul_f32_e32 v147, 0x3fb8aa3b, v142
	v_exp_f32_e32 v194, v194
	v_exp_f32_e32 v147, v147
	v_mul_f32_e32 v154, v111, v154
	v_sub_f32_e32 v196, 1.0, v196
	v_mul_f32_e32 v154, v154, v195
	v_sub_f32_e32 v195, v200, v149
	v_mul_f32_e32 v153, v196, v153
	v_mul_f32_e32 v196, 0xbfb8aa3b, v95
	v_mul_f32_e32 v198, 0x3fb8aa3b, v195
	v_mul_f32_e32 v195, 0xbfb8aa3b, v195
	v_mul_f32_e32 v192, v92, v192
	v_mul_f32_e32 v143, v76, v143
	v_mul_f32_e32 v142, 0xbfb8aa3b, v142
	v_add_f32_e32 v140, v140, v144
	v_sub_f32_e32 v144, v184, v141
	v_exp_f32_e32 v196, v196
	v_exp_f32_e32 v195, v195
	v_mul_f32_e32 v192, v192, v194
	v_mul_f32_e32 v194, v143, v147
	v_exp_f32_e32 v142, v142
	v_sub_f32_e32 v147, 1.0, v183
	v_mul_f32_e32 v183, 0x3fb8aa3b, v144
	v_mul_f32_e32 v144, 0xbfb8aa3b, v144
	v_exp_f32_e32 v144, v144
	v_sub_f32_e32 v197, 1.0, v197
	v_sub_f32_e32 v187, 1.0, v187
	v_add_f32_e32 v196, 1.0, v196
	v_mul_f32_e32 v195, v197, v195
	v_sub_f32_e32 v197, v201, v149
	v_mul_f32_e32 v149, 0xbfb8aa3b, v79
	v_mul_f32_e32 v187, v187, v142
	v_sub_f32_e32 v142, 1.0, v173
	v_rcp_f32_e32 v196, v196
	v_exp_f32_e32 v149, v149
	v_add_f32_e32 v145, v185, v145
	v_mul_f32_e32 v185, v142, v144
	v_mul_f32_e32 v144, 0xbfb8aa3b, v109
	v_exp_f32_e32 v198, v198
	v_exp_f32_e32 v144, v144
	v_mul_f32_e32 v196, v95, v196
	v_add_f32_e32 v149, 1.0, v149
	v_sub_f32_e32 v142, v145, v141
	v_mul_f32_e32 v196, v196, v198
	v_rcp_f32_e32 v149, v149
	v_mul_f32_e32 v198, 0x3fb8aa3b, v197
	v_add_f32_e32 v144, 1.0, v144
	v_mul_f32_e32 v145, 0x3fb8aa3b, v142
	v_mul_f32_e32 v142, 0xbfb8aa3b, v142
	v_exp_f32_e32 v198, v198
	v_rcp_f32_e32 v144, v144
	v_exp_f32_e32 v142, v142
	v_exp_f32_e32 v145, v145
	v_mul_f32_e32 v149, v79, v149
	v_sub_f32_e32 v143, 1.0, v182
	v_add_f32_e32 v173, v186, v141
	v_mul_f32_e32 v149, v149, v198
	v_mul_f32_e32 v144, v109, v144
	v_mul_f32_e32 v198, v143, v142
	v_sub_f32_e32 v142, v173, v141
	v_mul_f32_e32 v186, v144, v145
	v_mul_f32_e32 v144, 0x3fb8aa3b, v142
	v_mul_f32_e32 v142, 0xbfb8aa3b, v142
	v_sub_f32_e32 v140, v140, v141
	v_mul_f32_e32 v141, 0xbfb8aa3b, v77
	v_exp_f32_e32 v142, v142
	v_exp_f32_e32 v141, v141
	v_mul_f32_e32 v143, 0xbfb8aa3b, v93
	v_mul_f32_e32 v182, 0xbfb8aa3b, v125
	v_exp_f32_e32 v143, v143
	v_exp_f32_e32 v182, v182
	v_mul_f32_e32 v201, v147, v142
	v_add_f32_e32 v141, 1.0, v141
	v_mul_f32_e32 v142, 0x3fb8aa3b, v140
	v_mul_f32_e32 v140, 0xbfb8aa3b, v140
	v_mul_f32_e32 v197, 0xbfb8aa3b, v197
	v_rcp_f32_e32 v141, v141
	v_exp_f32_e32 v140, v140
	v_exp_f32_e32 v197, v197
	v_add_f32_e32 v143, 1.0, v143
	v_exp_f32_e32 v142, v142
	v_add_f32_e32 v182, 1.0, v182
	v_rcp_f32_e32 v143, v143
	v_sub_f32_e32 v146, 1.0, v146
	v_rcp_f32_e32 v182, v182
	v_exp_f32_e32 v144, v144
	s_lshl_b64 s[26:27], s[68:69], 14
	v_exp_f32_e32 v183, v183
	v_mul_f32_e32 v141, v77, v141
	v_mul_f32_e32 v207, v146, v140
	v_lshlrev_b32_e32 v140, 7, v172
	s_add_u32 s34, s95, s26
	v_mul_f32_e32 v197, v206, v197
	v_mul_f32_e32 v206, v141, v142
	v_ashrrev_i32_e32 v141, 31, v140
	s_addc_u32 s35, s96, s27
	v_mul_f32_e32 v143, v93, v143
	v_lshlrev_b64 v[140:141], 1, v[140:141]
	s_add_u32 s26, s97, s26
	v_mul_f32_e32 v182, v125, v182
	v_mul_f32_e32 v200, v143, v144
	v_lshl_add_u64 v[144:145], s[34:35], 0, v[140:141]
	v_lshlrev_b64 v[142:143], 1, v[136:137]
	s_addc_u32 s27, s85, s27
	v_mul_f32_e32 v184, v182, v183
	v_lshl_add_u64 v[172:173], v[144:145], 0, v[142:143]
	v_lshl_add_u64 v[144:145], s[26:27], 0, v[140:141]
	v_lshl_add_u64 v[182:183], v[144:145], 0, v[142:143]
; __device__ __forceinline__ unsigned pk2(float lo, float hi) { return __builtin_bit_cast(unsigned, __builtin_convertvector((f32x2){lo, hi}, bf16x2_t)); }
; __device__ __forceinline__ float fexp(float x) { return __builtin_amdgcn_exp2f(x * 1.44269504089f); }
; __device__ __forceinline__ float fsigmoid(float x) { return __builtin_amdgcn_rcpf(1.0f + fexp(-x)); }
;     __device__ __forceinline__ void operator()(f32x4 (&acc)[2][2][4][2], const pg8::Unit& u, int wr, int wc, int fr, int fq) const {
;     ...
;                     for (int j = 0; j < 4; ++j) {
;                         const float lbv = lbp[4 * n + j];
;                         float cc[4];
; #pragma unroll
;                         for (int m = 0; m < 4; ++m) { const float s = fsigmoid(acc[ai][1][m][n][j]); const float f = lbv + (1.0f - lbv) * s;
;                             acc[ai][1][m][n][j] = 1.0f - f; cc[m] = row16_scan(__builtin_amdgcn_logf(f) * 0.69314718056f); }
;                         const float t0 = __shfl(cc[0], src15), t1 = __shfl(cc[1], src15), t2 = __shfl(cc[2], src15), t3 = __shfl(cc[3], src15);
;                         const float cmid = t0 + t1, clast = cmid + t2 + t3;
;                         cc[1] += t0; cc[2] += cmid; cc[3] += cmid + t2;
; #pragma unroll
;                         for (int m = 0; m < 4; ++m) { const float x = cc[m] - cmid; const float qv = acc[ai][0][m][n][j];
;                             acc[ai][0][m][n][j] = qv * fsigmoid(qv) * fexp(x); acc[ai][1][m][n][j] *= fexp(-x); }
;                         if (fr == 0) { float* sp = (float*)(ws + WS_SCL) + cb * 384 + c8 + 4 * n + j; sp[0] = fexp(cmid); sp[128] = fexp(clast); sp[256] = fexp(clast - cmid); }
;     ...
;                 bf16_t* qp = (bf16_t*)(ws + WS_QI) + cb * 8192 + fr * 128 + c8; bf16_t* kp = (bf16_t*)(ws + WS_KI) + cb * 8192 + fr * 128 + c8;
; #pragma unroll
;                 for (int m = 0; m < 4; ++m) {
;                     const f32x4 a0 = acc[ai][0][m][0], a1 = acc[ai][0][m][1], b0 = acc[ai][1][m][0], b1 = acc[ai][1][m][1];
;                     *(u32x4*)(qp + m * 2048) = (u32x4){pk2(a0[0], a0[1]), pk2(a0[2], a0[3]), pk2(a1[0], a1[1]), pk2(a1[2], a1[3])};
;                     *(u32x4*)(kp + m * 2048) = (u32x4){pk2(b0[0], b0[1]), pk2(b0[2], b0[3]), pk2(b1[0], b1[1]), pk2(b1[2], b1[3])};
;                 }
	v_cvt_pk_bf16_f32 v144, v193, v184
	v_cvt_pk_bf16_f32 v145, v155, v152
	v_cvt_pk_bf16_f32 v146, v163, v161
	v_cvt_pk_bf16_f32 v147, v162, v169
	v_mul_f32_e32 v213, 0xbfb8aa3b, v213
	v_mul_f32_e32 v218, 0xbfb8aa3b, v218
	v_mul_f32_e32 v223, 0xbfb8aa3b, v223
	v_mul_f32_e32 v203, 0xbfb8aa3b, v203
	global_store_dwordx4 v[172:173], v[144:147], off
	v_exp_f32_e32 v213, v213
	v_exp_f32_e32 v218, v218
	v_cvt_pk_bf16_f32 v144, v188, v185
	v_cvt_pk_bf16_f32 v145, v150, v148
	v_cvt_pk_bf16_f32 v146, v158, v156
	v_cvt_pk_bf16_f32 v147, v160, v164
	v_exp_f32_e32 v223, v223
	v_exp_f32_e32 v203, v203
	global_store_dwordx4 v[182:183], v[144:147], off
	v_mul_f32_e32 v209, 0xbfb8aa3b, v209
	v_mul_f32_e32 v215, 0xbfb8aa3b, v215
	v_cvt_pk_bf16_f32 v145, v202, v154
	v_add_co_u32_e32 v154, vcc, s79, v172
	v_mul_f32_e32 v220, 0xbfb8aa3b, v220
	s_nop 0
	v_addc_co_u32_e32 v155, vcc, 0, v173, vcc
	v_mul_f32_e32 v225, 0xbfb8aa3b, v225
	v_mul_f32_e32 v205, 0xbfb8aa3b, v205
	v_cvt_pk_bf16_f32 v144, v191, v186
	v_cvt_pk_bf16_f32 v146, v217, v222
	v_cvt_pk_bf16_f32 v147, v168, v212
	v_add_co_u32_e32 v152, vcc, s79, v182
	v_exp_f32_e32 v209, v209
	v_exp_f32_e32 v215, v215
	v_exp_f32_e32 v220, v220
	v_exp_f32_e32 v225, v225
	v_exp_f32_e32 v205, v205
	global_store_dwordx4 v[154:155], v[144:147], off offset:-4096
	v_mul_f32_e32 v213, v235, v213
	v_mul_f32_e32 v218, v232, v218
	v_cvt_pk_bf16_f32 v144, v189, v198
	v_cvt_pk_bf16_f32 v145, v199, v153
	v_cvt_pk_bf16_f32 v146, v216, v221
	v_cvt_pk_bf16_f32 v147, v166, v211
	v_addc_co_u32_e32 v153, vcc, 0, v183, vcc
	v_mul_f32_e32 v223, v229, v223
	v_mul_f32_e32 v203, v226, v203
	global_store_dwordx4 v[152:153], v[144:147], off offset:-4096
	v_add_co_u32_e32 v148, vcc, s62, v172
	s_nop 0
	v_cvt_pk_bf16_f32 v144, v192, v200
	v_cvt_pk_bf16_f32 v145, v204, v196
	v_cvt_pk_bf16_f32 v146, v219, v224
	v_cvt_pk_bf16_f32 v147, v171, v214
	global_store_dwordx4 v[154:155], v[144:147], off
	v_mul_f32_e32 v209, v239, v209
	v_mul_f32_e32 v215, v236, v215
	v_cvt_pk_bf16_f32 v144, v190, v201
	v_cvt_pk_bf16_f32 v145, v203, v195
	v_cvt_pk_bf16_f32 v146, v218, v223
	v_cvt_pk_bf16_f32 v147, v170, v213
	global_store_dwordx4 v[152:153], v[144:147], off
	v_mul_f32_e32 v220, v233, v220
	v_mul_f32_e32 v225, v230, v225
	v_cvt_pk_bf16_f32 v144, v194, v206
	v_cvt_pk_bf16_f32 v145, v151, v149
	v_cvt_pk_bf16_f32 v146, v159, v157
	v_cvt_pk_bf16_f32 v147, v167, v165
	v_addc_co_u32_e32 v149, vcc, 0, v173, vcc
	v_mul_f32_e32 v205, v227, v205
	global_store_dwordx4 v[148:149], v[144:147], off
	v_add_co_u32_e32 v148, vcc, s62, v182
	s_nop 0
	v_cvt_pk_bf16_f32 v144, v187, v207
	v_cvt_pk_bf16_f32 v145, v205, v197
	v_cvt_pk_bf16_f32 v146, v220, v225
	v_cvt_pk_bf16_f32 v147, v209, v215
	v_addc_co_u32_e32 v149, vcc, 0, v183, vcc
	global_store_dwordx4 v[148:149], v[144:147], off
	v_mov_b32_e32 v182, v242
	s_lshl_b64 s[26:27], s[66:67], 4
	v_mul_f32_e32 v145, 0xbfb8aa3b, v56
	v_exp_f32_e32 v145, v145
	s_add_u32 s3, s26, s3
	s_addc_u32 s14, s27, 0
	s_add_u32 s66, s3, 32
	v_add_f32_e32 v145, 1.0, v145
	v_rcp_f32_e32 v145, v145
	s_addc_u32 s67, s14, 0
	s_mul_i32 s3, s67, 0x600
	s_mul_hi_u32 s14, s66, 0x600
	s_add_i32 s3, s14, s3
	s_mul_i32 s14, s66, 0x600
	v_sub_f32_e32 v144, 1.0, v182
	v_fma_f32 v183, v145, v144, v182
	v_log_f32_e32 v145, v183
	s_nop 0
	v_mul_f32_e32 v146, 0x3f317218, v145
	s_nop 1
	v_mov_b32_dpp v146, v146 row_shr:1 row_mask:0xf bank_mask:0xf bound_ctrl:1
	v_fmac_f32_e32 v146, 0x3f317218, v145
	s_nop 1
	v_add_f32_dpp v145, v146, v146 row_shr:2 row_mask:0xf bank_mask:0xf bound_ctrl:1
	s_nop 1
	v_add_f32_dpp v145, v145, v145 row_shr:4 row_mask:0xf bank_mask:0xf bound_ctrl:1
	s_nop 1
	v_add_f32_dpp v184, v145, v145 row_shr:8 row_mask:0xf bank_mask:0xf bound_ctrl:1
	v_mul_f32_e32 v145, 0xbfb8aa3b, v40
	v_exp_f32_e32 v145, v145
	ds_bpermute_b32 v151, v135, v184
	v_add_f32_e32 v145, 1.0, v145
	v_rcp_f32_e32 v145, v145
	s_nop 0
	v_fma_f32 v185, v145, v144, v182
	v_log_f32_e32 v145, v185
	s_nop 0
	v_mul_f32_e32 v146, 0x3f317218, v145
	s_nop 1
	v_mov_b32_dpp v146, v146 row_shr:1 row_mask:0xf bank_mask:0xf bound_ctrl:1
	v_fmac_f32_e32 v146, 0x3f317218, v145
	s_nop 1
	v_add_f32_dpp v145, v146, v146 row_shr:2 row_mask:0xf bank_mask:0xf bound_ctrl:1
	s_nop 1
	v_add_f32_dpp v145, v145, v145 row_shr:4 row_mask:0xf bank_mask:0xf bound_ctrl:1
	s_nop 1
	v_add_f32_dpp v186, v145, v145 row_shr:8 row_mask:0xf bank_mask:0xf bound_ctrl:1
	v_mul_f32_e32 v145, 0xbfb8aa3b, v24
	v_exp_f32_e32 v145, v145
	s_nop 0
	v_add_f32_e32 v145, 1.0, v145
	v_rcp_f32_e32 v145, v145
	s_nop 0
	v_fma_f32 v190, v145, v144, v182
	v_log_f32_e32 v145, v190
	s_nop 0
	v_mul_f32_e32 v146, 0x3f317218, v145
	s_nop 1
	v_mov_b32_dpp v146, v146 row_shr:1 row_mask:0xf bank_mask:0xf bound_ctrl:1
	v_fmac_f32_e32 v146, 0x3f317218, v145
	s_nop 1
	v_add_f32_dpp v145, v146, v146 row_shr:2 row_mask:0xf bank_mask:0xf bound_ctrl:1
	s_nop 1
	v_add_f32_dpp v145, v145, v145 row_shr:4 row_mask:0xf bank_mask:0xf bound_ctrl:1
	s_nop 1
	v_add_f32_dpp v192, v145, v145 row_shr:8 row_mask:0xf bank_mask:0xf bound_ctrl:1
	v_mul_f32_e32 v145, 0xbfb8aa3b, v8
	v_exp_f32_e32 v145, v145
	ds_bpermute_b32 v148, v135, v192
	v_add_f32_e32 v145, 1.0, v145
	v_rcp_f32_e32 v145, v145
	s_nop 0
	v_fmac_f32_e32 v182, v145, v144
	v_log_f32_e32 v144, v182
	s_nop 0
	v_mul_f32_e32 v145, 0x3f317218, v144
	s_nop 1
	v_mov_b32_dpp v145, v145 row_shr:1 row_mask:0xf bank_mask:0xf bound_ctrl:1
	v_fmac_f32_e32 v145, 0x3f317218, v144
	s_nop 1
	v_add_f32_dpp v144, v145, v145 row_shr:2 row_mask:0xf bank_mask:0xf bound_ctrl:1
	ds_bpermute_b32 v145, v135, v186
	s_nop 0
	v_add_f32_dpp v150, v144, v144 row_shr:4 row_mask:0xf bank_mask:0xf bound_ctrl:1
	s_nop 1
	v_mov_b32_dpp v144, v150 row_shr:8 row_mask:0xf bank_mask:0xf bound_ctrl:1
	s_waitcnt lgkmcnt(0)
	v_pk_add_f32 v[146:147], v[150:151], v[144:145]
	ds_bpermute_b32 v144, v135, v146
	v_add_f32_e32 v195, v147, v148
	s_and_saveexec_b64 s[68:69], s[4:5]
	s_cbranch_execz .LBB0_163
	s_waitcnt lgkmcnt(0)
	v_add_f32_e32 v144, v195, v144
	v_mul_f32_e32 v145, 0x3fb8aa3b, v147
	v_readlane_b32 s26, v252, 20
	v_exp_f32_e32 v148, v145
	v_mul_f32_e32 v145, 0x3fb8aa3b, v144
	v_sub_f32_e32 v144, v144, v147
	s_add_u32 s26, s26, s14
	v_readlane_b32 s27, v252, 21
	v_exp_f32_e32 v149, v145
	v_mul_f32_e32 v144, 0x3fb8aa3b, v144
	s_addc_u32 s27, s27, s3
	v_exp_f32_e32 v150, v144
	v_lshl_add_u64 v[144:145], v[136:137], 2, s[26:27]
	global_store_dword v[144:145], v148, off
	global_store_dword v[144:145], v149, off offset:512
	global_store_dword v[144:145], v150, off offset:1024
; __device__ __forceinline__ float fexp(float x) { return __builtin_amdgcn_exp2f(x * 1.44269504089f); }
; __device__ __forceinline__ float fsigmoid(float x) { return __builtin_amdgcn_rcpf(1.0f + fexp(-x)); }
; __device__ __forceinline__ float row16_scan(float t) { t += dpp0<0x111>(t); t += dpp0<0x112>(t); t += dpp0<0x114>(t); t += dpp0<0x118>(t); return t; }
;     __device__ __forceinline__ void operator()(f32x4 (&acc)[2][2][4][2], const pg8::Unit& u, int wr, int wc, int fr, int fq) const {
;     ...
;                     for (int j = 0; j < 4; ++j) {
;                         const float lbv = lbp[4 * n + j];
;                         float cc[4];
; #pragma unroll
;                         for (int m = 0; m < 4; ++m) { const float s = fsigmoid(acc[ai][1][m][n][j]); const float f = lbv + (1.0f - lbv) * s;
;                             acc[ai][1][m][n][j] = 1.0f - f; cc[m] = row16_scan(__builtin_amdgcn_logf(f) * 0.69314718056f); }
;                         const float t0 = __shfl(cc[0], src15), t1 = __shfl(cc[1], src15), t2 = __shfl(cc[2], src15), t3 = __shfl(cc[3], src15);
;                         const float cmid = t0 + t1, clast = cmid + t2 + t3;
;                         cc[1] += t0; cc[2] += cmid; cc[3] += cmid + t2;
; #pragma unroll
;                         for (int m = 0; m < 4; ++m) { const float x = cc[m] - cmid; const float qv = acc[ai][0][m][n][j];
;                             acc[ai][0][m][n][j] = qv * fsigmoid(qv) * fexp(x); acc[ai][1][m][n][j] *= fexp(-x); }
;                         if (fr == 0) { float* sp = (float*)(ws + WS_SCL) + cb * 384 + c8 + 4 * n + j; sp[0] = fexp(cmid); sp[128] = fexp(clast); sp[256] = fexp(clast - cmid); }
.LBB0_163:
	s_or_b64 exec, exec, s[68:69]
	v_mov_b32_e32 v150, v243
	s_waitcnt lgkmcnt(0)
	v_mul_f32_e32 v144, 0xbfb8aa3b, v57
	v_mul_f32_e32 v145, 0xbfb8aa3b, v41
	v_exp_f32_e32 v144, v144
	v_exp_f32_e32 v145, v145
	v_mul_f32_e32 v148, 0xbfb8aa3b, v25
	v_mul_f32_e32 v149, 0xbfb8aa3b, v9
	v_exp_f32_e32 v148, v148
	v_exp_f32_e32 v149, v149
	v_add_f32_e32 v144, 1.0, v144
	v_add_f32_e32 v145, 1.0, v145
	v_rcp_f32_e32 v144, v144
	v_rcp_f32_e32 v145, v145
	v_add_f32_e32 v148, 1.0, v148
	v_add_f32_e32 v149, 1.0, v149
	v_rcp_f32_e32 v148, v148
	v_rcp_f32_e32 v149, v149
	v_sub_f32_e32 v152, 1.0, v150
	v_fma_f32 v187, v144, v152, v150
	v_fma_f32 v188, v145, v152, v150
	v_log_f32_e32 v144, v187
	v_log_f32_e32 v145, v188
	v_fma_f32 v189, v148, v152, v150
	v_fmac_f32_e32 v150, v149, v152
	v_log_f32_e32 v148, v189
	v_log_f32_e32 v149, v150
	v_mul_f32_e32 v152, 0x3f317218, v144
	v_mul_f32_e32 v153, 0x3f317218, v145
	v_mul_f32_e32 v154, 0x3f317218, v148
	v_mov_b32_dpp v152, v152 row_shr:1 row_mask:0xf bank_mask:0xf bound_ctrl:1
	v_mov_b32_dpp v153, v153 row_shr:1 row_mask:0xf bank_mask:0xf bound_ctrl:1
	v_fmac_f32_e32 v152, 0x3f317218, v144
	v_fmac_f32_e32 v153, 0x3f317218, v145
	v_mul_f32_e32 v155, 0x3f317218, v149
	v_add_f32_dpp v144, v152, v152 row_shr:2 row_mask:0xf bank_mask:0xf bound_ctrl:1
	v_add_f32_dpp v145, v153, v153 row_shr:2 row_mask:0xf bank_mask:0xf bound_ctrl:1
	v_mov_b32_dpp v154, v154 row_shr:1 row_mask:0xf bank_mask:0xf bound_ctrl:1
	v_add_f32_dpp v144, v144, v144 row_shr:4 row_mask:0xf bank_mask:0xf bound_ctrl:1
	v_add_f32_dpp v145, v145, v145 row_shr:4 row_mask:0xf bank_mask:0xf bound_ctrl:1
	v_mov_b32_dpp v155, v155 row_shr:1 row_mask:0xf bank_mask:0xf bound_ctrl:1
	v_add_f32_dpp v191, v144, v144 row_shr:8 row_mask:0xf bank_mask:0xf bound_ctrl:1
	v_add_f32_dpp v193, v145, v145 row_shr:8 row_mask:0xf bank_mask:0xf bound_ctrl:1
	v_fmac_f32_e32 v154, 0x3f317218, v148
	v_fmac_f32_e32 v155, 0x3f317218, v149
	ds_bpermute_b32 v149, v135, v191
	ds_bpermute_b32 v145, v135, v193
	v_add_f32_dpp v148, v154, v154 row_shr:2 row_mask:0xf bank_mask:0xf bound_ctrl:1
	v_add_f32_dpp v144, v155, v155 row_shr:2 row_mask:0xf bank_mask:0xf bound_ctrl:1
	s_nop 0
	v_add_f32_dpp v148, v148, v148 row_shr:4 row_mask:0xf bank_mask:0xf bound_ctrl:1
	s_nop 1
	v_add_f32_dpp v194, v148, v148 row_shr:8 row_mask:0xf bank_mask:0xf bound_ctrl:1
	v_add_f32_dpp v148, v144, v144 row_shr:4 row_mask:0xf bank_mask:0xf bound_ctrl:1
	ds_bpermute_b32 v153, v135, v194
	s_nop 0
	v_mov_b32_dpp v144, v148 row_shr:8 row_mask:0xf bank_mask:0xf bound_ctrl:1
	s_waitcnt lgkmcnt(1)
	v_pk_add_f32 v[144:145], v[148:149], v[144:145]
	ds_bpermute_b32 v152, v135, v144
	s_waitcnt lgkmcnt(1)
	v_add_f32_e32 v148, v145, v153
	s_and_saveexec_b64 s[68:69], s[4:5]
	s_cbranch_execz .LBB0_165
	s_add_u32 s26, s30, s14
	v_mul_f32_e32 v155, 0x3fb8aa3b, v145
	s_addc_u32 s27, s31, s3
	v_exp_f32_e32 v155, v155
	s_waitcnt lgkmcnt(0)
	v_add_f32_e32 v154, v148, v152
	v_lshl_add_u64 v[152:153], v[136:137], 2, s[26:27]
	v_add_co_u32_e32 v152, vcc, 0x49300000, v152
	s_nop 1
	v_addc_co_u32_e32 v153, vcc, 0, v153, vcc
	global_store_dword v[152:153], v155, off offset:4
	v_mul_f32_e32 v155, 0x3fb8aa3b, v154
	v_sub_f32_e32 v154, v154, v145
	v_mul_f32_e32 v154, 0x3fb8aa3b, v154
	v_exp_f32_e32 v155, v155
	v_exp_f32_e32 v154, v154
	global_store_dword v[152:153], v155, off offset:516
	global_store_dword v[152:153], v154, off offset:1028
.LBB0_165:
	s_or_b64 exec, exec, s[68:69]
	v_mov_b32_e32 v200, v244
	s_waitcnt lgkmcnt(0)
	v_mul_f32_e32 v152, 0xbfb8aa3b, v58
	v_mul_f32_e32 v153, 0xbfb8aa3b, v42
	v_exp_f32_e32 v152, v152
	v_exp_f32_e32 v153, v153
	v_mul_f32_e32 v154, 0xbfb8aa3b, v26
	v_mul_f32_e32 v155, 0xbfb8aa3b, v10
	v_add_f32_e32 v152, 1.0, v152
	v_add_f32_e32 v153, 1.0, v153
	v_exp_f32_e32 v154, v154
	v_exp_f32_e32 v155, v155
	v_rcp_f32_e32 v152, v152
	v_rcp_f32_e32 v153, v153
	v_add_f32_e32 v154, 1.0, v154
	v_add_f32_e32 v155, 1.0, v155
	v_rcp_f32_e32 v154, v154
	v_rcp_f32_e32 v155, v155
	v_sub_f32_e32 v156, 1.0, v200
	v_fma_f32 v203, v152, v156, v200
	v_fma_f32 v204, v153, v156, v200
	v_log_f32_e32 v152, v203
	v_log_f32_e32 v153, v204
	v_fma_f32 v205, v154, v156, v200
	v_fmac_f32_e32 v200, v155, v156
	v_mul_f32_e32 v156, 0x3f317218, v152
	v_mul_f32_e32 v157, 0x3f317218, v153
	v_log_f32_e32 v154, v205
	v_log_f32_e32 v155, v200
	v_mov_b32_dpp v156, v156 row_shr:1 row_mask:0xf bank_mask:0xf bound_ctrl:1
	v_mov_b32_dpp v157, v157 row_shr:1 row_mask:0xf bank_mask:0xf bound_ctrl:1
	v_fmac_f32_e32 v156, 0x3f317218, v152
	v_fmac_f32_e32 v157, 0x3f317218, v153
	v_mul_f32_e32 v158, 0x3f317218, v154
	v_add_f32_dpp v152, v156, v156 row_shr:2 row_mask:0xf bank_mask:0xf bound_ctrl:1
	v_add_f32_dpp v153, v157, v157 row_shr:2 row_mask:0xf bank_mask:0xf bound_ctrl:1
	v_mul_f32_e32 v159, 0x3f317218, v155
	v_add_f32_dpp v152, v152, v152 row_shr:4 row_mask:0xf bank_mask:0xf bound_ctrl:1
	v_add_f32_dpp v153, v153, v153 row_shr:4 row_mask:0xf bank_mask:0xf bound_ctrl:1
	v_mov_b32_dpp v158, v158 row_shr:1 row_mask:0xf bank_mask:0xf bound_ctrl:1
	v_add_f32_dpp v206, v152, v152 row_shr:8 row_mask:0xf bank_mask:0xf bound_ctrl:1
	v_add_f32_dpp v207, v153, v153 row_shr:8 row_mask:0xf bank_mask:0xf bound_ctrl:1
	v_mov_b32_dpp v160, v159 row_shr:1 row_mask:0xf bank_mask:0xf bound_ctrl:1
	ds_bpermute_b32 v159, v135, v206
	ds_bpermute_b32 v153, v135, v207
	v_fmac_f32_e32 v158, 0x3f317218, v154
	v_fmac_f32_e32 v160, 0x3f317218, v155
	s_nop 0
	v_add_f32_dpp v154, v158, v158 row_shr:2 row_mask:0xf bank_mask:0xf bound_ctrl:1
	v_add_f32_dpp v152, v160, v160 row_shr:2 row_mask:0xf bank_mask:0xf bound_ctrl:1
	s_nop 0
	v_add_f32_dpp v154, v154, v154 row_shr:4 row_mask:0xf bank_mask:0xf bound_ctrl:1
	v_add_f32_dpp v158, v152, v152 row_shr:4 row_mask:0xf bank_mask:0xf bound_ctrl:1
	s_nop 0
	v_add_f32_dpp v208, v154, v154 row_shr:8 row_mask:0xf bank_mask:0xf bound_ctrl:1
	v_mov_b32_dpp v152, v158 row_shr:8 row_mask:0xf bank_mask:0xf bound_ctrl:1
	ds_bpermute_b32 v156, v135, v208
	s_waitcnt lgkmcnt(1)
	v_pk_add_f32 v[154:155], v[158:159], v[152:153]
	ds_bpermute_b32 v152, v135, v154
	s_waitcnt lgkmcnt(1)
	v_add_f32_e32 v209, v155, v156
	s_and_saveexec_b64 s[68:69], s[4:5]
	s_cbranch_execz .LBB0_167
	s_add_u32 s26, s30, s14
	v_mul_f32_e32 v157, 0x3fb8aa3b, v155
	s_addc_u32 s27, s31, s3
	v_exp_f32_e32 v157, v157
	s_waitcnt lgkmcnt(0)
	v_add_f32_e32 v156, v209, v152
	v_lshl_add_u64 v[152:153], v[136:137], 2, s[26:27]
	v_add_co_u32_e32 v152, vcc, 0x49300000, v152
	s_nop 1
	v_addc_co_u32_e32 v153, vcc, 0, v153, vcc
	global_store_dword v[152:153], v157, off offset:8
	v_mul_f32_e32 v157, 0x3fb8aa3b, v156
	v_sub_f32_e32 v156, v156, v155
	v_mul_f32_e32 v156, 0x3fb8aa3b, v156
	v_exp_f32_e32 v157, v157
	v_exp_f32_e32 v156, v156
	global_store_dword v[152:153], v157, off offset:520
	global_store_dword v[152:153], v156, off offset:1032
; __device__ __forceinline__ float fexp(float x) { return __builtin_amdgcn_exp2f(x * 1.44269504089f); }
; __device__ __forceinline__ float fsigmoid(float x) { return __builtin_amdgcn_rcpf(1.0f + fexp(-x)); }
; __device__ __forceinline__ float row16_scan(float t) { t += dpp0<0x111>(t); t += dpp0<0x112>(t); t += dpp0<0x114>(t); t += dpp0<0x118>(t); return t; }
;     __device__ __forceinline__ void operator()(f32x4 (&acc)[2][2][4][2], const pg8::Unit& u, int wr, int wc, int fr, int fq) const {
;     ...
;                     for (int j = 0; j < 4; ++j) {
;                         const float lbv = lbp[4 * n + j];
;                         float cc[4];
; #pragma unroll
;                         for (int m = 0; m < 4; ++m) { const float s = fsigmoid(acc[ai][1][m][n][j]); const float f = lbv + (1.0f - lbv) * s;
;                             acc[ai][1][m][n][j] = 1.0f - f; cc[m] = row16_scan(__builtin_amdgcn_logf(f) * 0.69314718056f); }
;                         const float t0 = __shfl(cc[0], src15), t1 = __shfl(cc[1], src15), t2 = __shfl(cc[2], src15), t3 = __shfl(cc[3], src15);
;                         const float cmid = t0 + t1, clast = cmid + t2 + t3;
;                         cc[1] += t0; cc[2] += cmid; cc[3] += cmid + t2;
; #pragma unroll
;                         for (int m = 0; m < 4; ++m) { const float x = cc[m] - cmid; const float qv = acc[ai][0][m][n][j];
;                             acc[ai][0][m][n][j] = qv * fsigmoid(qv) * fexp(x); acc[ai][1][m][n][j] *= fexp(-x); }
;                         if (fr == 0) { float* sp = (float*)(ws + WS_SCL) + cb * 384 + c8 + 4 * n + j; sp[0] = fexp(cmid); sp[128] = fexp(clast); sp[256] = fexp(clast - cmid); }
.LBB0_167:
	s_or_b64 exec, exec, s[68:69]
	v_mov_b32_e32 v158, v245
	s_waitcnt lgkmcnt(0)
	v_mul_f32_e32 v152, 0xbfb8aa3b, v59
	v_mul_f32_e32 v153, 0xbfb8aa3b, v43
	v_exp_f32_e32 v152, v152
	v_exp_f32_e32 v153, v153
	v_mul_f32_e32 v156, 0xbfb8aa3b, v27
	v_mul_f32_e32 v157, 0xbfb8aa3b, v11
	v_exp_f32_e32 v156, v156
	v_exp_f32_e32 v157, v157
	v_add_f32_e32 v152, 1.0, v152
	v_add_f32_e32 v153, 1.0, v153
	v_rcp_f32_e32 v152, v152
	v_rcp_f32_e32 v153, v153
	v_add_f32_e32 v156, 1.0, v156
	v_add_f32_e32 v157, 1.0, v157
	v_rcp_f32_e32 v156, v156
	v_rcp_f32_e32 v157, v157
	v_sub_f32_e32 v160, 1.0, v158
	v_fma_f32 v196, v152, v160, v158
	v_fma_f32 v197, v153, v160, v158
	v_log_f32_e32 v152, v196
	v_log_f32_e32 v153, v197
	v_fma_f32 v198, v156, v160, v158
	v_fmac_f32_e32 v158, v157, v160
	v_log_f32_e32 v156, v198
	v_log_f32_e32 v157, v158
	v_mul_f32_e32 v160, 0x3f317218, v152
	v_mul_f32_e32 v161, 0x3f317218, v153
	v_mul_f32_e32 v162, 0x3f317218, v156
	v_mov_b32_dpp v160, v160 row_shr:1 row_mask:0xf bank_mask:0xf bound_ctrl:1
	v_mov_b32_dpp v161, v161 row_shr:1 row_mask:0xf bank_mask:0xf bound_ctrl:1
	v_fmac_f32_e32 v160, 0x3f317218, v152
	v_fmac_f32_e32 v161, 0x3f317218, v153
	v_mul_f32_e32 v163, 0x3f317218, v157
	v_add_f32_dpp v152, v160, v160 row_shr:2 row_mask:0xf bank_mask:0xf bound_ctrl:1
	v_add_f32_dpp v153, v161, v161 row_shr:2 row_mask:0xf bank_mask:0xf bound_ctrl:1
	v_mov_b32_dpp v162, v162 row_shr:1 row_mask:0xf bank_mask:0xf bound_ctrl:1
	v_add_f32_dpp v152, v152, v152 row_shr:4 row_mask:0xf bank_mask:0xf bound_ctrl:1
	v_add_f32_dpp v153, v153, v153 row_shr:4 row_mask:0xf bank_mask:0xf bound_ctrl:1
	v_mov_b32_dpp v163, v163 row_shr:1 row_mask:0xf bank_mask:0xf bound_ctrl:1
	v_add_f32_dpp v199, v152, v152 row_shr:8 row_mask:0xf bank_mask:0xf bound_ctrl:1
	v_add_f32_dpp v201, v153, v153 row_shr:8 row_mask:0xf bank_mask:0xf bound_ctrl:1
	v_fmac_f32_e32 v162, 0x3f317218, v156
	v_fmac_f32_e32 v163, 0x3f317218, v157
	ds_bpermute_b32 v157, v135, v199
	ds_bpermute_b32 v153, v135, v201
	v_add_f32_dpp v156, v162, v162 row_shr:2 row_mask:0xf bank_mask:0xf bound_ctrl:1
	v_add_f32_dpp v152, v163, v163 row_shr:2 row_mask:0xf bank_mask:0xf bound_ctrl:1
	s_nop 0
	v_add_f32_dpp v156, v156, v156 row_shr:4 row_mask:0xf bank_mask:0xf bound_ctrl:1
	s_nop 1
	v_add_f32_dpp v202, v156, v156 row_shr:8 row_mask:0xf bank_mask:0xf bound_ctrl:1
	v_add_f32_dpp v156, v152, v152 row_shr:4 row_mask:0xf bank_mask:0xf bound_ctrl:1
	ds_bpermute_b32 v161, v135, v202
	s_nop 0
	v_mov_b32_dpp v152, v156 row_shr:8 row_mask:0xf bank_mask:0xf bound_ctrl:1
	s_waitcnt lgkmcnt(1)
	v_pk_add_f32 v[152:153], v[156:157], v[152:153]
	ds_bpermute_b32 v160, v135, v152
	s_waitcnt lgkmcnt(1)
	v_add_f32_e32 v156, v153, v161
	s_and_saveexec_b64 s[68:69], s[4:5]
	s_cbranch_execz .LBB0_169
	s_add_u32 s26, s30, s14
	v_mul_f32_e32 v163, 0x3fb8aa3b, v153
	s_addc_u32 s27, s31, s3
	v_exp_f32_e32 v163, v163
	s_waitcnt lgkmcnt(0)
	v_add_f32_e32 v162, v156, v160
	v_lshl_add_u64 v[160:161], v[136:137], 2, s[26:27]
	v_add_co_u32_e32 v160, vcc, 0x49300000, v160
	s_nop 1
	v_addc_co_u32_e32 v161, vcc, 0, v161, vcc
	global_store_dword v[160:161], v163, off offset:12
	v_mul_f32_e32 v163, 0x3fb8aa3b, v162
	v_sub_f32_e32 v162, v162, v153
	v_mul_f32_e32 v162, 0x3fb8aa3b, v162
	v_exp_f32_e32 v163, v163
	v_exp_f32_e32 v162, v162
	global_store_dword v[160:161], v163, off offset:524
	global_store_dword v[160:161], v162, off offset:1036
.LBB0_169:
	s_or_b64 exec, exec, s[68:69]
	v_mov_b32_e32 v215, v246
	s_waitcnt lgkmcnt(0)
	v_mul_f32_e32 v160, 0xbfb8aa3b, v48
	v_mul_f32_e32 v161, 0xbfb8aa3b, v32
	v_exp_f32_e32 v160, v160
	v_exp_f32_e32 v161, v161
	v_mul_f32_e32 v162, 0xbfb8aa3b, v16
	v_mul_f32_e32 v163, 0xbfb8aa3b, v0
	v_add_f32_e32 v160, 1.0, v160
	v_add_f32_e32 v161, 1.0, v161
	v_exp_f32_e32 v162, v162
	v_exp_f32_e32 v163, v163
	v_rcp_f32_e32 v160, v160
	v_rcp_f32_e32 v161, v161
	v_add_f32_e32 v162, 1.0, v162
	v_add_f32_e32 v163, 1.0, v163
	v_rcp_f32_e32 v162, v162
	v_rcp_f32_e32 v163, v163
	v_sub_f32_e32 v164, 1.0, v215
	v_fma_f32 v216, v160, v164, v215
	v_fma_f32 v217, v161, v164, v215
	v_log_f32_e32 v160, v216
	v_log_f32_e32 v161, v217
	v_fma_f32 v218, v162, v164, v215
	v_fmac_f32_e32 v215, v163, v164
	v_mul_f32_e32 v164, 0x3f317218, v160
	v_mul_f32_e32 v165, 0x3f317218, v161
	v_log_f32_e32 v162, v218
	v_log_f32_e32 v163, v215
	v_mov_b32_dpp v164, v164 row_shr:1 row_mask:0xf bank_mask:0xf bound_ctrl:1
	v_mov_b32_dpp v165, v165 row_shr:1 row_mask:0xf bank_mask:0xf bound_ctrl:1
	v_fmac_f32_e32 v164, 0x3f317218, v160
	v_fmac_f32_e32 v165, 0x3f317218, v161
	v_mul_f32_e32 v166, 0x3f317218, v162
	v_add_f32_dpp v160, v164, v164 row_shr:2 row_mask:0xf bank_mask:0xf bound_ctrl:1
	v_add_f32_dpp v161, v165, v165 row_shr:2 row_mask:0xf bank_mask:0xf bound_ctrl:1
	v_mul_f32_e32 v167, 0x3f317218, v163
	v_add_f32_dpp v160, v160, v160 row_shr:4 row_mask:0xf bank_mask:0xf bound_ctrl:1
	v_add_f32_dpp v161, v161, v161 row_shr:4 row_mask:0xf bank_mask:0xf bound_ctrl:1
	v_mov_b32_dpp v166, v166 row_shr:1 row_mask:0xf bank_mask:0xf bound_ctrl:1
	v_add_f32_dpp v219, v160, v160 row_shr:8 row_mask:0xf bank_mask:0xf bound_ctrl:1
	v_add_f32_dpp v228, v161, v161 row_shr:8 row_mask:0xf bank_mask:0xf bound_ctrl:1
	v_mov_b32_dpp v168, v167 row_shr:1 row_mask:0xf bank_mask:0xf bound_ctrl:1
	ds_bpermute_b32 v167, v135, v219
	ds_bpermute_b32 v161, v135, v228
	v_fmac_f32_e32 v166, 0x3f317218, v162
	v_fmac_f32_e32 v168, 0x3f317218, v163
	s_nop 0
	v_add_f32_dpp v162, v166, v166 row_shr:2 row_mask:0xf bank_mask:0xf bound_ctrl:1
	v_add_f32_dpp v160, v168, v168 row_shr:2 row_mask:0xf bank_mask:0xf bound_ctrl:1
	s_nop 0
	v_add_f32_dpp v162, v162, v162 row_shr:4 row_mask:0xf bank_mask:0xf bound_ctrl:1
	v_add_f32_dpp v166, v160, v160 row_shr:4 row_mask:0xf bank_mask:0xf bound_ctrl:1
	s_nop 0
	v_add_f32_dpp v229, v162, v162 row_shr:8 row_mask:0xf bank_mask:0xf bound_ctrl:1
	v_mov_b32_dpp v160, v166 row_shr:8 row_mask:0xf bank_mask:0xf bound_ctrl:1
	ds_bpermute_b32 v164, v135, v229
	s_waitcnt lgkmcnt(1)
	v_pk_add_f32 v[162:163], v[166:167], v[160:161]
	ds_bpermute_b32 v160, v135, v162
	s_waitcnt lgkmcnt(1)
	v_add_f32_e32 v230, v163, v164
	s_and_saveexec_b64 s[68:69], s[4:5]
	s_cbranch_execz .LBB0_171
	s_add_u32 s26, s30, s14
	v_mul_f32_e32 v165, 0x3fb8aa3b, v163
	s_addc_u32 s27, s31, s3
	v_exp_f32_e32 v165, v165
	s_waitcnt lgkmcnt(0)
	v_add_f32_e32 v164, v230, v160
	v_lshl_add_u64 v[160:161], v[136:137], 2, s[26:27]
	v_add_co_u32_e32 v160, vcc, 0x49300000, v160
	s_nop 1
	v_addc_co_u32_e32 v161, vcc, 0, v161, vcc
	global_store_dword v[160:161], v165, off offset:16
	v_mul_f32_e32 v165, 0x3fb8aa3b, v164
	v_sub_f32_e32 v164, v164, v163
	v_mul_f32_e32 v164, 0x3fb8aa3b, v164
	v_exp_f32_e32 v165, v165
	v_exp_f32_e32 v164, v164
	global_store_dword v[160:161], v165, off offset:528
	global_store_dword v[160:161], v164, off offset:1040
; __device__ __forceinline__ float fexp(float x) { return __builtin_amdgcn_exp2f(x * 1.44269504089f); }
; __device__ __forceinline__ float fsigmoid(float x) { return __builtin_amdgcn_rcpf(1.0f + fexp(-x)); }
; __device__ __forceinline__ float row16_scan(float t) { t += dpp0<0x111>(t); t += dpp0<0x112>(t); t += dpp0<0x114>(t); t += dpp0<0x118>(t); return t; }
;     __device__ __forceinline__ void operator()(f32x4 (&acc)[2][2][4][2], const pg8::Unit& u, int wr, int wc, int fr, int fq) const {
;     ...
;                     for (int j = 0; j < 4; ++j) {
;                         const float lbv = lbp[4 * n + j];
;                         float cc[4];
; #pragma unroll
;                         for (int m = 0; m < 4; ++m) { const float s = fsigmoid(acc[ai][1][m][n][j]); const float f = lbv + (1.0f - lbv) * s;
;                             acc[ai][1][m][n][j] = 1.0f - f; cc[m] = row16_scan(__builtin_amdgcn_logf(f) * 0.69314718056f); }
;                         const float t0 = __shfl(cc[0], src15), t1 = __shfl(cc[1], src15), t2 = __shfl(cc[2], src15), t3 = __shfl(cc[3], src15);
;                         const float cmid = t0 + t1, clast = cmid + t2 + t3;
;                         cc[1] += t0; cc[2] += cmid; cc[3] += cmid + t2;
; #pragma unroll
;                         for (int m = 0; m < 4; ++m) { const float x = cc[m] - cmid; const float qv = acc[ai][0][m][n][j];
;                             acc[ai][0][m][n][j] = qv * fsigmoid(qv) * fexp(x); acc[ai][1][m][n][j] *= fexp(-x); }
;                         if (fr == 0) { float* sp = (float*)(ws + WS_SCL) + cb * 384 + c8 + 4 * n + j; sp[0] = fexp(cmid); sp[128] = fexp(clast); sp[256] = fexp(clast - cmid); }
.LBB0_171:
	s_or_b64 exec, exec, s[68:69]
	v_mov_b32_e32 v220, v247
	s_waitcnt lgkmcnt(0)
	v_mul_f32_e32 v160, 0xbfb8aa3b, v49
	v_mul_f32_e32 v161, 0xbfb8aa3b, v33
	v_exp_f32_e32 v160, v160
	v_exp_f32_e32 v161, v161
	v_mul_f32_e32 v164, 0xbfb8aa3b, v17
	v_mul_f32_e32 v165, 0xbfb8aa3b, v1
	v_exp_f32_e32 v164, v164
	v_exp_f32_e32 v165, v165
	v_add_f32_e32 v160, 1.0, v160
	v_add_f32_e32 v161, 1.0, v161
	v_rcp_f32_e32 v160, v160
	v_rcp_f32_e32 v161, v161
	v_add_f32_e32 v164, 1.0, v164
	v_add_f32_e32 v165, 1.0, v165
	v_rcp_f32_e32 v164, v164
	v_rcp_f32_e32 v165, v165
	v_sub_f32_e32 v166, 1.0, v220
	v_fma_f32 v221, v160, v166, v220
	v_fma_f32 v222, v161, v166, v220
	v_log_f32_e32 v160, v221
	v_log_f32_e32 v161, v222
	v_fma_f32 v223, v164, v166, v220
	v_fmac_f32_e32 v220, v165, v166
	v_log_f32_e32 v164, v223
	v_log_f32_e32 v165, v220
	v_mul_f32_e32 v166, 0x3f317218, v160
	v_mul_f32_e32 v168, 0x3f317218, v161
	v_mul_f32_e32 v169, 0x3f317218, v164
	v_mov_b32_dpp v166, v166 row_shr:1 row_mask:0xf bank_mask:0xf bound_ctrl:1
	v_mov_b32_dpp v168, v168 row_shr:1 row_mask:0xf bank_mask:0xf bound_ctrl:1
	v_fmac_f32_e32 v166, 0x3f317218, v160
	v_fmac_f32_e32 v168, 0x3f317218, v161
	v_mul_f32_e32 v170, 0x3f317218, v165
	v_add_f32_dpp v160, v166, v166 row_shr:2 row_mask:0xf bank_mask:0xf bound_ctrl:1
	v_add_f32_dpp v161, v168, v168 row_shr:2 row_mask:0xf bank_mask:0xf bound_ctrl:1
	v_mov_b32_dpp v169, v169 row_shr:1 row_mask:0xf bank_mask:0xf bound_ctrl:1
	v_add_f32_dpp v160, v160, v160 row_shr:4 row_mask:0xf bank_mask:0xf bound_ctrl:1
	v_add_f32_dpp v161, v161, v161 row_shr:4 row_mask:0xf bank_mask:0xf bound_ctrl:1
	v_mov_b32_dpp v170, v170 row_shr:1 row_mask:0xf bank_mask:0xf bound_ctrl:1
	v_add_f32_dpp v224, v160, v160 row_shr:8 row_mask:0xf bank_mask:0xf bound_ctrl:1
	v_add_f32_dpp v225, v161, v161 row_shr:8 row_mask:0xf bank_mask:0xf bound_ctrl:1
	v_fmac_f32_e32 v169, 0x3f317218, v164
	v_fmac_f32_e32 v170, 0x3f317218, v165
	ds_bpermute_b32 v165, v135, v224
	ds_bpermute_b32 v161, v135, v225
	v_add_f32_dpp v164, v169, v169 row_shr:2 row_mask:0xf bank_mask:0xf bound_ctrl:1
	v_add_f32_dpp v160, v170, v170 row_shr:2 row_mask:0xf bank_mask:0xf bound_ctrl:1
	s_nop 0
	v_add_f32_dpp v164, v164, v164 row_shr:4 row_mask:0xf bank_mask:0xf bound_ctrl:1
	s_nop 1
	v_add_f32_dpp v226, v164, v164 row_shr:8 row_mask:0xf bank_mask:0xf bound_ctrl:1
	v_add_f32_dpp v164, v160, v160 row_shr:4 row_mask:0xf bank_mask:0xf bound_ctrl:1
	ds_bpermute_b32 v166, v135, v226
	s_nop 0
	v_mov_b32_dpp v160, v164 row_shr:8 row_mask:0xf bank_mask:0xf bound_ctrl:1
	s_waitcnt lgkmcnt(1)
	v_pk_add_f32 v[160:161], v[164:165], v[160:161]
	ds_bpermute_b32 v164, v135, v160
	s_waitcnt lgkmcnt(1)
	v_add_f32_e32 v227, v161, v166
	s_and_saveexec_b64 s[68:69], s[4:5]
	s_cbranch_execz .LBB0_173
	s_add_u32 s26, s30, s14
	v_mul_f32_e32 v166, 0x3fb8aa3b, v161
	s_addc_u32 s27, s31, s3
	v_exp_f32_e32 v166, v166
	v_lshl_add_u64 v[168:169], v[136:137], 2, s[26:27]
	v_add_co_u32_e32 v168, vcc, 0x49300000, v168
	s_waitcnt lgkmcnt(0)
	v_add_f32_e32 v164, v227, v164
	v_addc_co_u32_e32 v169, vcc, 0, v169, vcc
	global_store_dword v[168:169], v166, off offset:20
	v_mul_f32_e32 v166, 0x3fb8aa3b, v164
	v_sub_f32_e32 v164, v164, v161
	v_mul_f32_e32 v164, 0x3fb8aa3b, v164
	v_exp_f32_e32 v166, v166
	v_exp_f32_e32 v164, v164
	global_store_dword v[168:169], v166, off offset:532
	global_store_dword v[168:169], v164, off offset:1044
; __device__ __forceinline__ float fexp(float x) { return __builtin_amdgcn_exp2f(x * 1.44269504089f); }
; __device__ __forceinline__ float fsigmoid(float x) { return __builtin_amdgcn_rcpf(1.0f + fexp(-x)); }
; __device__ __forceinline__ float row16_scan(float t) { t += dpp0<0x111>(t); t += dpp0<0x112>(t); t += dpp0<0x114>(t); t += dpp0<0x118>(t); return t; }
;     __device__ __forceinline__ void operator()(f32x4 (&acc)[2][2][4][2], const pg8::Unit& u, int wr, int wc, int fr, int fq) const {
;     ...
;                     for (int j = 0; j < 4; ++j) {
;                         const float lbv = lbp[4 * n + j];
;                         float cc[4];
; #pragma unroll
;                         for (int m = 0; m < 4; ++m) { const float s = fsigmoid(acc[ai][1][m][n][j]); const float f = lbv + (1.0f - lbv) * s;
;                             acc[ai][1][m][n][j] = 1.0f - f; cc[m] = row16_scan(__builtin_amdgcn_logf(f) * 0.69314718056f); }
;                         const float t0 = __shfl(cc[0], src15), t1 = __shfl(cc[1], src15), t2 = __shfl(cc[2], src15), t3 = __shfl(cc[3], src15);
;                         const float cmid = t0 + t1, clast = cmid + t2 + t3;
;                         cc[1] += t0; cc[2] += cmid; cc[3] += cmid + t2;
; #pragma unroll
;                         for (int m = 0; m < 4; ++m) { const float x = cc[m] - cmid; const float qv = acc[ai][0][m][n][j];
;                             acc[ai][0][m][n][j] = qv * fsigmoid(qv) * fexp(x); acc[ai][1][m][n][j] *= fexp(-x); }
;                         if (fr == 0) { float* sp = (float*)(ws + WS_SCL) + cb * 384 + c8 + 4 * n + j; sp[0] = fexp(cmid); sp[128] = fexp(clast); sp[256] = fexp(clast - cmid); }
.LBB0_173:
	s_or_b64 exec, exec, s[68:69]
	s_waitcnt lgkmcnt(0)
	v_mov_b32_e32 v164, v248
	v_mul_f32_e32 v166, 0xbfb8aa3b, v50
	v_mul_f32_e32 v168, 0xbfb8aa3b, v34
	v_mul_f32_e32 v169, 0xbfb8aa3b, v18
	v_exp_f32_e32 v166, v166
	v_exp_f32_e32 v168, v168
	v_exp_f32_e32 v169, v169
	v_mul_f32_e32 v170, 0xbfb8aa3b, v2
	v_add_f32_e32 v166, 1.0, v166
	v_add_f32_e32 v168, 1.0, v168
	v_exp_f32_e32 v170, v170
	v_add_f32_e32 v169, 1.0, v169
	v_rcp_f32_e32 v166, v166
	v_rcp_f32_e32 v168, v168
	v_rcp_f32_e32 v169, v169
	v_add_f32_e32 v170, 1.0, v170
	v_rcp_f32_e32 v170, v170
	v_sub_f32_e32 v171, 1.0, v164
	v_fma_f32 v166, v166, v171, v164
	v_fma_f32 v235, v168, v171, v164
	v_fma_f32 v236, v169, v171, v164
	v_log_f32_e32 v168, v166
	v_log_f32_e32 v169, v235
	v_fmac_f32_e32 v164, v170, v171
	v_log_f32_e32 v170, v236
	v_mul_f32_e32 v172, 0x3f317218, v168
	v_mul_f32_e32 v173, 0x3f317218, v169
	v_log_f32_e32 v171, v164
	v_mov_b32_dpp v172, v172 row_shr:1 row_mask:0xf bank_mask:0xf bound_ctrl:1
	v_mov_b32_dpp v173, v173 row_shr:1 row_mask:0xf bank_mask:0xf bound_ctrl:1
	v_fmac_f32_e32 v172, 0x3f317218, v168
	v_fmac_f32_e32 v173, 0x3f317218, v169
	v_mul_f32_e32 v211, 0x3f317218, v170
	v_add_f32_dpp v168, v172, v172 row_shr:2 row_mask:0xf bank_mask:0xf bound_ctrl:1
	v_add_f32_dpp v169, v173, v173 row_shr:2 row_mask:0xf bank_mask:0xf bound_ctrl:1
	v_mul_f32_e32 v212, 0x3f317218, v171
	v_add_f32_dpp v168, v168, v168 row_shr:4 row_mask:0xf bank_mask:0xf bound_ctrl:1
	v_add_f32_dpp v169, v169, v169 row_shr:4 row_mask:0xf bank_mask:0xf bound_ctrl:1
	v_mov_b32_dpp v211, v211 row_shr:1 row_mask:0xf bank_mask:0xf bound_ctrl:1
	v_add_f32_dpp v237, v168, v168 row_shr:8 row_mask:0xf bank_mask:0xf bound_ctrl:1
	v_add_f32_dpp v238, v169, v169 row_shr:8 row_mask:0xf bank_mask:0xf bound_ctrl:1
	v_mov_b32_dpp v212, v212 row_shr:1 row_mask:0xf bank_mask:0xf bound_ctrl:1
	ds_bpermute_b32 v173, v135, v237
	ds_bpermute_b32 v169, v135, v238
	v_fmac_f32_e32 v211, 0x3f317218, v170
	v_fmac_f32_e32 v212, 0x3f317218, v171
	s_nop 0
	v_add_f32_dpp v170, v211, v211 row_shr:2 row_mask:0xf bank_mask:0xf bound_ctrl:1
	v_add_f32_dpp v168, v212, v212 row_shr:2 row_mask:0xf bank_mask:0xf bound_ctrl:1
	s_nop 0
	v_add_f32_dpp v170, v170, v170 row_shr:4 row_mask:0xf bank_mask:0xf bound_ctrl:1
	v_add_f32_dpp v172, v168, v168 row_shr:4 row_mask:0xf bank_mask:0xf bound_ctrl:1
	s_nop 0
	v_add_f32_dpp v239, v170, v170 row_shr:8 row_mask:0xf bank_mask:0xf bound_ctrl:1
	v_mov_b32_dpp v168, v172 row_shr:8 row_mask:0xf bank_mask:0xf bound_ctrl:1
	ds_bpermute_b32 v171, v135, v239
	s_waitcnt lgkmcnt(1)
	v_pk_add_f32 v[168:169], v[172:173], v[168:169]
	ds_bpermute_b32 v170, v135, v168
	s_waitcnt lgkmcnt(1)
	v_add_f32_e32 v172, v169, v171
	s_and_saveexec_b64 s[68:69], s[4:5]
	s_cbranch_execz .LBB0_175
	s_add_u32 s26, s30, s14
	v_mul_f32_e32 v212, 0x3fb8aa3b, v169
	s_addc_u32 s27, s31, s3
	v_exp_f32_e32 v212, v212
	s_waitcnt lgkmcnt(0)
	v_add_f32_e32 v211, v172, v170
	v_lshl_add_u64 v[170:171], v[136:137], 2, s[26:27]
	v_add_co_u32_e32 v170, vcc, 0x49300000, v170
	s_nop 1
	v_addc_co_u32_e32 v171, vcc, 0, v171, vcc
	global_store_dword v[170:171], v212, off offset:24
	v_mul_f32_e32 v212, 0x3fb8aa3b, v211
	v_sub_f32_e32 v211, v211, v169
	v_mul_f32_e32 v211, 0x3fb8aa3b, v211
	v_exp_f32_e32 v212, v212
	v_exp_f32_e32 v211, v211
	global_store_dword v[170:171], v212, off offset:536
	global_store_dword v[170:171], v211, off offset:1048
.LBB0_175:
	s_or_b64 exec, exec, s[68:69]
	v_mov_b32_e32 v211, v249
	v_mul_f32_e32 v138, 0xbfb8aa3b, v51
	v_mul_f32_e32 v139, 0xbfb8aa3b, v35
	v_exp_f32_e32 v138, v138
	v_exp_f32_e32 v139, v139
	s_waitcnt lgkmcnt(0)
	v_mul_f32_e32 v170, 0xbfb8aa3b, v19
	v_mul_f32_e32 v171, 0xbfb8aa3b, v3
	v_exp_f32_e32 v170, v170
	v_exp_f32_e32 v171, v171
	v_add_f32_e32 v138, 1.0, v138
	v_add_f32_e32 v139, 1.0, v139
	v_rcp_f32_e32 v138, v138
	v_rcp_f32_e32 v139, v139
	v_add_f32_e32 v170, 1.0, v170
	v_add_f32_e32 v171, 1.0, v171
	v_rcp_f32_e32 v170, v170
	v_rcp_f32_e32 v171, v171
	v_sub_f32_e32 v231, 1.0, v211
	v_fma_f32 v212, v138, v231, v211
	v_fma_f32 v213, v139, v231, v211
	v_log_f32_e32 v138, v212
	v_log_f32_e32 v139, v213
	v_fma_f32 v214, v170, v231, v211
	v_fmac_f32_e32 v211, v171, v231
	v_log_f32_e32 v170, v214
	v_log_f32_e32 v171, v211
	v_mul_f32_e32 v231, 0x3f317218, v138
	v_mul_f32_e32 v232, 0x3f317218, v139
	v_mul_f32_e32 v233, 0x3f317218, v170
	v_mov_b32_dpp v231, v231 row_shr:1 row_mask:0xf bank_mask:0xf bound_ctrl:1
	v_mov_b32_dpp v232, v232 row_shr:1 row_mask:0xf bank_mask:0xf bound_ctrl:1
	v_fmac_f32_e32 v231, 0x3f317218, v138
	v_fmac_f32_e32 v232, 0x3f317218, v139
	v_mul_f32_e32 v234, 0x3f317218, v171
	v_add_f32_dpp v138, v231, v231 row_shr:2 row_mask:0xf bank_mask:0xf bound_ctrl:1
	v_add_f32_dpp v139, v232, v232 row_shr:2 row_mask:0xf bank_mask:0xf bound_ctrl:1
	v_mov_b32_dpp v233, v233 row_shr:1 row_mask:0xf bank_mask:0xf bound_ctrl:1
	v_add_f32_dpp v138, v138, v138 row_shr:4 row_mask:0xf bank_mask:0xf bound_ctrl:1
	v_add_f32_dpp v139, v139, v139 row_shr:4 row_mask:0xf bank_mask:0xf bound_ctrl:1
	v_mov_b32_dpp v234, v234 row_shr:1 row_mask:0xf bank_mask:0xf bound_ctrl:1
	v_add_f32_dpp v231, v138, v138 row_shr:8 row_mask:0xf bank_mask:0xf bound_ctrl:1
	v_add_f32_dpp v232, v139, v139 row_shr:8 row_mask:0xf bank_mask:0xf bound_ctrl:1
	v_fmac_f32_e32 v233, 0x3f317218, v170
	v_fmac_f32_e32 v234, 0x3f317218, v171
	ds_bpermute_b32 v171, v135, v231
	ds_bpermute_b32 v139, v135, v232
	v_add_f32_dpp v170, v233, v233 row_shr:2 row_mask:0xf bank_mask:0xf bound_ctrl:1
	v_add_f32_dpp v138, v234, v234 row_shr:2 row_mask:0xf bank_mask:0xf bound_ctrl:1
	s_nop 0
	v_add_f32_dpp v170, v170, v170 row_shr:4 row_mask:0xf bank_mask:0xf bound_ctrl:1
	s_nop 1
	v_add_f32_dpp v233, v170, v170 row_shr:8 row_mask:0xf bank_mask:0xf bound_ctrl:1
	v_add_f32_dpp v170, v138, v138 row_shr:4 row_mask:0xf bank_mask:0xf bound_ctrl:1
	ds_bpermute_b32 v234, v135, v233
	s_nop 0
	v_mov_b32_dpp v138, v170 row_shr:8 row_mask:0xf bank_mask:0xf bound_ctrl:1
	s_waitcnt lgkmcnt(1)
	v_pk_add_f32 v[138:139], v[170:171], v[138:139]
	ds_bpermute_b32 v135, v135, v138
	s_waitcnt lgkmcnt(1)
	v_add_f32_e32 v234, v139, v234
	s_and_saveexec_b64 s[68:69], s[4:5]
	s_cbranch_execz .LBB0_177
	s_add_u32 s4, s30, s14
	s_addc_u32 s5, s31, s3
	v_lshl_add_u64 v[240:241], v[136:137], 2, s[4:5]
	v_mul_f32_e32 v137, 0x3fb8aa3b, v139
	v_exp_f32_e32 v137, v137
	v_add_co_u32_e32 v240, vcc, 0x49300000, v240
	s_waitcnt lgkmcnt(0)
	v_add_f32_e32 v135, v234, v135
	v_addc_co_u32_e32 v241, vcc, 0, v241, vcc
	global_store_dword v[240:241], v137, off offset:28
	v_mul_f32_e32 v137, 0x3fb8aa3b, v135
	v_sub_f32_e32 v135, v135, v139
	v_mul_f32_e32 v135, 0x3fb8aa3b, v135
	v_exp_f32_e32 v137, v137
	v_exp_f32_e32 v135, v135
	global_store_dword v[240:241], v137, off offset:540
	global_store_dword v[240:241], v135, off offset:1052

; #define PG8_STAGE(bufoff, gbase, voff) do { _Pragma("unroll") for (int _i = 0; _i < 2; ++_i) \
;         __builtin_amdgcn_global_load_lds((const unsigned*)((const char*)(gbase) + (voff)[_i]), (LAS unsigned*)(lds + (bufoff) + ldsw + _i * 8192), 16, 0, 0); } while (0)
; #define PG8_LDA(dst, b, h) do { _Pragma("unroll") for (int m = 0; m < 4; ++m) _Pragma("unroll") for (int k = 0; k < 2; ++k) dst[m][k] = *(const LAS bf16x8*)(lds + PG8_SA(b, h) + aoff + m * 2048 + k * 1024); } while (0)
; #define PG8_LDB(dst, b, h) do { _Pragma("unroll") for (int n = 0; n < 2; ++n) _Pragma("unroll") for (int k = 0; k < 2; ++k) dst[n][k] = *(const LAS bf16x8*)(lds + PG8_SB(b, h) + boff + n * 2048 + k * 1024); } while (0)
; #define PG8_MMA(ai, bj, At, Bt) do { __builtin_amdgcn_s_setprio(1); _Pragma("unroll") for (int m = 0; m < 4; ++m) _Pragma("unroll") for (int n = 0; n < 2; ++n) _Pragma("unroll") for (int k = 0; k < 2; ++k) \
;         acc[ai][bj][m][n] = __builtin_amdgcn_mfma_f32_16x16x32_bf16(Bt[n][k], At[m][k], acc[ai][bj][m][n], 0, 0, 0); __builtin_amdgcn_s_setprio(0); } while (0)
; #define PG8_WAIT_V(n) asm volatile("s_waitcnt vmcnt(" #n ")" ::: "memory")
; #define PG8_BAR __builtin_amdgcn_s_barrier()
; template <class Epi>
; __device__ __forceinline__ void gemm_phase(LAS unsigned char* lds, const Gemm g, const StaticOrder& S, const Epi& E) {
;     ...
;         for (int t = 0; t < nt; t += 2) {
;             const bool last = (t == nt - 2);
;             if constexpr (Epi::MIDHOOK) { if (t == nt / 2) { if (wr == 0) PG8_BAR; E.mid(acc, cur, wr, wc, fr, fq); if (wr == 1) PG8_BAR; } }
;             const char* a1 = cA + (size_t)(t + 1) * kstep;
;             const char* a2 = last ? nA : cA + (size_t)(t + 2) * kstep; const char* b2 = last ? nB : cB + (size_t)(t + 2) * kstep;
;             const char* a3 = a2 + kstep; const char* b3 = b2 + kstep;
;             PG8_LDB(B0, 0, 0); PG8_LDA(At, 0, 0); PG8_LDB(B1, 0, 1); PG8_STAGE(PG8_SA(1, 1), a1 + hstep, voffA);
;             PG8_WAIT_L(0); PG8_BAR; PG8_SCHED; PG8_MMA(0, 0, At, B0); PG8_MMA(0, 1, At, B1); PG8_SCHED; PG8_BAR; PG8_SCHED;
;             PG8_LDA(At, 0, 1); PG8_STAGE(PG8_SB(0, 0), b2, voffB); PG8_STAGE(PG8_SA(0, 0), a2, voffA); PG8_STAGE(PG8_SB(0, 1), b2 + hstep, voffB);
;             PG8_WAIT_V(6); PG8_WAIT_L(0); PG8_BAR; PG8_SCHED; PG8_MMA(1, 0, At, B0); PG8_MMA(1, 1, At, B1); PG8_SCHED; PG8_BAR; PG8_SCHED;
.LBB0_451:
	s_add_u32 s86, s66, s68
	s_addc_u32 s87, s67, s69
	s_add_u32 s86, s86, 0x8000
	s_addc_u32 s87, s87, 0
	s_add_u32 s88, s70, s68
	s_addc_u32 s89, s71, s69
	s_cmp_eq_u32 s68, 0xf8000
	v_add_u32_e32 v0, s79, v143
	v_lshl_add_u64 v[2:3], v[138:139], 0, s[68:69]
	s_cselect_b32 s87, s55, s87
	s_cselect_b32 s86, s81, s86
	ds_read_b128 v[148:151], v0
	ds_read_b128 v[152:155], v0 offset:1024
	ds_read_b128 v[156:159], v0 offset:2048
	ds_read_b128 v[160:163], v0 offset:3072
	s_cselect_b32 s89, s83, s89
	s_cselect_b32 s88, s84, s88
	v_add_u32_e32 v0, s80, v143
	v_lshl_add_u64 v[208:209], v[2:3], 0, s[22:23]
	s_add_i32 m0, s59, 0xc000
	ds_read_b128 v[164:167], v145
	ds_read_b128 v[168:171], v145 offset:1024
	ds_read_b128 v[172:175], v145 offset:2048
	ds_read_b128 v[176:179], v145 offset:3072
	ds_read_b128 v[180:183], v145 offset:4096
	ds_read_b128 v[184:187], v145 offset:5120
	ds_read_b128 v[188:191], v145 offset:6144
	ds_read_b128 v[192:195], v145 offset:7168
	ds_read_b128 v[196:199], v0
	ds_read_b128 v[200:203], v0 offset:1024
	ds_read_b128 v[204:207], v0 offset:2048
	ds_read_b128 v[212:215], v0 offset:3072
	global_load_lds_dwordx4 v[208:209], off
	v_lshl_add_u64 v[2:3], v[2:3], 0, s[24:25]
	s_add_i32 m0, s59, 0xe000
	s_nop 0
	global_load_lds_dwordx4 v[2:3], off
	s_waitcnt vmcnt(8)
	s_waitcnt lgkmcnt(0)
	s_barrier
	s_setprio 1
	s_waitcnt lgkmcnt(0)
	v_mfma_f32_16x16x32_bf16 v[128:131], v[148:151], v[164:167], v[128:131]
	v_mfma_f32_16x16x32_bf16 v[124:127], v[156:159], v[164:167], v[124:127]
	v_mfma_f32_16x16x32_bf16 v[112:115], v[148:151], v[172:175], v[112:115]
	v_mfma_f32_16x16x32_bf16 v[108:111], v[156:159], v[172:175], v[108:111]
	v_mfma_f32_16x16x32_bf16 v[96:99], v[148:151], v[180:183], v[96:99]
	v_mfma_f32_16x16x32_bf16 v[92:95], v[156:159], v[180:183], v[92:95]
	v_mfma_f32_16x16x32_bf16 v[80:83], v[148:151], v[188:191], v[80:83]
	v_mfma_f32_16x16x32_bf16 v[76:79], v[156:159], v[188:191], v[76:79]
	v_mfma_f32_16x16x32_bf16 v[128:131], v[152:155], v[168:171], v[128:131]
	v_mfma_f32_16x16x32_bf16 v[124:127], v[160:163], v[168:171], v[124:127]
	v_mfma_f32_16x16x32_bf16 v[112:115], v[152:155], v[176:179], v[112:115]
	v_mfma_f32_16x16x32_bf16 v[108:111], v[160:163], v[176:179], v[108:111]
	v_mfma_f32_16x16x32_bf16 v[96:99], v[152:155], v[184:187], v[96:99]
	v_mfma_f32_16x16x32_bf16 v[92:95], v[160:163], v[184:187], v[92:95]
	v_mfma_f32_16x16x32_bf16 v[80:83], v[152:155], v[192:195], v[80:83]
	v_mfma_f32_16x16x32_bf16 v[76:79], v[160:163], v[192:195], v[76:79]
	s_setprio 0
	s_setprio 1
	v_mfma_f32_16x16x32_bf16 v[120:123], v[196:199], v[164:167], v[120:123]
	v_mfma_f32_16x16x32_bf16 v[116:119], v[204:207], v[164:167], v[116:119]
	v_mfma_f32_16x16x32_bf16 v[104:107], v[196:199], v[172:175], v[104:107]
	v_mfma_f32_16x16x32_bf16 v[100:103], v[204:207], v[172:175], v[100:103]
	v_mfma_f32_16x16x32_bf16 v[88:91], v[196:199], v[180:183], v[88:91]
	v_mfma_f32_16x16x32_bf16 v[84:87], v[204:207], v[180:183], v[84:87]
	v_mfma_f32_16x16x32_bf16 v[72:75], v[196:199], v[188:191], v[72:75]
	v_mfma_f32_16x16x32_bf16 v[68:71], v[204:207], v[188:191], v[68:71]
	v_mfma_f32_16x16x32_bf16 v[120:123], v[200:203], v[168:171], v[120:123]
	v_mfma_f32_16x16x32_bf16 v[116:119], v[212:215], v[168:171], v[116:119]
	v_mfma_f32_16x16x32_bf16 v[104:107], v[200:203], v[176:179], v[104:107]
	v_mfma_f32_16x16x32_bf16 v[100:103], v[212:215], v[176:179], v[100:103]
	v_mfma_f32_16x16x32_bf16 v[88:91], v[200:203], v[184:187], v[88:91]
	v_mfma_f32_16x16x32_bf16 v[84:87], v[212:215], v[184:187], v[84:87]
	v_mfma_f32_16x16x32_bf16 v[72:75], v[200:203], v[192:195], v[72:75]
	v_mfma_f32_16x16x32_bf16 v[68:71], v[212:215], v[192:195], v[68:71]
	s_setprio 0
	s_barrier
	v_lshl_add_u64 v[208:209], s[88:89], 0, v[132:133]
	s_add_i32 s88, s79, s58
	s_mov_b32 m0, s88
	ds_read_b128 v[164:167], v145 offset:16384
	ds_read_b128 v[168:171], v145 offset:17408
	ds_read_b128 v[172:175], v145 offset:18432
	ds_read_b128 v[176:179], v145 offset:19456
	ds_read_b128 v[180:183], v145 offset:20480
	ds_read_b128 v[184:187], v145 offset:21504
	ds_read_b128 v[188:191], v145 offset:22528
	ds_read_b128 v[192:195], v145 offset:23552
	global_load_lds_dwordx4 v[208:209], off
	v_lshl_add_u64 v[2:3], v[208:209], 0, s[6:7]
	s_add_i32 m0, s88, 0x2000
	v_lshl_add_u64 v[216:217], s[86:87], 0, v[132:133]
	global_load_lds_dwordx4 v[2:3], off
	s_mov_b32 m0, s59
	v_lshl_add_u64 v[2:3], v[216:217], 0, s[6:7]
	global_load_lds_dwordx4 v[216:217], off
	s_mov_b32 m0, s60
	s_add_i32 s86, s80, s58
	global_load_lds_dwordx4 v[2:3], off
	v_lshl_add_u64 v[2:3], v[208:209], 0, s[8:9]
	s_mov_b32 m0, s86
	s_nop 0
	global_load_lds_dwordx4 v[2:3], off
	v_lshl_add_u64 v[2:3], v[208:209], 0, s[10:11]
	s_add_i32 m0, s86, 0x2000
	s_nop 0
	global_load_lds_dwordx4 v[2:3], off
	s_waitcnt vmcnt(8)
	s_waitcnt lgkmcnt(0)
	s_barrier
; #define PG8_STAGE(bufoff, gbase, voff) do { _Pragma("unroll") for (int _i = 0; _i < 2; ++_i) \
;         __builtin_amdgcn_global_load_lds((const unsigned*)((const char*)(gbase) + (voff)[_i]), (LAS unsigned*)(lds + (bufoff) + ldsw + _i * 8192), 16, 0, 0); } while (0)
; #define PG8_LDA(dst, b, h) do { _Pragma("unroll") for (int m = 0; m < 4; ++m) _Pragma("unroll") for (int k = 0; k < 2; ++k) dst[m][k] = *(const LAS bf16x8*)(lds + PG8_SA(b, h) + aoff + m * 2048 + k * 1024); } while (0)
; #define PG8_LDB(dst, b, h) do { _Pragma("unroll") for (int n = 0; n < 2; ++n) _Pragma("unroll") for (int k = 0; k < 2; ++k) dst[n][k] = *(const LAS bf16x8*)(lds + PG8_SB(b, h) + boff + n * 2048 + k * 1024); } while (0)
; #define PG8_MMA(ai, bj, At, Bt) do { __builtin_amdgcn_s_setprio(1); _Pragma("unroll") for (int m = 0; m < 4; ++m) _Pragma("unroll") for (int n = 0; n < 2; ++n) _Pragma("unroll") for (int k = 0; k < 2; ++k) \
;         acc[ai][bj][m][n] = __builtin_amdgcn_mfma_f32_16x16x32_bf16(Bt[n][k], At[m][k], acc[ai][bj][m][n], 0, 0, 0); __builtin_amdgcn_s_setprio(0); } while (0)
; #define PG8_WAIT_V(n) asm volatile("s_waitcnt vmcnt(" #n ")" ::: "memory")
; #define PG8_WAIT_L(n) asm volatile("s_waitcnt lgkmcnt(" #n ")" ::: "memory")
; #define PG8_BAR __builtin_amdgcn_s_barrier()
; #define PG8_SCHED __builtin_amdgcn_sched_barrier(0)
; template <class Epi>
; __device__ __forceinline__ void gemm_phase(LAS unsigned char* lds, const Gemm g, const StaticOrder& S, const Epi& E) {
;     ...
;             PG8_WAIT_V(6); PG8_WAIT_L(0); PG8_BAR; PG8_SCHED; PG8_MMA(1, 0, At, B0); PG8_MMA(1, 1, At, B1); PG8_SCHED; PG8_BAR; PG8_SCHED;
;             PG8_LDB(B0, 1, 0); PG8_LDA(At, 1, 0); PG8_LDB(B1, 1, 1); PG8_STAGE(PG8_SA(0, 1), a2 + hstep, voffA);
;             PG8_WAIT_L(0); PG8_BAR; PG8_SCHED; PG8_MMA(0, 0, At, B0); PG8_MMA(0, 1, At, B1); PG8_SCHED; PG8_BAR; PG8_SCHED;
;             PG8_LDA(At, 1, 1); PG8_STAGE(PG8_SB(1, 0), b3, voffB); PG8_STAGE(PG8_SA(1, 0), a3, voffA); PG8_STAGE(PG8_SB(1, 1), b3 + hstep, voffB);
	s_setprio 1
	s_waitcnt lgkmcnt(0)
	v_mfma_f32_16x16x32_bf16 v[64:67], v[148:151], v[164:167], v[64:67]
	v_mfma_f32_16x16x32_bf16 v[60:63], v[156:159], v[164:167], v[60:63]
	v_mfma_f32_16x16x32_bf16 v[48:51], v[148:151], v[172:175], v[48:51]
	v_mfma_f32_16x16x32_bf16 v[44:47], v[156:159], v[172:175], v[44:47]
	v_mfma_f32_16x16x32_bf16 v[32:35], v[148:151], v[180:183], v[32:35]
	v_mfma_f32_16x16x32_bf16 v[28:31], v[156:159], v[180:183], v[28:31]
	v_mfma_f32_16x16x32_bf16 v[16:19], v[148:151], v[188:191], v[16:19]
	v_mfma_f32_16x16x32_bf16 v[12:15], v[156:159], v[188:191], v[12:15]
	v_mfma_f32_16x16x32_bf16 v[64:67], v[152:155], v[168:171], v[64:67]
	v_mfma_f32_16x16x32_bf16 v[60:63], v[160:163], v[168:171], v[60:63]
	v_mfma_f32_16x16x32_bf16 v[48:51], v[152:155], v[176:179], v[48:51]
	v_mfma_f32_16x16x32_bf16 v[44:47], v[160:163], v[176:179], v[44:47]
	v_mfma_f32_16x16x32_bf16 v[32:35], v[152:155], v[184:187], v[32:35]
	v_mfma_f32_16x16x32_bf16 v[28:31], v[160:163], v[184:187], v[28:31]
	v_mfma_f32_16x16x32_bf16 v[16:19], v[152:155], v[192:195], v[16:19]
	v_mfma_f32_16x16x32_bf16 v[12:15], v[160:163], v[192:195], v[12:15]
	s_setprio 0
	s_setprio 1
	v_mfma_f32_16x16x32_bf16 v[56:59], v[196:199], v[164:167], v[56:59]
	v_mfma_f32_16x16x32_bf16 v[52:55], v[204:207], v[164:167], v[52:55]
	v_mfma_f32_16x16x32_bf16 v[40:43], v[196:199], v[172:175], v[40:43]
	v_mfma_f32_16x16x32_bf16 v[36:39], v[204:207], v[172:175], v[36:39]
	v_mfma_f32_16x16x32_bf16 v[24:27], v[196:199], v[180:183], v[24:27]
	v_mfma_f32_16x16x32_bf16 v[20:23], v[204:207], v[180:183], v[20:23]
	v_mfma_f32_16x16x32_bf16 v[8:11], v[196:199], v[188:191], v[8:11]
	v_mfma_f32_16x16x32_bf16 v[2:5], v[204:207], v[188:191], v[4:7]
	v_mfma_f32_16x16x32_bf16 v[56:59], v[200:203], v[168:171], v[56:59]
	v_mfma_f32_16x16x32_bf16 v[52:55], v[212:215], v[168:171], v[52:55]
	v_mfma_f32_16x16x32_bf16 v[40:43], v[200:203], v[176:179], v[40:43]
	v_mfma_f32_16x16x32_bf16 v[36:39], v[212:215], v[176:179], v[36:39]
	v_mfma_f32_16x16x32_bf16 v[24:27], v[200:203], v[184:187], v[24:27]
	v_mfma_f32_16x16x32_bf16 v[20:23], v[212:215], v[184:187], v[20:23]
	v_mfma_f32_16x16x32_bf16 v[8:11], v[200:203], v[192:195], v[8:11]
	v_mfma_f32_16x16x32_bf16 v[2:5], v[212:215], v[192:195], v[2:5]
	s_setprio 0
	s_barrier
	s_add_i32 s86, 0, 0x18000
	v_add_u32_e32 v0, s86, v143
	s_add_i32 s87, 0, 0x1c000
	s_mov_b32 m0, s61
	ds_read_b128 v[148:151], v0
	ds_read_b128 v[152:155], v0 offset:1024
	ds_read_b128 v[156:159], v0 offset:2048
	ds_read_b128 v[160:163], v0 offset:3072
	ds_read_b128 v[164:167], v145 offset:32768
	ds_read_b128 v[168:171], v145 offset:33792
	ds_read_b128 v[172:175], v145 offset:34816
	ds_read_b128 v[176:179], v145 offset:35840
	ds_read_b128 v[180:183], v145 offset:36864
	ds_read_b128 v[184:187], v145 offset:37888
	ds_read_b128 v[188:191], v145 offset:38912
	ds_read_b128 v[192:195], v145 offset:39936
	v_add_u32_e32 v0, s87, v143
	v_lshl_add_u64 v[6:7], v[216:217], 0, s[8:9]
	ds_read_b128 v[196:199], v0
	ds_read_b128 v[200:203], v0 offset:1024
	ds_read_b128 v[204:207], v0 offset:2048
	ds_read_b128 v[212:215], v0 offset:3072
	global_load_lds_dwordx4 v[6:7], off
	v_lshl_add_u64 v[6:7], v[216:217], 0, s[10:11]
	s_mov_b32 m0, s62
	s_nop 0
	global_load_lds_dwordx4 v[6:7], off
	s_waitcnt vmcnt(8)
	s_waitcnt lgkmcnt(0)
	s_barrier
	s_setprio 1
	s_waitcnt lgkmcnt(0)
	v_mfma_f32_16x16x32_bf16 v[128:131], v[148:151], v[164:167], v[128:131]
	v_mfma_f32_16x16x32_bf16 v[124:127], v[156:159], v[164:167], v[124:127]
	v_mfma_f32_16x16x32_bf16 v[112:115], v[148:151], v[172:175], v[112:115]
	v_mfma_f32_16x16x32_bf16 v[108:111], v[156:159], v[172:175], v[108:111]
	v_mfma_f32_16x16x32_bf16 v[96:99], v[148:151], v[180:183], v[96:99]
	v_mfma_f32_16x16x32_bf16 v[92:95], v[156:159], v[180:183], v[92:95]
	v_mfma_f32_16x16x32_bf16 v[80:83], v[148:151], v[188:191], v[80:83]
	v_mfma_f32_16x16x32_bf16 v[76:79], v[156:159], v[188:191], v[76:79]
	v_mfma_f32_16x16x32_bf16 v[128:131], v[152:155], v[168:171], v[128:131]
	v_mfma_f32_16x16x32_bf16 v[124:127], v[160:163], v[168:171], v[124:127]
	v_mfma_f32_16x16x32_bf16 v[112:115], v[152:155], v[176:179], v[112:115]
	v_mfma_f32_16x16x32_bf16 v[108:111], v[160:163], v[176:179], v[108:111]
	v_mfma_f32_16x16x32_bf16 v[96:99], v[152:155], v[184:187], v[96:99]
	v_mfma_f32_16x16x32_bf16 v[92:95], v[160:163], v[184:187], v[92:95]
	v_mfma_f32_16x16x32_bf16 v[80:83], v[152:155], v[192:195], v[80:83]
	v_mfma_f32_16x16x32_bf16 v[76:79], v[160:163], v[192:195], v[76:79]
	s_setprio 0
	s_setprio 1
	v_mfma_f32_16x16x32_bf16 v[120:123], v[196:199], v[164:167], v[120:123]
	v_mfma_f32_16x16x32_bf16 v[116:119], v[204:207], v[164:167], v[116:119]
	v_mfma_f32_16x16x32_bf16 v[104:107], v[196:199], v[172:175], v[104:107]
	v_mfma_f32_16x16x32_bf16 v[100:103], v[204:207], v[172:175], v[100:103]
	v_mfma_f32_16x16x32_bf16 v[88:91], v[196:199], v[180:183], v[88:91]
	v_mfma_f32_16x16x32_bf16 v[84:87], v[204:207], v[180:183], v[84:87]
	v_mfma_f32_16x16x32_bf16 v[72:75], v[196:199], v[188:191], v[72:75]
	v_mfma_f32_16x16x32_bf16 v[68:71], v[204:207], v[188:191], v[68:71]
	v_mfma_f32_16x16x32_bf16 v[120:123], v[200:203], v[168:171], v[120:123]
	v_mfma_f32_16x16x32_bf16 v[116:119], v[212:215], v[168:171], v[116:119]
	v_mfma_f32_16x16x32_bf16 v[104:107], v[200:203], v[176:179], v[104:107]
	v_mfma_f32_16x16x32_bf16 v[100:103], v[212:215], v[176:179], v[100:103]
	v_mfma_f32_16x16x32_bf16 v[88:91], v[200:203], v[184:187], v[88:91]
	v_mfma_f32_16x16x32_bf16 v[84:87], v[212:215], v[184:187], v[84:87]
	v_mfma_f32_16x16x32_bf16 v[72:75], v[200:203], v[192:195], v[72:75]
	v_mfma_f32_16x16x32_bf16 v[68:71], v[212:215], v[192:195], v[68:71]
	s_setprio 0
	s_barrier
; #define PG8_STAGE(bufoff, gbase, voff) do { _Pragma("unroll") for (int _i = 0; _i < 2; ++_i) \
;         __builtin_amdgcn_global_load_lds((const unsigned*)((const char*)(gbase) + (voff)[_i]), (LAS unsigned*)(lds + (bufoff) + ldsw + _i * 8192), 16, 0, 0); } while (0)
; #define PG8_LDA(dst, b, h) do { _Pragma("unroll") for (int m = 0; m < 4; ++m) _Pragma("unroll") for (int k = 0; k < 2; ++k) dst[m][k] = *(const LAS bf16x8*)(lds + PG8_SA(b, h) + aoff + m * 2048 + k * 1024); } while (0)
; #define PG8_MMA(ai, bj, At, Bt) do { __builtin_amdgcn_s_setprio(1); _Pragma("unroll") for (int m = 0; m < 4; ++m) _Pragma("unroll") for (int n = 0; n < 2; ++n) _Pragma("unroll") for (int k = 0; k < 2; ++k) \
;         acc[ai][bj][m][n] = __builtin_amdgcn_mfma_f32_16x16x32_bf16(Bt[n][k], At[m][k], acc[ai][bj][m][n], 0, 0, 0); __builtin_amdgcn_s_setprio(0); } while (0)
; #define PG8_WAIT_V(n) asm volatile("s_waitcnt vmcnt(" #n ")" ::: "memory")
; #define PG8_WAIT_L(n) asm volatile("s_waitcnt lgkmcnt(" #n ")" ::: "memory")
; #define PG8_BAR __builtin_amdgcn_s_barrier()
; #define PG8_SCHED __builtin_amdgcn_sched_barrier(0)
; template <class Epi>
; __device__ __forceinline__ void gemm_phase(LAS unsigned char* lds, const Gemm g, const StaticOrder& S, const Epi& E) {
;     ...
;             PG8_LDA(At, 1, 1); PG8_STAGE(PG8_SB(1, 0), b3, voffB); PG8_STAGE(PG8_SA(1, 0), a3, voffA); PG8_STAGE(PG8_SB(1, 1), b3 + hstep, voffB);
;             PG8_WAIT_V(6); PG8_WAIT_L(0); PG8_BAR; PG8_SCHED; PG8_MMA(1, 0, At, B0); PG8_MMA(1, 1, At, B1); PG8_SCHED; PG8_BAR; PG8_SCHED;
;         }
	s_add_i32 s86, s86, s58
	v_lshl_add_u64 v[6:7], v[208:209], 0, s[18:19]
	s_mov_b32 m0, s86
	ds_read_b128 v[164:167], v145 offset:49152
	ds_read_b128 v[168:171], v145 offset:50176
	ds_read_b128 v[172:175], v145 offset:51200
	ds_read_b128 v[176:179], v145 offset:52224
	ds_read_b128 v[180:183], v145 offset:53248
	ds_read_b128 v[184:187], v145 offset:54272
	ds_read_b128 v[188:191], v145 offset:55296
	ds_read_b128 v[192:195], v145 offset:56320
	global_load_lds_dwordx4 v[6:7], off
	v_lshl_add_u64 v[6:7], v[208:209], 0, s[20:21]
	s_add_i32 m0, s86, 0x2000
	s_add_i32 s86, s87, s58
	global_load_lds_dwordx4 v[6:7], off
	v_lshl_add_u64 v[6:7], v[216:217], 0, s[18:19]
	s_mov_b32 m0, s72
	s_nop 0
	global_load_lds_dwordx4 v[6:7], off
	v_lshl_add_u64 v[6:7], v[216:217], 0, s[20:21]
	s_mov_b32 m0, s73
	s_nop 0
	global_load_lds_dwordx4 v[6:7], off
	v_lshl_add_u64 v[6:7], v[208:209], 0, s[22:23]
	s_mov_b32 m0, s86
	s_nop 0
	global_load_lds_dwordx4 v[6:7], off
	v_lshl_add_u64 v[6:7], v[208:209], 0, s[24:25]
	s_add_i32 m0, s86, 0x2000
	s_nop 0
	global_load_lds_dwordx4 v[6:7], off
	s_waitcnt vmcnt(8)
	s_waitcnt lgkmcnt(0)
	s_barrier
	s_setprio 1
	s_waitcnt lgkmcnt(0)
	v_mfma_f32_16x16x32_bf16 v[64:67], v[148:151], v[164:167], v[64:67]
	v_mfma_f32_16x16x32_bf16 v[60:63], v[156:159], v[164:167], v[60:63]
	v_mfma_f32_16x16x32_bf16 v[48:51], v[148:151], v[172:175], v[48:51]
	v_mfma_f32_16x16x32_bf16 v[44:47], v[156:159], v[172:175], v[44:47]
	v_mfma_f32_16x16x32_bf16 v[32:35], v[148:151], v[180:183], v[32:35]
	v_mfma_f32_16x16x32_bf16 v[28:31], v[156:159], v[180:183], v[28:31]
	v_mfma_f32_16x16x32_bf16 v[16:19], v[148:151], v[188:191], v[16:19]
	v_mfma_f32_16x16x32_bf16 v[12:15], v[156:159], v[188:191], v[12:15]
	v_mfma_f32_16x16x32_bf16 v[64:67], v[152:155], v[168:171], v[64:67]
	v_mfma_f32_16x16x32_bf16 v[60:63], v[160:163], v[168:171], v[60:63]
	v_mfma_f32_16x16x32_bf16 v[48:51], v[152:155], v[176:179], v[48:51]
	v_mfma_f32_16x16x32_bf16 v[44:47], v[160:163], v[176:179], v[44:47]
	v_mfma_f32_16x16x32_bf16 v[32:35], v[152:155], v[184:187], v[32:35]
	v_mfma_f32_16x16x32_bf16 v[28:31], v[160:163], v[184:187], v[28:31]
	v_mfma_f32_16x16x32_bf16 v[16:19], v[152:155], v[192:195], v[16:19]
	v_mfma_f32_16x16x32_bf16 v[12:15], v[160:163], v[192:195], v[12:15]
	s_setprio 0
	s_setprio 1
	v_mfma_f32_16x16x32_bf16 v[56:59], v[196:199], v[164:167], v[56:59]
	v_mfma_f32_16x16x32_bf16 v[52:55], v[204:207], v[164:167], v[52:55]
	v_mfma_f32_16x16x32_bf16 v[40:43], v[196:199], v[172:175], v[40:43]
	v_mfma_f32_16x16x32_bf16 v[36:39], v[204:207], v[172:175], v[36:39]
	v_mfma_f32_16x16x32_bf16 v[24:27], v[196:199], v[180:183], v[24:27]
	v_mfma_f32_16x16x32_bf16 v[20:23], v[204:207], v[180:183], v[20:23]
	v_mfma_f32_16x16x32_bf16 v[6:9], v[196:199], v[188:191], v[8:11]
	v_mfma_f32_16x16x32_bf16 v[2:5], v[204:207], v[188:191], v[2:5]
	v_mfma_f32_16x16x32_bf16 v[56:59], v[200:203], v[168:171], v[56:59]
	v_mfma_f32_16x16x32_bf16 v[52:55], v[212:215], v[168:171], v[52:55]
	v_mfma_f32_16x16x32_bf16 v[40:43], v[200:203], v[176:179], v[40:43]
	v_mfma_f32_16x16x32_bf16 v[36:39], v[212:215], v[176:179], v[36:39]
	v_mfma_f32_16x16x32_bf16 v[24:27], v[200:203], v[184:187], v[24:27]
	v_mfma_f32_16x16x32_bf16 v[20:23], v[212:215], v[184:187], v[20:23]
	v_mfma_f32_16x16x32_bf16 v[8:11], v[200:203], v[192:195], v[6:9]
	v_mfma_f32_16x16x32_bf16 v[4:7], v[212:215], v[192:195], v[2:5]
	s_setprio 0
	s_barrier
	s_add_i32 s85, s85, 2
	s_add_u32 s68, s68, 0x8000
	s_addc_u32 s69, s69, 0
	s_cmp_gt_u32 s85, 61
	s_cbranch_scc1 .LBB0_457

; #define PG8_STAGE(bufoff, gbase, voff) do { _Pragma("unroll") for (int _i = 0; _i < 2; ++_i) \
;         __builtin_amdgcn_global_load_lds((const unsigned*)((const char*)(gbase) + (voff)[_i]), (LAS unsigned*)(lds + (bufoff) + ldsw + _i * 8192), 16, 0, 0); } while (0)
; #define PG8_LDA(dst, b, h) do { _Pragma("unroll") for (int m = 0; m < 4; ++m) _Pragma("unroll") for (int k = 0; k < 2; ++k) dst[m][k] = *(const LAS bf16x8*)(lds + PG8_SA(b, h) + aoff + m * 2048 + k * 1024); } while (0)
; #define PG8_LDB(dst, b, h) do { _Pragma("unroll") for (int n = 0; n < 2; ++n) _Pragma("unroll") for (int k = 0; k < 2; ++k) dst[n][k] = *(const LAS bf16x8*)(lds + PG8_SB(b, h) + boff + n * 2048 + k * 1024); } while (0)
; #define PG8_MMA(ai, bj, At, Bt) do { __builtin_amdgcn_s_setprio(1); _Pragma("unroll") for (int m = 0; m < 4; ++m) _Pragma("unroll") for (int n = 0; n < 2; ++n) _Pragma("unroll") for (int k = 0; k < 2; ++k) \
;         acc[ai][bj][m][n] = __builtin_amdgcn_mfma_f32_16x16x32_bf16(Bt[n][k], At[m][k], acc[ai][bj][m][n], 0, 0, 0); __builtin_amdgcn_s_setprio(0); } while (0)
; #define PG8_WAIT_V(n) asm volatile("s_waitcnt vmcnt(" #n ")" ::: "memory")
; #define PG8_BAR __builtin_amdgcn_s_barrier()
; template <class Epi>
; __device__ __forceinline__ void gemm_phase(LAS unsigned char* lds, const Gemm g, const StaticOrder& S, const Epi& E) {
;     ...
;         for (int t = 0; t < nt; t += 2) {
;             const bool last = (t == nt - 2);
;             if constexpr (Epi::MIDHOOK) { if (t == nt / 2) { if (wr == 0) PG8_BAR; E.mid(acc, cur, wr, wc, fr, fq); if (wr == 1) PG8_BAR; } }
;             const char* a1 = cA + (size_t)(t + 1) * kstep;
;             const char* a2 = last ? nA : cA + (size_t)(t + 2) * kstep; const char* b2 = last ? nB : cB + (size_t)(t + 2) * kstep;
;             const char* a3 = a2 + kstep; const char* b3 = b2 + kstep;
;             PG8_LDB(B0, 0, 0); PG8_LDA(At, 0, 0); PG8_LDB(B1, 0, 1); PG8_STAGE(PG8_SA(1, 1), a1 + hstep, voffA);
;             PG8_WAIT_L(0); PG8_BAR; PG8_SCHED; PG8_MMA(0, 0, At, B0); PG8_MMA(0, 1, At, B1); PG8_SCHED; PG8_BAR; PG8_SCHED;
;             PG8_LDA(At, 0, 1); PG8_STAGE(PG8_SB(0, 0), b2, voffB); PG8_STAGE(PG8_SA(0, 0), a2, voffA); PG8_STAGE(PG8_SB(0, 1), b2 + hstep, voffB);
;             PG8_WAIT_V(6); PG8_WAIT_L(0); PG8_BAR; PG8_SCHED; PG8_MMA(1, 0, At, B0); PG8_MMA(1, 1, At, B1); PG8_SCHED; PG8_BAR; PG8_SCHED;
.LBB0_537:
	s_add_u32 s71, s52, 0xfff04000
	s_addc_u32 s72, s53, -1
	s_cmp_eq_u32 s70, 60
	s_cselect_b32 s73, s45, s72
	s_cselect_b32 s72, s51, s71
	s_cselect_b32 s75, s43, s55
	s_cselect_b32 s74, s69, s54
	v_lshl_add_u64 v[206:207], s[52:53], 0, v[128:129]
	s_add_i32 m0, s34, 0xc000
	ds_read_b128 v[134:137], v141
	ds_read_b128 v[146:149], v141 offset:1024
	ds_read_b128 v[150:153], v141 offset:2048
	ds_read_b128 v[154:157], v141 offset:3072
	ds_read_b128 v[158:161], v142
	ds_read_b128 v[162:165], v142 offset:1024
	ds_read_b128 v[166:169], v142 offset:2048
	ds_read_b128 v[170:173], v142 offset:3072
	ds_read_b128 v[174:177], v142 offset:4096
	ds_read_b128 v[178:181], v142 offset:5120
	ds_read_b128 v[182:185], v142 offset:6144
	ds_read_b128 v[186:189], v142 offset:7168
	ds_read_b128 v[190:193], v143
	ds_read_b128 v[194:197], v143 offset:1024
	ds_read_b128 v[198:201], v143 offset:2048
	ds_read_b128 v[202:205], v143 offset:3072
	global_load_lds_dwordx4 v[206:207], off
	v_lshl_add_u64 v[206:207], v[206:207], 0, s[6:7]
	s_add_i32 m0, s34, 0xe000
	s_nop 0
	global_load_lds_dwordx4 v[206:207], off
	s_waitcnt vmcnt(8)
	s_waitcnt lgkmcnt(0)
	s_barrier
	s_setprio 1
	s_waitcnt lgkmcnt(0)
	v_mfma_f32_16x16x32_bf16 v[124:127], v[134:137], v[158:161], v[124:127]
	v_mfma_f32_16x16x32_bf16 v[120:123], v[150:153], v[158:161], v[120:123]
	v_mfma_f32_16x16x32_bf16 v[108:111], v[134:137], v[166:169], v[108:111]
	v_mfma_f32_16x16x32_bf16 v[104:107], v[150:153], v[166:169], v[104:107]
	v_mfma_f32_16x16x32_bf16 v[92:95], v[134:137], v[174:177], v[92:95]
	v_mfma_f32_16x16x32_bf16 v[88:91], v[150:153], v[174:177], v[88:91]
	v_mfma_f32_16x16x32_bf16 v[76:79], v[134:137], v[182:185], v[76:79]
	v_mfma_f32_16x16x32_bf16 v[72:75], v[150:153], v[182:185], v[72:75]
	v_mfma_f32_16x16x32_bf16 v[124:127], v[146:149], v[162:165], v[124:127]
	v_mfma_f32_16x16x32_bf16 v[120:123], v[154:157], v[162:165], v[120:123]
	v_mfma_f32_16x16x32_bf16 v[108:111], v[146:149], v[170:173], v[108:111]
	v_mfma_f32_16x16x32_bf16 v[104:107], v[154:157], v[170:173], v[104:107]
	v_mfma_f32_16x16x32_bf16 v[92:95], v[146:149], v[178:181], v[92:95]
	v_mfma_f32_16x16x32_bf16 v[88:91], v[154:157], v[178:181], v[88:91]
	v_mfma_f32_16x16x32_bf16 v[76:79], v[146:149], v[186:189], v[76:79]
	v_mfma_f32_16x16x32_bf16 v[72:75], v[154:157], v[186:189], v[72:75]
	s_setprio 0
	s_setprio 1
	v_mfma_f32_16x16x32_bf16 v[116:119], v[190:193], v[158:161], v[116:119]
	v_mfma_f32_16x16x32_bf16 v[112:115], v[198:201], v[158:161], v[112:115]
	v_mfma_f32_16x16x32_bf16 v[100:103], v[190:193], v[166:169], v[100:103]
	v_mfma_f32_16x16x32_bf16 v[96:99], v[198:201], v[166:169], v[96:99]
	v_mfma_f32_16x16x32_bf16 v[84:87], v[190:193], v[174:177], v[84:87]
	v_mfma_f32_16x16x32_bf16 v[80:83], v[198:201], v[174:177], v[80:83]
	v_mfma_f32_16x16x32_bf16 v[68:71], v[190:193], v[182:185], v[68:71]
	v_mfma_f32_16x16x32_bf16 v[64:67], v[198:201], v[182:185], v[64:67]
	v_mfma_f32_16x16x32_bf16 v[116:119], v[194:197], v[162:165], v[116:119]
	v_mfma_f32_16x16x32_bf16 v[112:115], v[202:205], v[162:165], v[112:115]
	v_mfma_f32_16x16x32_bf16 v[100:103], v[194:197], v[170:173], v[100:103]
	v_mfma_f32_16x16x32_bf16 v[96:99], v[202:205], v[170:173], v[96:99]
	v_mfma_f32_16x16x32_bf16 v[84:87], v[194:197], v[178:181], v[84:87]
	v_mfma_f32_16x16x32_bf16 v[80:83], v[202:205], v[178:181], v[80:83]
	v_mfma_f32_16x16x32_bf16 v[68:71], v[194:197], v[186:189], v[68:71]
	v_mfma_f32_16x16x32_bf16 v[64:67], v[202:205], v[186:189], v[64:67]
	s_setprio 0
	s_barrier
	s_add_i32 s71, s65, s27
	v_lshl_add_u64 v[206:207], s[74:75], 0, v[128:129]
	s_mov_b32 m0, s71
	ds_read_b128 v[158:161], v142 offset:16384
	ds_read_b128 v[162:165], v142 offset:17408
	ds_read_b128 v[166:169], v142 offset:18432
	ds_read_b128 v[170:173], v142 offset:19456
	ds_read_b128 v[174:177], v142 offset:20480
	ds_read_b128 v[178:181], v142 offset:21504
	ds_read_b128 v[182:185], v142 offset:22528
	ds_read_b128 v[186:189], v142 offset:23552
	global_load_lds_dwordx4 v[206:207], off
	v_lshl_add_u64 v[208:209], v[206:207], 0, s[6:7]
	s_add_i32 m0, s71, 0x2000
	s_add_i32 s71, s66, s27
	global_load_lds_dwordx4 v[208:209], off
	v_lshl_add_u64 v[208:209], s[72:73], 0, v[128:129]
	s_mov_b32 m0, s34
	v_lshl_add_u64 v[212:213], v[208:209], 0, s[6:7]
	global_load_lds_dwordx4 v[208:209], off
	s_mov_b32 m0, s35
	s_nop 0
	global_load_lds_dwordx4 v[212:213], off
	v_lshl_add_u64 v[212:213], v[206:207], 0, s[8:9]
	s_mov_b32 m0, s71
	s_nop 0
	global_load_lds_dwordx4 v[212:213], off
	v_lshl_add_u64 v[212:213], v[206:207], 0, s[10:11]
	s_add_i32 m0, s71, 0x2000
	s_nop 0
	global_load_lds_dwordx4 v[212:213], off
	s_waitcnt vmcnt(8)
	s_waitcnt lgkmcnt(0)
	s_barrier
; #define PG8_STAGE(bufoff, gbase, voff) do { _Pragma("unroll") for (int _i = 0; _i < 2; ++_i) \
;         __builtin_amdgcn_global_load_lds((const unsigned*)((const char*)(gbase) + (voff)[_i]), (LAS unsigned*)(lds + (bufoff) + ldsw + _i * 8192), 16, 0, 0); } while (0)
; #define PG8_LDA(dst, b, h) do { _Pragma("unroll") for (int m = 0; m < 4; ++m) _Pragma("unroll") for (int k = 0; k < 2; ++k) dst[m][k] = *(const LAS bf16x8*)(lds + PG8_SA(b, h) + aoff + m * 2048 + k * 1024); } while (0)
; #define PG8_LDB(dst, b, h) do { _Pragma("unroll") for (int n = 0; n < 2; ++n) _Pragma("unroll") for (int k = 0; k < 2; ++k) dst[n][k] = *(const LAS bf16x8*)(lds + PG8_SB(b, h) + boff + n * 2048 + k * 1024); } while (0)
; #define PG8_MMA(ai, bj, At, Bt) do { __builtin_amdgcn_s_setprio(1); _Pragma("unroll") for (int m = 0; m < 4; ++m) _Pragma("unroll") for (int n = 0; n < 2; ++n) _Pragma("unroll") for (int k = 0; k < 2; ++k) \
;         acc[ai][bj][m][n] = __builtin_amdgcn_mfma_f32_16x16x32_bf16(Bt[n][k], At[m][k], acc[ai][bj][m][n], 0, 0, 0); __builtin_amdgcn_s_setprio(0); } while (0)
; #define PG8_WAIT_V(n) asm volatile("s_waitcnt vmcnt(" #n ")" ::: "memory")
; #define PG8_WAIT_L(n) asm volatile("s_waitcnt lgkmcnt(" #n ")" ::: "memory")
; #define PG8_BAR __builtin_amdgcn_s_barrier()
; #define PG8_SCHED __builtin_amdgcn_sched_barrier(0)
; template <class Epi>
; __device__ __forceinline__ void gemm_phase(LAS unsigned char* lds, const Gemm g, const StaticOrder& S, const Epi& E) {
;     ...
;             PG8_WAIT_V(6); PG8_WAIT_L(0); PG8_BAR; PG8_SCHED; PG8_MMA(1, 0, At, B0); PG8_MMA(1, 1, At, B1); PG8_SCHED; PG8_BAR; PG8_SCHED;
;             PG8_LDB(B0, 1, 0); PG8_LDA(At, 1, 0); PG8_LDB(B1, 1, 1); PG8_STAGE(PG8_SA(0, 1), a2 + hstep, voffA);
;             PG8_WAIT_L(0); PG8_BAR; PG8_SCHED; PG8_MMA(0, 0, At, B0); PG8_MMA(0, 1, At, B1); PG8_SCHED; PG8_BAR; PG8_SCHED;
;             PG8_LDA(At, 1, 1); PG8_STAGE(PG8_SB(1, 0), b3, voffB); PG8_STAGE(PG8_SA(1, 0), a3, voffA); PG8_STAGE(PG8_SB(1, 1), b3 + hstep, voffB);
	s_setprio 1
	s_waitcnt lgkmcnt(0)
	v_mfma_f32_16x16x32_bf16 v[60:63], v[134:137], v[158:161], v[60:63]
	v_mfma_f32_16x16x32_bf16 v[56:59], v[150:153], v[158:161], v[56:59]
	v_mfma_f32_16x16x32_bf16 v[44:47], v[134:137], v[166:169], v[44:47]
	v_mfma_f32_16x16x32_bf16 v[40:43], v[150:153], v[166:169], v[40:43]
	v_mfma_f32_16x16x32_bf16 v[28:31], v[134:137], v[174:177], v[28:31]
	v_mfma_f32_16x16x32_bf16 v[24:27], v[150:153], v[174:177], v[24:27]
	v_mfma_f32_16x16x32_bf16 v[12:15], v[134:137], v[182:185], v[12:15]
	v_mfma_f32_16x16x32_bf16 v[8:11], v[150:153], v[182:185], v[8:11]
	v_mfma_f32_16x16x32_bf16 v[60:63], v[146:149], v[162:165], v[60:63]
	v_mfma_f32_16x16x32_bf16 v[56:59], v[154:157], v[162:165], v[56:59]
	v_mfma_f32_16x16x32_bf16 v[44:47], v[146:149], v[170:173], v[44:47]
	v_mfma_f32_16x16x32_bf16 v[40:43], v[154:157], v[170:173], v[40:43]
	v_mfma_f32_16x16x32_bf16 v[28:31], v[146:149], v[178:181], v[28:31]
	v_mfma_f32_16x16x32_bf16 v[24:27], v[154:157], v[178:181], v[24:27]
	v_mfma_f32_16x16x32_bf16 v[12:15], v[146:149], v[186:189], v[12:15]
	v_mfma_f32_16x16x32_bf16 v[8:11], v[154:157], v[186:189], v[8:11]
	s_setprio 0
	s_setprio 1
	v_mfma_f32_16x16x32_bf16 v[52:55], v[190:193], v[158:161], v[52:55]
	v_mfma_f32_16x16x32_bf16 v[48:51], v[198:201], v[158:161], v[48:51]
	v_mfma_f32_16x16x32_bf16 v[36:39], v[190:193], v[166:169], v[36:39]
	v_mfma_f32_16x16x32_bf16 v[32:35], v[198:201], v[166:169], v[32:35]
	v_mfma_f32_16x16x32_bf16 v[20:23], v[190:193], v[174:177], v[20:23]
	v_mfma_f32_16x16x32_bf16 v[16:19], v[198:201], v[174:177], v[16:19]
	v_mfma_f32_16x16x32_bf16 v[4:7], v[190:193], v[182:185], v[4:7]
	v_mfma_f32_16x16x32_bf16 v[0:3], v[198:201], v[182:185], v[0:3]
	v_mfma_f32_16x16x32_bf16 v[52:55], v[194:197], v[162:165], v[52:55]
	v_mfma_f32_16x16x32_bf16 v[48:51], v[202:205], v[162:165], v[48:51]
	v_mfma_f32_16x16x32_bf16 v[36:39], v[194:197], v[170:173], v[36:39]
	v_mfma_f32_16x16x32_bf16 v[32:35], v[202:205], v[170:173], v[32:35]
	v_mfma_f32_16x16x32_bf16 v[20:23], v[194:197], v[178:181], v[20:23]
	v_mfma_f32_16x16x32_bf16 v[16:19], v[202:205], v[178:181], v[16:19]
	v_mfma_f32_16x16x32_bf16 v[4:7], v[194:197], v[186:189], v[4:7]
	v_mfma_f32_16x16x32_bf16 v[0:3], v[202:205], v[186:189], v[0:3]
	s_setprio 0
	s_barrier
	s_add_i32 s71, 0, 0x18000
	v_add_u32_e32 v145, s71, v140
	s_add_i32 s72, 0, 0x1c000
	s_mov_b32 m0, s56
	ds_read_b128 v[134:137], v145
	ds_read_b128 v[146:149], v145 offset:1024
	ds_read_b128 v[150:153], v145 offset:2048
	ds_read_b128 v[154:157], v145 offset:3072
	ds_read_b128 v[158:161], v142 offset:32768
	ds_read_b128 v[162:165], v142 offset:33792
	ds_read_b128 v[166:169], v142 offset:34816
	ds_read_b128 v[170:173], v142 offset:35840
	ds_read_b128 v[174:177], v142 offset:36864
	ds_read_b128 v[178:181], v142 offset:37888
	ds_read_b128 v[182:185], v142 offset:38912
	ds_read_b128 v[186:189], v142 offset:39936
	v_add_u32_e32 v145, s72, v140
	v_lshl_add_u64 v[212:213], v[208:209], 0, s[8:9]
	ds_read_b128 v[190:193], v145
	ds_read_b128 v[194:197], v145 offset:1024
	ds_read_b128 v[198:201], v145 offset:2048
	ds_read_b128 v[202:205], v145 offset:3072
	global_load_lds_dwordx4 v[212:213], off
	v_lshl_add_u64 v[212:213], v[208:209], 0, s[10:11]
	s_mov_b32 m0, s57
	s_nop 0
	global_load_lds_dwordx4 v[212:213], off
	s_waitcnt vmcnt(8)
	s_waitcnt lgkmcnt(0)
	s_barrier
	s_setprio 1
	s_waitcnt lgkmcnt(0)
	v_mfma_f32_16x16x32_bf16 v[124:127], v[134:137], v[158:161], v[124:127]
	v_mfma_f32_16x16x32_bf16 v[120:123], v[150:153], v[158:161], v[120:123]
	v_mfma_f32_16x16x32_bf16 v[108:111], v[134:137], v[166:169], v[108:111]
	v_mfma_f32_16x16x32_bf16 v[104:107], v[150:153], v[166:169], v[104:107]
	v_mfma_f32_16x16x32_bf16 v[92:95], v[134:137], v[174:177], v[92:95]
	v_mfma_f32_16x16x32_bf16 v[88:91], v[150:153], v[174:177], v[88:91]
	v_mfma_f32_16x16x32_bf16 v[76:79], v[134:137], v[182:185], v[76:79]
	v_mfma_f32_16x16x32_bf16 v[72:75], v[150:153], v[182:185], v[72:75]
	v_mfma_f32_16x16x32_bf16 v[124:127], v[146:149], v[162:165], v[124:127]
	v_mfma_f32_16x16x32_bf16 v[120:123], v[154:157], v[162:165], v[120:123]
	v_mfma_f32_16x16x32_bf16 v[108:111], v[146:149], v[170:173], v[108:111]
	v_mfma_f32_16x16x32_bf16 v[104:107], v[154:157], v[170:173], v[104:107]
	v_mfma_f32_16x16x32_bf16 v[92:95], v[146:149], v[178:181], v[92:95]
	v_mfma_f32_16x16x32_bf16 v[88:91], v[154:157], v[178:181], v[88:91]
	v_mfma_f32_16x16x32_bf16 v[76:79], v[146:149], v[186:189], v[76:79]
	v_mfma_f32_16x16x32_bf16 v[72:75], v[154:157], v[186:189], v[72:75]
	s_setprio 0
	s_setprio 1
	v_mfma_f32_16x16x32_bf16 v[116:119], v[190:193], v[158:161], v[116:119]
	v_mfma_f32_16x16x32_bf16 v[112:115], v[198:201], v[158:161], v[112:115]
	v_mfma_f32_16x16x32_bf16 v[100:103], v[190:193], v[166:169], v[100:103]
	v_mfma_f32_16x16x32_bf16 v[96:99], v[198:201], v[166:169], v[96:99]
	v_mfma_f32_16x16x32_bf16 v[84:87], v[190:193], v[174:177], v[84:87]
	v_mfma_f32_16x16x32_bf16 v[80:83], v[198:201], v[174:177], v[80:83]
	v_mfma_f32_16x16x32_bf16 v[68:71], v[190:193], v[182:185], v[68:71]
	v_mfma_f32_16x16x32_bf16 v[64:67], v[198:201], v[182:185], v[64:67]
	v_mfma_f32_16x16x32_bf16 v[116:119], v[194:197], v[162:165], v[116:119]
	v_mfma_f32_16x16x32_bf16 v[112:115], v[202:205], v[162:165], v[112:115]
	v_mfma_f32_16x16x32_bf16 v[100:103], v[194:197], v[170:173], v[100:103]
	v_mfma_f32_16x16x32_bf16 v[96:99], v[202:205], v[170:173], v[96:99]
	v_mfma_f32_16x16x32_bf16 v[84:87], v[194:197], v[178:181], v[84:87]
	v_mfma_f32_16x16x32_bf16 v[80:83], v[202:205], v[178:181], v[80:83]
	v_mfma_f32_16x16x32_bf16 v[68:71], v[194:197], v[186:189], v[68:71]
	v_mfma_f32_16x16x32_bf16 v[64:67], v[202:205], v[186:189], v[64:67]
	s_setprio 0
	s_barrier
; __device__ __forceinline__ unsigned pk2(float lo, float hi) { return __builtin_bit_cast(unsigned, __builtin_convertvector((f32x2){lo, hi}, bf16x2_t)); }
; #define PG8_STAGE(bufoff, gbase, voff) do { _Pragma("unroll") for (int _i = 0; _i < 2; ++_i) \
;         __builtin_amdgcn_global_load_lds((const unsigned*)((const char*)(gbase) + (voff)[_i]), (LAS unsigned*)(lds + (bufoff) + ldsw + _i * 8192), 16, 0, 0); } while (0)
; #define PG8_LDA(dst, b, h) do { _Pragma("unroll") for (int m = 0; m < 4; ++m) _Pragma("unroll") for (int k = 0; k < 2; ++k) dst[m][k] = *(const LAS bf16x8*)(lds + PG8_SA(b, h) + aoff + m * 2048 + k * 1024); } while (0)
; #define PG8_WAIT_V(n) asm volatile("s_waitcnt vmcnt(" #n ")" ::: "memory")
; #define PG8_WAIT_L(n) asm volatile("s_waitcnt lgkmcnt(" #n ")" ::: "memory")
; #define PG8_BAR __builtin_amdgcn_s_barrier()
; template <class Epi>
; __device__ __forceinline__ void gemm_phase(LAS unsigned char* lds, const Gemm g, const StaticOrder& S, const Epi& E) {
;     ...
;             PG8_LDA(At, 1, 1); PG8_STAGE(PG8_SB(1, 0), b3, voffB); PG8_STAGE(PG8_SA(1, 0), a3, voffA); PG8_STAGE(PG8_SB(1, 1), b3 + hstep, voffB);
;             PG8_WAIT_V(6); PG8_WAIT_L(0); PG8_BAR; PG8_SCHED; PG8_MMA(1, 0, At, B0); PG8_MMA(1, 1, At, B1); PG8_SCHED; PG8_BAR; PG8_SCHED;
;         }
;     __device__ __forceinline__ void operator()(f32x4 (&acc)[2][2][4][2], const pg8::Unit& u, int wr, int wc, int fr, int fq) const {
;     ...
;         const int row0 = u.pm * 256 + wr * 64 + fr, col0 = u.pn * 256 + wc * 32 + 8 * fq;
; #pragma unroll
;         for (int ai = 0; ai < 2; ++ai)
; #pragma unroll
;             for (int m = 0; m < 4; ++m) {
;                 const int row = row0 + ai * 128 + m * 16;
;                 const size_t off = (size_t)row * DM + col0;
;                 float ss = 0.f;
; #pragma unroll
;                 for (int bj = 0; bj < 2; ++bj) {
;                     const f32x4 y0 = *(const f32x4*)(x + off + bj * 128) + acc[ai][bj][m][0], y1 = *(const f32x4*)(x + off + bj * 128 + 4) + acc[ai][bj][m][1];
;                     ss += (y0[0] * y0[0] + y0[1] * y0[1]) + (y0[2] * y0[2] + y0[3] * y0[3]) + (y1[0] * y1[0] + y1[1] * y1[1]) + (y1[2] * y1[2] + y1[3] * y1[3]);
;                     *(u32x4*)(Y + (size_t)row * LDP + col0 + bj * 128) = (u32x4){pk2(y0[0], y0[1]), pk2(y0[2], y0[3]), pk2(y1[0], y1[1]), pk2(y1[2], y1[3])};
	s_add_i32 s71, s71, s27
	v_lshl_add_u64 v[212:213], v[206:207], 0, s[20:21]
	s_mov_b32 m0, s71
	ds_read_b128 v[158:161], v142 offset:49152
	ds_read_b128 v[162:165], v142 offset:50176
	ds_read_b128 v[166:169], v142 offset:51200
	ds_read_b128 v[170:173], v142 offset:52224
	ds_read_b128 v[174:177], v142 offset:53248
	ds_read_b128 v[178:181], v142 offset:54272
	ds_read_b128 v[182:185], v142 offset:55296
	ds_read_b128 v[186:189], v142 offset:56320
	global_load_lds_dwordx4 v[212:213], off
	v_lshl_add_u64 v[212:213], v[206:207], 0, s[22:23]
	s_add_i32 m0, s71, 0x2000
	s_add_i32 s71, s72, s27
	global_load_lds_dwordx4 v[212:213], off
	v_lshl_add_u64 v[212:213], v[208:209], 0, s[20:21]
	s_mov_b32 m0, s58
	v_lshl_add_u64 v[208:209], v[208:209], 0, s[22:23]
	global_load_lds_dwordx4 v[212:213], off
	s_mov_b32 m0, s59
	s_nop 0
	global_load_lds_dwordx4 v[208:209], off
	v_lshl_add_u64 v[208:209], v[206:207], 0, s[24:25]
	s_mov_b32 m0, s71
	v_lshl_add_u64 v[206:207], v[206:207], 0, s[38:39]
	global_load_lds_dwordx4 v[208:209], off
	s_add_i32 m0, s71, 0x2000
	s_nop 0
	global_load_lds_dwordx4 v[206:207], off
	s_waitcnt vmcnt(8)
	s_waitcnt lgkmcnt(0)
	s_barrier
	s_setprio 1
	s_waitcnt lgkmcnt(0)
	v_mfma_f32_16x16x32_bf16 v[60:63], v[134:137], v[158:161], v[60:63]
	v_mfma_f32_16x16x32_bf16 v[56:59], v[150:153], v[158:161], v[56:59]
	v_mfma_f32_16x16x32_bf16 v[44:47], v[134:137], v[166:169], v[44:47]
	v_mfma_f32_16x16x32_bf16 v[40:43], v[150:153], v[166:169], v[40:43]
	v_mfma_f32_16x16x32_bf16 v[28:31], v[134:137], v[174:177], v[28:31]
	v_mfma_f32_16x16x32_bf16 v[24:27], v[150:153], v[174:177], v[24:27]
	v_mfma_f32_16x16x32_bf16 v[12:15], v[134:137], v[182:185], v[12:15]
	v_mfma_f32_16x16x32_bf16 v[8:11], v[150:153], v[182:185], v[8:11]
	v_mfma_f32_16x16x32_bf16 v[60:63], v[146:149], v[162:165], v[60:63]
	v_mfma_f32_16x16x32_bf16 v[56:59], v[154:157], v[162:165], v[56:59]
	v_mfma_f32_16x16x32_bf16 v[44:47], v[146:149], v[170:173], v[44:47]
	v_mfma_f32_16x16x32_bf16 v[40:43], v[154:157], v[170:173], v[40:43]
	v_mfma_f32_16x16x32_bf16 v[28:31], v[146:149], v[178:181], v[28:31]
	v_mfma_f32_16x16x32_bf16 v[24:27], v[154:157], v[178:181], v[24:27]
	v_mfma_f32_16x16x32_bf16 v[12:15], v[146:149], v[186:189], v[12:15]
	v_mfma_f32_16x16x32_bf16 v[8:11], v[154:157], v[186:189], v[8:11]
	s_setprio 0
	s_setprio 1
	v_mfma_f32_16x16x32_bf16 v[52:55], v[190:193], v[158:161], v[52:55]
	v_mfma_f32_16x16x32_bf16 v[48:51], v[198:201], v[158:161], v[48:51]
	v_mfma_f32_16x16x32_bf16 v[36:39], v[190:193], v[166:169], v[36:39]
	v_mfma_f32_16x16x32_bf16 v[32:35], v[198:201], v[166:169], v[32:35]
	v_mfma_f32_16x16x32_bf16 v[20:23], v[190:193], v[174:177], v[20:23]
	v_mfma_f32_16x16x32_bf16 v[16:19], v[198:201], v[174:177], v[16:19]
	v_mfma_f32_16x16x32_bf16 v[4:7], v[190:193], v[182:185], v[4:7]
	v_mfma_f32_16x16x32_bf16 v[0:3], v[198:201], v[182:185], v[0:3]
	v_mfma_f32_16x16x32_bf16 v[52:55], v[194:197], v[162:165], v[52:55]
	v_mfma_f32_16x16x32_bf16 v[48:51], v[202:205], v[162:165], v[48:51]
	v_mfma_f32_16x16x32_bf16 v[36:39], v[194:197], v[170:173], v[36:39]
	v_mfma_f32_16x16x32_bf16 v[32:35], v[202:205], v[170:173], v[32:35]
	v_mfma_f32_16x16x32_bf16 v[20:23], v[194:197], v[178:181], v[20:23]
	v_mfma_f32_16x16x32_bf16 v[16:19], v[202:205], v[178:181], v[16:19]
	v_mfma_f32_16x16x32_bf16 v[4:7], v[194:197], v[186:189], v[4:7]
	v_mfma_f32_16x16x32_bf16 v[0:3], v[202:205], v[186:189], v[0:3]
	s_setprio 0
	s_barrier
	s_add_i32 s70, s70, 2
	s_add_u32 s52, s52, 0x8000
	s_addc_u32 s53, s53, 0
	s_add_u32 s54, s54, 0x8000
	s_addc_u32 s55, s55, 0
	s_cmp_gt_u32 s70, 61
	s_cbranch_scc0 .LBB0_537
	s_and_b64 vcc, exec, s[40:41]
	s_cbranch_vccz .LBB0_540
	s_barrier
.LBB0_540:
	s_lshl_b32 s43, s50, 8
	v_mov_b32_e32 v134, v138
	v_mov_b32_e32 v145, v139
	s_add_i32 s43, s43, s61
	v_mov_b64_e32 v[246:247], s[16:17]
	v_add_u32_e32 v136, s43, v134
	s_lshl_b32 s43, s14, 8
	s_or_b32 s43, s43, s62
	v_ashrrev_i32_e32 v137, 31, v136
	v_lshl_add_u32 v134, v145, 3, s43
	v_lshlrev_b64 v[244:245], 14, v[136:137]
	v_ashrrev_i32_e32 v135, 31, v134
	v_lshl_add_u64 v[244:245], s[36:37], 0, v[244:245]
	v_lshl_add_u64 v[244:245], v[134:135], 2, v[244:245]
	v_mad_i64_i32 v[246:247], s[50:51], v136, s67, v[246:247]
	v_lshl_add_u64 v[246:247], v[134:135], 1, v[246:247]
	s_lshl_b32 s50, s14, 2
	s_ashr_i32 s51, s50, 31
	v_lshlrev_b64 v[248:249], 8, v[136:137]
	v_lshl_add_u64 v[248:249], s[18:19], 0, v[248:249]
	v_lshl_add_u64 v[248:249], s[50:51], 2, v[248:249]
	s_lshl_b32 s14, s60, 2
	v_lshl_add_u64 v[248:249], v[248:249], 0, s[14:15]
	s_mov_b32 s51, 0
	global_load_dwordx4 v[146:149], v[244:245], off
	global_load_dwordx4 v[150:153], v[244:245], off offset:16
	global_load_dwordx4 v[154:157], v[244:245], off offset:512
	global_load_dwordx4 v[158:161], v[244:245], off offset:528
	s_mov_b32 s14, 0x40000
	v_lshl_add_u64 v[244:245], v[244:245], 0, s[14:15]
	global_load_dwordx4 v[162:165], v[244:245], off
	global_load_dwordx4 v[166:169], v[244:245], off offset:16
	global_load_dwordx4 v[170:173], v[244:245], off offset:512
	global_load_dwordx4 v[174:177], v[244:245], off offset:528
	s_mov_b32 s14, 0x40000
	v_lshl_add_u64 v[244:245], v[244:245], 0, s[14:15]
	global_load_dwordx4 v[178:181], v[244:245], off
	global_load_dwordx4 v[182:185], v[244:245], off offset:16
	global_load_dwordx4 v[186:189], v[244:245], off offset:512
	global_load_dwordx4 v[190:193], v[244:245], off offset:528
	s_mov_b32 s14, 0x40000
	v_lshl_add_u64 v[244:245], v[244:245], 0, s[14:15]
	global_load_dwordx4 v[194:197], v[244:245], off
	global_load_dwordx4 v[198:201], v[244:245], off offset:16
	global_load_dwordx4 v[202:205], v[244:245], off offset:512
	global_load_dwordx4 v[206:209], v[244:245], off offset:528
	s_mov_b32 s14, 0x140000
	v_lshl_add_u64 v[244:245], v[244:245], 0, s[14:15]
	global_load_dwordx4 v[212:215], v[244:245], off
	global_load_dwordx4 v[216:219], v[244:245], off offset:16
	global_load_dwordx4 v[220:223], v[244:245], off offset:512
	global_load_dwordx4 v[224:227], v[244:245], off offset:528
	s_mov_b32 s14, 0x40000
	v_lshl_add_u64 v[244:245], v[244:245], 0, s[14:15]
	v_and_b32_e32 v236, 64, v144
	v_xor_b32_e32 v250, 16, v144
	v_add_u32_e32 v236, 64, v236
	v_xor_b32_e32 v251, 32, v144
	v_cmp_lt_i32_e32 vcc, v250, v236
	s_nop 1
	v_cndmask_b32_e32 v250, v144, v250, vcc
	v_cmp_lt_i32_e32 vcc, v251, v236
	v_lshlrev_b32_e32 v250, 2, v250
	s_nop 0
	v_cndmask_b32_e32 v251, v144, v251, vcc
	v_lshlrev_b32_e32 v251, 2, v251
	s_waitcnt vmcnt(16)
; __device__ __forceinline__ unsigned pk2(float lo, float hi) { return __builtin_bit_cast(unsigned, __builtin_convertvector((f32x2){lo, hi}, bf16x2_t)); }
;     __device__ __forceinline__ void operator()(f32x4 (&acc)[2][2][4][2], const pg8::Unit& u, int wr, int wc, int fr, int fq) const {
;     ...
;                 const int row = row0 + ai * 128 + m * 16;
;                 const size_t off = (size_t)row * DM + col0;
;                 float ss = 0.f;
; #pragma unroll
;                 for (int bj = 0; bj < 2; ++bj) {
;                     const f32x4 y0 = *(const f32x4*)(x + off + bj * 128) + acc[ai][bj][m][0], y1 = *(const f32x4*)(x + off + bj * 128 + 4) + acc[ai][bj][m][1];
;                     ss += (y0[0] * y0[0] + y0[1] * y0[1]) + (y0[2] * y0[2] + y0[3] * y0[3]) + (y1[0] * y1[0] + y1[1] * y1[1]) + (y1[2] * y1[2] + y1[3] * y1[3]);
;                     *(u32x4*)(Y + (size_t)row * LDP + col0 + bj * 128) = (u32x4){pk2(y0[0], y0[1]), pk2(y0[2], y0[3]), pk2(y1[0], y1[1]), pk2(y1[2], y1[3])};
;                 }
	v_pk_add_f32 v[124:125], v[124:125], v[146:147]
	v_pk_add_f32 v[126:127], v[126:127], v[148:149]
	v_pk_add_f32 v[120:121], v[120:121], v[150:151]
	v_pk_add_f32 v[122:123], v[122:123], v[152:153]
	v_pk_add_f32 v[116:117], v[116:117], v[154:155]
	v_pk_add_f32 v[118:119], v[118:119], v[156:157]
	v_pk_add_f32 v[112:113], v[112:113], v[158:159]
	v_pk_add_f32 v[114:115], v[114:115], v[160:161]
	global_load_dwordx4 v[146:149], v[244:245], off
	global_load_dwordx4 v[150:153], v[244:245], off offset:16
	global_load_dwordx4 v[154:157], v[244:245], off offset:512
	global_load_dwordx4 v[158:161], v[244:245], off offset:528
	s_mov_b32 s14, 0x40000
	v_lshl_add_u64 v[244:245], v[244:245], 0, s[14:15]
	v_cvt_pk_bf16_f32 v228, v124, v125
	v_cvt_pk_bf16_f32 v229, v126, v127
	v_cvt_pk_bf16_f32 v230, v120, v121
	v_cvt_pk_bf16_f32 v231, v122, v123
	v_cvt_pk_bf16_f32 v232, v116, v117
	v_cvt_pk_bf16_f32 v233, v118, v119
	v_cvt_pk_bf16_f32 v234, v112, v113
	v_cvt_pk_bf16_f32 v235, v114, v115
	global_store_dwordx4 v[246:247], v[228:231], off
	global_store_dwordx4 v[246:247], v[232:235], off offset:256
	s_mov_b32 s50, 0x20800
	v_lshl_add_u64 v[246:247], v[246:247], 0, s[50:51]
	v_mul_f32_e32 v236, v125, v125
	v_mul_f32_e32 v237, v127, v127
	v_mul_f32_e32 v238, v121, v121
	v_mul_f32_e32 v239, v123, v123
	v_fmac_f32_e32 v236, v124, v124
	v_fmac_f32_e32 v237, v126, v126
	v_fmac_f32_e32 v238, v120, v120
	v_fmac_f32_e32 v239, v122, v122
	v_add_f32_e32 v236, v236, v237
	v_add_f32_e32 v236, v236, v238
	v_add_f32_e32 v236, v239, v236
	v_mul_f32_e32 v240, v117, v117
	v_mul_f32_e32 v241, v119, v119
	v_mul_f32_e32 v242, v113, v113
	v_mul_f32_e32 v243, v115, v115
	v_fmac_f32_e32 v240, v116, v116
	v_fmac_f32_e32 v241, v118, v118
	v_fmac_f32_e32 v242, v112, v112
	v_fmac_f32_e32 v243, v114, v114
	v_add_f32_e32 v240, v240, v241
	v_add_f32_e32 v240, v240, v242
	v_add_f32_e32 v240, v243, v240
	v_add_f32_e32 v112, v236, v240
	s_waitcnt vmcnt(18)
	v_pk_add_f32 v[108:109], v[108:109], v[162:163]
	v_pk_add_f32 v[110:111], v[110:111], v[164:165]
	v_pk_add_f32 v[104:105], v[104:105], v[166:167]
	v_pk_add_f32 v[106:107], v[106:107], v[168:169]
	v_pk_add_f32 v[100:101], v[100:101], v[170:171]
	v_pk_add_f32 v[102:103], v[102:103], v[172:173]
	v_pk_add_f32 v[96:97], v[96:97], v[174:175]
	v_pk_add_f32 v[98:99], v[98:99], v[176:177]
	global_load_dwordx4 v[162:165], v[244:245], off
	global_load_dwordx4 v[166:169], v[244:245], off offset:16
	global_load_dwordx4 v[170:173], v[244:245], off offset:512
	global_load_dwordx4 v[174:177], v[244:245], off offset:528
	s_mov_b32 s14, 0x40000
	v_lshl_add_u64 v[244:245], v[244:245], 0, s[14:15]
	v_cvt_pk_bf16_f32 v228, v108, v109
	v_cvt_pk_bf16_f32 v229, v110, v111
	v_cvt_pk_bf16_f32 v230, v104, v105
	v_cvt_pk_bf16_f32 v231, v106, v107
	v_cvt_pk_bf16_f32 v232, v100, v101
	v_cvt_pk_bf16_f32 v233, v102, v103
	v_cvt_pk_bf16_f32 v234, v96, v97
	v_cvt_pk_bf16_f32 v235, v98, v99
	global_store_dwordx4 v[246:247], v[228:231], off
	global_store_dwordx4 v[246:247], v[232:235], off offset:256
	s_mov_b32 s50, 0x20800
	v_lshl_add_u64 v[246:247], v[246:247], 0, s[50:51]
	v_mul_f32_e32 v236, v109, v109
	v_mul_f32_e32 v237, v111, v111
	v_mul_f32_e32 v238, v105, v105
	v_mul_f32_e32 v239, v107, v107
	v_fmac_f32_e32 v236, v108, v108
	v_fmac_f32_e32 v237, v110, v110
	v_fmac_f32_e32 v238, v104, v104
	v_fmac_f32_e32 v239, v106, v106
	v_add_f32_e32 v236, v236, v237
	v_add_f32_e32 v236, v236, v238
	v_add_f32_e32 v236, v239, v236
	v_mul_f32_e32 v240, v101, v101
	v_mul_f32_e32 v241, v103, v103
	v_mul_f32_e32 v242, v97, v97
	v_mul_f32_e32 v243, v99, v99
	v_fmac_f32_e32 v240, v100, v100
	v_fmac_f32_e32 v241, v102, v102
	v_fmac_f32_e32 v242, v96, v96
	v_fmac_f32_e32 v243, v98, v98
	v_add_f32_e32 v240, v240, v241
	v_add_f32_e32 v240, v240, v242
	v_add_f32_e32 v240, v243, v240
	v_add_f32_e32 v113, v236, v240
	s_waitcnt vmcnt(20)
	v_pk_add_f32 v[92:93], v[92:93], v[178:179]
	v_pk_add_f32 v[94:95], v[94:95], v[180:181]
	v_pk_add_f32 v[88:89], v[88:89], v[182:183]
	v_pk_add_f32 v[90:91], v[90:91], v[184:185]
	v_pk_add_f32 v[84:85], v[84:85], v[186:187]
	v_pk_add_f32 v[86:87], v[86:87], v[188:189]
	v_pk_add_f32 v[80:81], v[80:81], v[190:191]
	v_pk_add_f32 v[82:83], v[82:83], v[192:193]
	global_load_dwordx4 v[178:181], v[244:245], off
	global_load_dwordx4 v[182:185], v[244:245], off offset:16
	global_load_dwordx4 v[186:189], v[244:245], off offset:512
	global_load_dwordx4 v[190:193], v[244:245], off offset:528
	v_cvt_pk_bf16_f32 v228, v92, v93
	v_cvt_pk_bf16_f32 v229, v94, v95
	v_cvt_pk_bf16_f32 v230, v88, v89
	v_cvt_pk_bf16_f32 v231, v90, v91
	v_cvt_pk_bf16_f32 v232, v84, v85
	v_cvt_pk_bf16_f32 v233, v86, v87
	v_cvt_pk_bf16_f32 v234, v80, v81
	v_cvt_pk_bf16_f32 v235, v82, v83
	global_store_dwordx4 v[246:247], v[228:231], off
	global_store_dwordx4 v[246:247], v[232:235], off offset:256
	s_mov_b32 s50, 0x20800
	v_lshl_add_u64 v[246:247], v[246:247], 0, s[50:51]
	v_mul_f32_e32 v236, v93, v93
	v_mul_f32_e32 v237, v95, v95
	v_mul_f32_e32 v238, v89, v89
	v_mul_f32_e32 v239, v91, v91
	v_fmac_f32_e32 v236, v92, v92
	v_fmac_f32_e32 v237, v94, v94
	v_fmac_f32_e32 v238, v88, v88
	v_fmac_f32_e32 v239, v90, v90
	v_add_f32_e32 v236, v236, v237
	v_add_f32_e32 v236, v236, v238
	v_add_f32_e32 v236, v239, v236
	v_mul_f32_e32 v240, v85, v85
	v_mul_f32_e32 v241, v87, v87
	v_mul_f32_e32 v242, v81, v81
	v_mul_f32_e32 v243, v83, v83
	v_fmac_f32_e32 v240, v84, v84
	v_fmac_f32_e32 v241, v86, v86
	v_fmac_f32_e32 v242, v80, v80
	v_fmac_f32_e32 v243, v82, v82
	v_add_f32_e32 v240, v240, v241
	v_add_f32_e32 v240, v240, v242
	v_add_f32_e32 v240, v243, v240
	v_add_f32_e32 v114, v236, v240
	s_waitcnt vmcnt(22)
; __device__ __forceinline__ unsigned pk2(float lo, float hi) { return __builtin_bit_cast(unsigned, __builtin_convertvector((f32x2){lo, hi}, bf16x2_t)); }
;     __device__ __forceinline__ void operator()(f32x4 (&acc)[2][2][4][2], const pg8::Unit& u, int wr, int wc, int fr, int fq) const {
;     ...
;                 const int row = row0 + ai * 128 + m * 16;
;                 const size_t off = (size_t)row * DM + col0;
;                 float ss = 0.f;
; #pragma unroll
;                 for (int bj = 0; bj < 2; ++bj) {
;                     const f32x4 y0 = *(const f32x4*)(x + off + bj * 128) + acc[ai][bj][m][0], y1 = *(const f32x4*)(x + off + bj * 128 + 4) + acc[ai][bj][m][1];
;                     ss += (y0[0] * y0[0] + y0[1] * y0[1]) + (y0[2] * y0[2] + y0[3] * y0[3]) + (y1[0] * y1[0] + y1[1] * y1[1]) + (y1[2] * y1[2] + y1[3] * y1[3]);
;                     *(u32x4*)(Y + (size_t)row * LDP + col0 + bj * 128) = (u32x4){pk2(y0[0], y0[1]), pk2(y0[2], y0[3]), pk2(y1[0], y1[1]), pk2(y1[2], y1[3])};
;                 }
	v_pk_add_f32 v[76:77], v[76:77], v[194:195]
	v_pk_add_f32 v[78:79], v[78:79], v[196:197]
	v_pk_add_f32 v[72:73], v[72:73], v[198:199]
	v_pk_add_f32 v[74:75], v[74:75], v[200:201]
	v_pk_add_f32 v[68:69], v[68:69], v[202:203]
	v_pk_add_f32 v[70:71], v[70:71], v[204:205]
	v_pk_add_f32 v[64:65], v[64:65], v[206:207]
	v_pk_add_f32 v[66:67], v[66:67], v[208:209]
	v_cvt_pk_bf16_f32 v228, v76, v77
	v_cvt_pk_bf16_f32 v229, v78, v79
	v_cvt_pk_bf16_f32 v230, v72, v73
	v_cvt_pk_bf16_f32 v231, v74, v75
	v_cvt_pk_bf16_f32 v232, v68, v69
	v_cvt_pk_bf16_f32 v233, v70, v71
	v_cvt_pk_bf16_f32 v234, v64, v65
	v_cvt_pk_bf16_f32 v235, v66, v67
	global_store_dwordx4 v[246:247], v[228:231], off
	global_store_dwordx4 v[246:247], v[232:235], off offset:256
	s_mov_b32 s50, 0xa2800
	v_lshl_add_u64 v[246:247], v[246:247], 0, s[50:51]
	v_mul_f32_e32 v236, v77, v77
	v_mul_f32_e32 v237, v79, v79
	v_mul_f32_e32 v238, v73, v73
	v_mul_f32_e32 v239, v75, v75
	v_fmac_f32_e32 v236, v76, v76
	v_fmac_f32_e32 v237, v78, v78
	v_fmac_f32_e32 v238, v72, v72
	v_fmac_f32_e32 v239, v74, v74
	v_add_f32_e32 v236, v236, v237
	v_add_f32_e32 v236, v236, v238
	v_add_f32_e32 v236, v239, v236
	v_mul_f32_e32 v240, v69, v69
	v_mul_f32_e32 v241, v71, v71
	v_mul_f32_e32 v242, v65, v65
	v_mul_f32_e32 v243, v67, v67
	v_fmac_f32_e32 v240, v68, v68
	v_fmac_f32_e32 v241, v70, v70
	v_fmac_f32_e32 v242, v64, v64
	v_fmac_f32_e32 v243, v66, v66
	v_add_f32_e32 v240, v240, v241
	v_add_f32_e32 v240, v240, v242
	v_add_f32_e32 v240, v243, v240
	v_add_f32_e32 v115, v236, v240
	s_waitcnt vmcnt(20)
	v_pk_add_f32 v[60:61], v[60:61], v[212:213]
	v_pk_add_f32 v[62:63], v[62:63], v[214:215]
	v_pk_add_f32 v[56:57], v[56:57], v[216:217]
	v_pk_add_f32 v[58:59], v[58:59], v[218:219]
	v_pk_add_f32 v[52:53], v[52:53], v[220:221]
	v_pk_add_f32 v[54:55], v[54:55], v[222:223]
	v_pk_add_f32 v[48:49], v[48:49], v[224:225]
	v_pk_add_f32 v[50:51], v[50:51], v[226:227]
	v_cvt_pk_bf16_f32 v228, v60, v61
	v_cvt_pk_bf16_f32 v229, v62, v63
	v_cvt_pk_bf16_f32 v230, v56, v57
	v_cvt_pk_bf16_f32 v231, v58, v59
	v_cvt_pk_bf16_f32 v232, v52, v53
	v_cvt_pk_bf16_f32 v233, v54, v55
	v_cvt_pk_bf16_f32 v234, v48, v49
	v_cvt_pk_bf16_f32 v235, v50, v51
	global_store_dwordx4 v[246:247], v[228:231], off
	global_store_dwordx4 v[246:247], v[232:235], off offset:256
	s_mov_b32 s50, 0x20800
	v_lshl_add_u64 v[246:247], v[246:247], 0, s[50:51]
	v_mul_f32_e32 v236, v61, v61
	v_mul_f32_e32 v237, v63, v63
	v_mul_f32_e32 v238, v57, v57
	v_mul_f32_e32 v239, v59, v59
	v_fmac_f32_e32 v236, v60, v60
	v_fmac_f32_e32 v237, v62, v62
	v_fmac_f32_e32 v238, v56, v56
	v_fmac_f32_e32 v239, v58, v58
	v_add_f32_e32 v236, v236, v237
	v_add_f32_e32 v236, v236, v238
	v_add_f32_e32 v236, v239, v236
	v_mul_f32_e32 v240, v53, v53
	v_mul_f32_e32 v241, v55, v55
	v_mul_f32_e32 v242, v49, v49
	v_mul_f32_e32 v243, v51, v51
	v_fmac_f32_e32 v240, v52, v52
	v_fmac_f32_e32 v241, v54, v54
	v_fmac_f32_e32 v242, v48, v48
	v_fmac_f32_e32 v243, v50, v50
	v_add_f32_e32 v240, v240, v241
	v_add_f32_e32 v240, v240, v242
	v_add_f32_e32 v240, v243, v240
	v_add_f32_e32 v116, v236, v240
	s_waitcnt vmcnt(18)
	v_pk_add_f32 v[44:45], v[44:45], v[146:147]
	v_pk_add_f32 v[46:47], v[46:47], v[148:149]
	v_pk_add_f32 v[40:41], v[40:41], v[150:151]
	v_pk_add_f32 v[42:43], v[42:43], v[152:153]
	v_pk_add_f32 v[36:37], v[36:37], v[154:155]
	v_pk_add_f32 v[38:39], v[38:39], v[156:157]
	v_pk_add_f32 v[32:33], v[32:33], v[158:159]
	v_pk_add_f32 v[34:35], v[34:35], v[160:161]
	v_cvt_pk_bf16_f32 v228, v44, v45
	v_cvt_pk_bf16_f32 v229, v46, v47
	v_cvt_pk_bf16_f32 v230, v40, v41
	v_cvt_pk_bf16_f32 v231, v42, v43
	v_cvt_pk_bf16_f32 v232, v36, v37
	v_cvt_pk_bf16_f32 v233, v38, v39
	v_cvt_pk_bf16_f32 v234, v32, v33
	v_cvt_pk_bf16_f32 v235, v34, v35
	global_store_dwordx4 v[246:247], v[228:231], off
	global_store_dwordx4 v[246:247], v[232:235], off offset:256
	s_mov_b32 s50, 0x20800
	v_lshl_add_u64 v[246:247], v[246:247], 0, s[50:51]
	v_mul_f32_e32 v236, v45, v45
	v_mul_f32_e32 v237, v47, v47
	v_mul_f32_e32 v238, v41, v41
	v_mul_f32_e32 v239, v43, v43
	v_fmac_f32_e32 v236, v44, v44
	v_fmac_f32_e32 v237, v46, v46
	v_fmac_f32_e32 v238, v40, v40
	v_fmac_f32_e32 v239, v42, v42
	v_add_f32_e32 v236, v236, v237
	v_add_f32_e32 v236, v236, v238
	v_add_f32_e32 v236, v239, v236
	v_mul_f32_e32 v240, v37, v37
	v_mul_f32_e32 v241, v39, v39
	v_mul_f32_e32 v242, v33, v33
	v_mul_f32_e32 v243, v35, v35
	v_fmac_f32_e32 v240, v36, v36
	v_fmac_f32_e32 v241, v38, v38
	v_fmac_f32_e32 v242, v32, v32
	v_fmac_f32_e32 v243, v34, v34
	v_add_f32_e32 v240, v240, v241
	v_add_f32_e32 v240, v240, v242
	v_add_f32_e32 v240, v243, v240
	v_add_f32_e32 v117, v236, v240
	s_waitcnt vmcnt(14)
; __device__ __forceinline__ unsigned pk2(float lo, float hi) { return __builtin_bit_cast(unsigned, __builtin_convertvector((f32x2){lo, hi}, bf16x2_t)); }
;     __device__ __forceinline__ void operator()(f32x4 (&acc)[2][2][4][2], const pg8::Unit& u, int wr, int wc, int fr, int fq) const {
;     ...
;                 const int row = row0 + ai * 128 + m * 16;
;                 const size_t off = (size_t)row * DM + col0;
;                 float ss = 0.f;
; #pragma unroll
;                 for (int bj = 0; bj < 2; ++bj) {
;                     const f32x4 y0 = *(const f32x4*)(x + off + bj * 128) + acc[ai][bj][m][0], y1 = *(const f32x4*)(x + off + bj * 128 + 4) + acc[ai][bj][m][1];
;                     ss += (y0[0] * y0[0] + y0[1] * y0[1]) + (y0[2] * y0[2] + y0[3] * y0[3]) + (y1[0] * y1[0] + y1[1] * y1[1]) + (y1[2] * y1[2] + y1[3] * y1[3]);
;                     *(u32x4*)(Y + (size_t)row * LDP + col0 + bj * 128) = (u32x4){pk2(y0[0], y0[1]), pk2(y0[2], y0[3]), pk2(y1[0], y1[1]), pk2(y1[2], y1[3])};
;                 }
;                 ss += __shfl_xor(ss, 16); ss += __shfl_xor(ss, 32);
;                 if (fq == 0) rsq[(size_t)row * 64 + u.pn * 4 + wc] = ss;
	v_pk_add_f32 v[28:29], v[28:29], v[162:163]
	v_pk_add_f32 v[30:31], v[30:31], v[164:165]
	v_pk_add_f32 v[24:25], v[24:25], v[166:167]
	v_pk_add_f32 v[26:27], v[26:27], v[168:169]
	v_pk_add_f32 v[20:21], v[20:21], v[170:171]
	v_pk_add_f32 v[22:23], v[22:23], v[172:173]
	v_pk_add_f32 v[16:17], v[16:17], v[174:175]
	v_pk_add_f32 v[18:19], v[18:19], v[176:177]
	v_cvt_pk_bf16_f32 v228, v28, v29
	v_cvt_pk_bf16_f32 v229, v30, v31
	v_cvt_pk_bf16_f32 v230, v24, v25
	v_cvt_pk_bf16_f32 v231, v26, v27
	v_cvt_pk_bf16_f32 v232, v20, v21
	v_cvt_pk_bf16_f32 v233, v22, v23
	v_cvt_pk_bf16_f32 v234, v16, v17
	v_cvt_pk_bf16_f32 v235, v18, v19
	global_store_dwordx4 v[246:247], v[228:231], off
	global_store_dwordx4 v[246:247], v[232:235], off offset:256
	s_mov_b32 s50, 0x20800
	v_lshl_add_u64 v[246:247], v[246:247], 0, s[50:51]
	v_mul_f32_e32 v236, v29, v29
	v_mul_f32_e32 v237, v31, v31
	v_mul_f32_e32 v238, v25, v25
	v_mul_f32_e32 v239, v27, v27
	v_fmac_f32_e32 v236, v28, v28
	v_fmac_f32_e32 v237, v30, v30
	v_fmac_f32_e32 v238, v24, v24
	v_fmac_f32_e32 v239, v26, v26
	v_add_f32_e32 v236, v236, v237
	v_add_f32_e32 v236, v236, v238
	v_add_f32_e32 v236, v239, v236
	v_mul_f32_e32 v240, v21, v21
	v_mul_f32_e32 v241, v23, v23
	v_mul_f32_e32 v242, v17, v17
	v_mul_f32_e32 v243, v19, v19
	v_fmac_f32_e32 v240, v20, v20
	v_fmac_f32_e32 v241, v22, v22
	v_fmac_f32_e32 v242, v16, v16
	v_fmac_f32_e32 v243, v18, v18
	v_add_f32_e32 v240, v240, v241
	v_add_f32_e32 v240, v240, v242
	v_add_f32_e32 v240, v243, v240
	v_add_f32_e32 v118, v236, v240
	s_waitcnt vmcnt(10)
	v_pk_add_f32 v[12:13], v[12:13], v[178:179]
	v_pk_add_f32 v[14:15], v[14:15], v[180:181]
	v_pk_add_f32 v[8:9], v[8:9], v[182:183]
	v_pk_add_f32 v[10:11], v[10:11], v[184:185]
	v_pk_add_f32 v[4:5], v[4:5], v[186:187]
	v_pk_add_f32 v[6:7], v[6:7], v[188:189]
	v_pk_add_f32 v[0:1], v[0:1], v[190:191]
	v_pk_add_f32 v[2:3], v[2:3], v[192:193]
	v_cvt_pk_bf16_f32 v228, v12, v13
	v_cvt_pk_bf16_f32 v229, v14, v15
	v_cvt_pk_bf16_f32 v230, v8, v9
	v_cvt_pk_bf16_f32 v231, v10, v11
	v_cvt_pk_bf16_f32 v232, v4, v5
	v_cvt_pk_bf16_f32 v233, v6, v7
	v_cvt_pk_bf16_f32 v234, v0, v1
	v_cvt_pk_bf16_f32 v235, v2, v3
	global_store_dwordx4 v[246:247], v[228:231], off
	global_store_dwordx4 v[246:247], v[232:235], off offset:256
	v_mul_f32_e32 v236, v13, v13
	v_mul_f32_e32 v237, v15, v15
	v_mul_f32_e32 v238, v9, v9
	v_mul_f32_e32 v239, v11, v11
	v_fmac_f32_e32 v236, v12, v12
	v_fmac_f32_e32 v237, v14, v14
	v_fmac_f32_e32 v238, v8, v8
	v_fmac_f32_e32 v239, v10, v10
	v_add_f32_e32 v236, v236, v237
	v_add_f32_e32 v236, v236, v238
	v_add_f32_e32 v236, v239, v236
	v_mul_f32_e32 v240, v5, v5
	v_mul_f32_e32 v241, v7, v7
	v_mul_f32_e32 v242, v1, v1
	v_mul_f32_e32 v243, v3, v3
	v_fmac_f32_e32 v240, v4, v4
	v_fmac_f32_e32 v241, v6, v6
	v_fmac_f32_e32 v242, v0, v0
	v_fmac_f32_e32 v243, v2, v2
	v_add_f32_e32 v240, v240, v241
	v_add_f32_e32 v240, v240, v242
	v_add_f32_e32 v240, v243, v240
	v_add_f32_e32 v119, v236, v240
	ds_bpermute_b32 v236, v250, v112
	ds_bpermute_b32 v237, v250, v113
	ds_bpermute_b32 v238, v250, v114
	ds_bpermute_b32 v239, v250, v115
	ds_bpermute_b32 v240, v250, v116
	ds_bpermute_b32 v241, v250, v117
	ds_bpermute_b32 v242, v250, v118
	ds_bpermute_b32 v243, v250, v119
	v_cmp_eq_u32_e32 vcc, 0, v145
	s_waitcnt lgkmcnt(0)
	v_add_f32_e32 v112, v112, v236
	v_add_f32_e32 v113, v113, v237
	v_add_f32_e32 v114, v114, v238
	v_add_f32_e32 v115, v115, v239
	v_add_f32_e32 v116, v116, v240
	v_add_f32_e32 v117, v117, v241
	v_add_f32_e32 v118, v118, v242
	v_add_f32_e32 v119, v119, v243
	ds_bpermute_b32 v236, v251, v112
	ds_bpermute_b32 v237, v251, v113
	ds_bpermute_b32 v238, v251, v114
	ds_bpermute_b32 v239, v251, v115
	ds_bpermute_b32 v240, v251, v116
	ds_bpermute_b32 v241, v251, v117
	ds_bpermute_b32 v242, v251, v118
	ds_bpermute_b32 v243, v251, v119
	s_waitcnt lgkmcnt(0)
	v_add_f32_e32 v112, v112, v236
	v_add_f32_e32 v113, v113, v237
	v_add_f32_e32 v114, v114, v238
	v_add_f32_e32 v115, v115, v239
	v_add_f32_e32 v116, v116, v240
	v_add_f32_e32 v117, v117, v241
	v_add_f32_e32 v118, v118, v242
	v_add_f32_e32 v119, v119, v243
	s_and_saveexec_b64 s[52:53], vcc
	global_store_dword v[248:249], v112, off
	s_mov_b32 s50, 0x1000
	v_lshl_add_u64 v[248:249], v[248:249], 0, s[50:51]
	global_store_dword v[248:249], v113, off
	s_mov_b32 s50, 0x1000
	v_lshl_add_u64 v[248:249], v[248:249], 0, s[50:51]
	global_store_dword v[248:249], v114, off
	s_mov_b32 s50, 0x1000
	v_lshl_add_u64 v[248:249], v[248:249], 0, s[50:51]
	global_store_dword v[248:249], v115, off
	s_mov_b32 s50, 0x5000
	v_lshl_add_u64 v[248:249], v[248:249], 0, s[50:51]
	global_store_dword v[248:249], v116, off
	s_mov_b32 s50, 0x1000
	v_lshl_add_u64 v[248:249], v[248:249], 0, s[50:51]
	global_store_dword v[248:249], v117, off
	s_mov_b32 s50, 0x1000
	v_lshl_add_u64 v[248:249], v[248:249], 0, s[50:51]
	global_store_dword v[248:249], v118, off
	s_mov_b32 s50, 0x1000
	v_lshl_add_u64 v[248:249], v[248:249], 0, s[50:51]
	global_store_dword v[248:249], v119, off
	s_or_b64 exec, exec, s[52:53]
	s_andn2_b64 vcc, exec, s[0:1]
	s_mov_b64 s[0:1], -1
	s_cbranch_vccnz .LBB0_529
	s_andn2_b64 vcc, exec, s[12:13]
	s_cbranch_vccnz .LBB0_528
	s_barrier
	s_branch .LBB0_528
